# GEMM K-loops: saddr-form LDS-DMA (no per-load 64-bit VALU add), duplicate lgkmcnt waits and m0-hazard nops removed; on top of attention loop rescheduling
# speedup vs baseline: 1.0078x; 1.0078x over previous
; #define PG8_STAGE(bufoff, gbase, voff) do { _Pragma("unroll") for (int _i = 0; _i < 2; ++_i) \
;         __builtin_amdgcn_global_load_lds((const unsigned*)((const char*)(gbase) + (voff)[_i]), (LAS unsigned*)(lds + (bufoff) + ldsw + _i * 8192), 16, 0, 0); } while (0)
; #define PG8_LDA(dst, b, h) do { _Pragma("unroll") for (int m = 0; m < 4; ++m) _Pragma("unroll") for (int k = 0; k < 2; ++k) dst[m][k] = *(const LAS bf16x8*)(lds + PG8_SA(b, h) + aoff + m * 2048 + k * 1024); } while (0)
; #define PG8_LDB(dst, b, h) do { _Pragma("unroll") for (int n = 0; n < 2; ++n) _Pragma("unroll") for (int k = 0; k < 2; ++k) dst[n][k] = *(const LAS bf16x8*)(lds + PG8_SB(b, h) + boff + n * 2048 + k * 1024); } while (0)
; #define PG8_MMA(ai, bj, At, Bt) do { __builtin_amdgcn_s_setprio(1); _Pragma("unroll") for (int m = 0; m < 4; ++m) _Pragma("unroll") for (int n = 0; n < 2; ++n) _Pragma("unroll") for (int k = 0; k < 2; ++k) \
;         acc[ai][bj][m][n] = __builtin_amdgcn_mfma_f32_16x16x32_bf16(Bt[n][k], At[m][k], acc[ai][bj][m][n], 0, 0, 0); __builtin_amdgcn_s_setprio(0); } while (0)
; #define PG8_WAIT_L(n) asm volatile("s_waitcnt lgkmcnt(" #n ")" ::: "memory")
; #define PG8_BAR __builtin_amdgcn_s_barrier()
; #define PG8_SCHED __builtin_amdgcn_sched_barrier(0)
; template <class Epi, class Sched>
; __device__ __forceinline__ void gemm_phase(LAS unsigned char* lds, const Gemm g, const Sched& S, const Epi& E, const int tid) {
;     ...
;             const bool last = (t == nt - 2);
;             const char* a1 = cA + (size_t)(t + 1) * kstep;
;             const char* a2 = last ? nA : cA + (size_t)(t + 2) * kstep; const char* b2 = last ? nB : cB + (size_t)(t + 2) * kstep;
;             const char* a3 = a2 + kstep; const char* b3 = b2 + kstep;
;             if (last && has_next) S.a_ready(nxt);
;             if constexpr (Epi::PRELOAD) { if (last) E.preload(cur, lds, wid, lane); }
;             PG8_LDB(B0, 0, 0); PG8_SCHED; PG8_LDA(At, 0, 0); PG8_STAGE(PG8_SA(1, 1), a1 + hstep, voffA);
;             PG8_WAIT_L(8); PG8_BAR; PG8_WAIT_L(0); PG8_MMA(0, 0, At, B0); PG8_BAR; PG8_SCHED;
;             PG8_LDB(B1, 0, 1); PG8_STAGE(PG8_SB(0, 0), b2, voffB);
;             PG8_BAR; PG8_WAIT_L(0); PG8_MMA(0, 1, At, B1); PG8_BAR;
;             PG8_LDA(At, 0, 1); PG8_STAGE(PG8_SA(0, 0), a2, voffA);
;             PG8_BAR; PG8_WAIT_L(0); PG8_MMA(1, 0, At, B0); PG8_BAR; PG8_SCHED;
.LBB0_277:
	s_add_u32 s18, s16, 0xfff80080
	s_addc_u32 s19, s17, -1
	s_add_i32 s53, 0, 0x10000
	v_add_u32_e32 v156, s53, v141
	ds_read_b128 v[144:147], v156
	ds_read_b128 v[148:151], v156 offset:1024
	ds_read_b128 v[152:155], v156 offset:2048
	ds_read_b128 v[156:159], v156 offset:3072
	s_cmp_eq_u32 s52, 28
	s_cselect_b32 s21, s11, s19
	s_cselect_b32 s20, s25, s18
	s_cselect_b32 s19, s7, s51
	s_cselect_b32 s18, s49, s50
	s_add_i32 m0, s5, 0xc000
	ds_read_b128 v[160:163], v143
	ds_read_b128 v[164:167], v143 offset:1024
	ds_read_b128 v[168:171], v143 offset:2048
	ds_read_b128 v[172:175], v143 offset:3072
	ds_read_b128 v[176:179], v143 offset:4096
	ds_read_b128 v[180:183], v143 offset:5120
	ds_read_b128 v[184:187], v143 offset:6144
	ds_read_b128 v[188:191], v143 offset:7168
	global_load_lds_dwordx4 v136, s[16:17]
	s_add_i32 m0, s5, 0xe000
	s_nop 0
	global_load_lds_dwordx4 v138, s[16:17]
	s_waitcnt lgkmcnt(8)
	s_barrier
	s_waitcnt lgkmcnt(0)
	s_setprio 1
	v_mfma_f32_16x16x32_bf16 v[126:129], v[144:147], v[160:163], v[126:129]
	v_mfma_f32_16x16x32_bf16 v[122:125], v[152:155], v[160:163], v[122:125]
	v_mfma_f32_16x16x32_bf16 v[118:121], v[144:147], v[168:171], v[118:121]
	v_mfma_f32_16x16x32_bf16 v[114:117], v[152:155], v[168:171], v[114:117]
	v_mfma_f32_16x16x32_bf16 v[102:105], v[144:147], v[176:179], v[102:105]
	v_mfma_f32_16x16x32_bf16 v[98:101], v[152:155], v[176:179], v[98:101]
	v_mfma_f32_16x16x32_bf16 v[86:89], v[144:147], v[184:187], v[86:89]
	v_mfma_f32_16x16x32_bf16 v[82:85], v[152:155], v[184:187], v[82:85]
	v_mfma_f32_16x16x32_bf16 v[126:129], v[148:151], v[164:167], v[126:129]
	v_mfma_f32_16x16x32_bf16 v[122:125], v[156:159], v[164:167], v[122:125]
	v_mfma_f32_16x16x32_bf16 v[118:121], v[148:151], v[172:175], v[118:121]
	v_mfma_f32_16x16x32_bf16 v[114:117], v[156:159], v[172:175], v[114:117]
	v_mfma_f32_16x16x32_bf16 v[102:105], v[148:151], v[180:183], v[102:105]
	v_mfma_f32_16x16x32_bf16 v[98:101], v[156:159], v[180:183], v[98:101]
	v_mfma_f32_16x16x32_bf16 v[86:89], v[148:151], v[188:191], v[86:89]
	v_mfma_f32_16x16x32_bf16 v[82:85], v[156:159], v[188:191], v[82:85]
	s_setprio 0
	s_barrier
	s_add_i32 s56, 0, 0x14000
	s_add_i32 s53, s53, s42
	v_add_u32_e32 v204, s56, v141
	v_lshl_add_u64 v[208:209], s[18:19], 0, v[0:1]
	s_mov_b32 m0, s53
	ds_read_b128 v[192:195], v204
	ds_read_b128 v[196:199], v204 offset:1024
	ds_read_b128 v[200:203], v204 offset:2048
	ds_read_b128 v[204:207], v204 offset:3072
	global_load_lds_dwordx4 v[208:209], off
	s_add_i32 m0, s53, 0x2000
	v_lshl_add_u64 v[210:211], s[18:19], 0, v[134:135]
	global_load_lds_dwordx4 v[210:211], off
	s_barrier
	s_waitcnt lgkmcnt(0)
	s_setprio 1
	v_mfma_f32_16x16x32_bf16 v[110:113], v[192:195], v[160:163], v[110:113]
	v_mfma_f32_16x16x32_bf16 v[106:109], v[200:203], v[160:163], v[106:109]
	v_mfma_f32_16x16x32_bf16 v[94:97], v[192:195], v[168:171], v[94:97]
	v_mfma_f32_16x16x32_bf16 v[90:93], v[200:203], v[168:171], v[90:93]
	v_mfma_f32_16x16x32_bf16 v[78:81], v[192:195], v[176:179], v[78:81]
	v_mfma_f32_16x16x32_bf16 v[74:77], v[200:203], v[176:179], v[74:77]
	v_mfma_f32_16x16x32_bf16 v[70:73], v[192:195], v[184:187], v[70:73]
	v_mfma_f32_16x16x32_bf16 v[66:69], v[200:203], v[184:187], v[66:69]
	v_mfma_f32_16x16x32_bf16 v[110:113], v[196:199], v[164:167], v[110:113]
	v_mfma_f32_16x16x32_bf16 v[106:109], v[204:207], v[164:167], v[106:109]
	v_mfma_f32_16x16x32_bf16 v[94:97], v[196:199], v[172:175], v[94:97]
	v_mfma_f32_16x16x32_bf16 v[90:93], v[204:207], v[172:175], v[90:93]
	v_mfma_f32_16x16x32_bf16 v[78:81], v[196:199], v[180:183], v[78:81]
	v_mfma_f32_16x16x32_bf16 v[74:77], v[204:207], v[180:183], v[74:77]
	v_mfma_f32_16x16x32_bf16 v[70:73], v[196:199], v[188:191], v[70:73]
	v_mfma_f32_16x16x32_bf16 v[66:69], v[204:207], v[188:191], v[66:69]
	s_setprio 0
	s_mov_b32 m0, s5
	v_lshl_add_u64 v[214:215], s[20:21], 0, v[130:131]
	s_barrier
	ds_read_b128 v[160:163], v143 offset:16384
	ds_read_b128 v[164:167], v143 offset:17408
	ds_read_b128 v[168:171], v143 offset:18432
	ds_read_b128 v[172:175], v143 offset:19456
	ds_read_b128 v[176:179], v143 offset:20480
	ds_read_b128 v[180:183], v143 offset:21504
	ds_read_b128 v[184:187], v143 offset:22528
	ds_read_b128 v[188:191], v143 offset:23552
	global_load_lds_dwordx4 v[214:215], off
	s_mov_b32 m0, s43
	v_lshl_add_u64 v[216:217], s[20:21], 0, v[132:133]
	global_load_lds_dwordx4 v[216:217], off
	s_barrier
	s_waitcnt lgkmcnt(0)
	s_setprio 1
	v_mfma_f32_16x16x32_bf16 v[62:65], v[144:147], v[160:163], v[62:65]
	v_mfma_f32_16x16x32_bf16 v[58:61], v[152:155], v[160:163], v[58:61]
	v_mfma_f32_16x16x32_bf16 v[54:57], v[144:147], v[168:171], v[54:57]
	v_mfma_f32_16x16x32_bf16 v[50:53], v[152:155], v[168:171], v[50:53]
	v_mfma_f32_16x16x32_bf16 v[38:41], v[144:147], v[176:179], v[38:41]
	v_mfma_f32_16x16x32_bf16 v[34:37], v[152:155], v[176:179], v[34:37]
	v_mfma_f32_16x16x32_bf16 v[22:25], v[144:147], v[184:187], v[22:25]
	v_mfma_f32_16x16x32_bf16 v[18:21], v[152:155], v[184:187], v[18:21]
	v_mfma_f32_16x16x32_bf16 v[62:65], v[148:151], v[164:167], v[62:65]
	v_mfma_f32_16x16x32_bf16 v[58:61], v[156:159], v[164:167], v[58:61]
	v_mfma_f32_16x16x32_bf16 v[54:57], v[148:151], v[172:175], v[54:57]
	v_mfma_f32_16x16x32_bf16 v[50:53], v[156:159], v[172:175], v[50:53]
	v_mfma_f32_16x16x32_bf16 v[38:41], v[148:151], v[180:183], v[38:41]
	v_mfma_f32_16x16x32_bf16 v[34:37], v[156:159], v[180:183], v[34:37]
	v_mfma_f32_16x16x32_bf16 v[22:25], v[148:151], v[188:191], v[22:25]
	v_mfma_f32_16x16x32_bf16 v[18:21], v[156:159], v[188:191], v[18:21]
	s_setprio 0
	s_barrier
; #define PG8_STAGE(bufoff, gbase, voff) do { _Pragma("unroll") for (int _i = 0; _i < 2; ++_i) \
;         __builtin_amdgcn_global_load_lds((const unsigned*)((const char*)(gbase) + (voff)[_i]), (LAS unsigned*)(lds + (bufoff) + ldsw + _i * 8192), 16, 0, 0); } while (0)
; #define PG8_LDA(dst, b, h) do { _Pragma("unroll") for (int m = 0; m < 4; ++m) _Pragma("unroll") for (int k = 0; k < 2; ++k) dst[m][k] = *(const LAS bf16x8*)(lds + PG8_SA(b, h) + aoff + m * 2048 + k * 1024); } while (0)
; #define PG8_LDB(dst, b, h) do { _Pragma("unroll") for (int n = 0; n < 2; ++n) _Pragma("unroll") for (int k = 0; k < 2; ++k) dst[n][k] = *(const LAS bf16x8*)(lds + PG8_SB(b, h) + boff + n * 2048 + k * 1024); } while (0)
; #define PG8_MMA(ai, bj, At, Bt) do { __builtin_amdgcn_s_setprio(1); _Pragma("unroll") for (int m = 0; m < 4; ++m) _Pragma("unroll") for (int n = 0; n < 2; ++n) _Pragma("unroll") for (int k = 0; k < 2; ++k) \
;         acc[ai][bj][m][n] = __builtin_amdgcn_mfma_f32_16x16x32_bf16(Bt[n][k], At[m][k], acc[ai][bj][m][n], 0, 0, 0); __builtin_amdgcn_s_setprio(0); } while (0)
; #define PG8_WAIT_V(n) asm volatile("s_waitcnt vmcnt(" #n ")" ::: "memory")
; #define PG8_WAIT_L(n) asm volatile("s_waitcnt lgkmcnt(" #n ")" ::: "memory")
; #define PG8_BAR __builtin_amdgcn_s_barrier()
; #define PG8_SCHED __builtin_amdgcn_sched_barrier(0)
; template <class Epi, class Sched>
; __device__ __forceinline__ void gemm_phase(LAS unsigned char* lds, const Gemm g, const Sched& S, const Epi& E, const int tid) {
;     ...
;             PG8_STAGE(PG8_SB(0, 1), b2 + hstep, voffB);
;             PG8_WAIT_V(6); PG8_BAR; PG8_MMA(1, 1, At, B1); PG8_BAR;
;             PG8_LDB(B0, 1, 0); PG8_SCHED; PG8_LDA(At, 1, 0); PG8_STAGE(PG8_SA(0, 1), a2 + hstep, voffA);
;             PG8_WAIT_L(8); PG8_BAR; PG8_WAIT_L(0); PG8_MMA(0, 0, At, B0); PG8_BAR; PG8_SCHED;
;             PG8_LDB(B1, 1, 1); PG8_STAGE(PG8_SB(1, 0), b3, voffB);
;             PG8_BAR; PG8_WAIT_L(0); PG8_MMA(0, 1, At, B1); PG8_BAR;
;             PG8_LDA(At, 1, 1); PG8_STAGE(PG8_SA(1, 0), a3, voffA);
	s_add_u32 s54, s18, 0x80000
	s_addc_u32 s55, s19, 0
	s_add_i32 s53, s56, s42
	s_mov_b32 m0, s53
	s_nop 0
	global_load_lds_dwordx4 v0, s[54:55]
	s_add_i32 m0, s53, 0x2000
	s_nop 0
	global_load_lds_dwordx4 v134, s[54:55]
	s_waitcnt vmcnt(6)
	s_barrier
	s_setprio 1
	v_mfma_f32_16x16x32_bf16 v[46:49], v[192:195], v[160:163], v[46:49]
	v_mfma_f32_16x16x32_bf16 v[42:45], v[200:203], v[160:163], v[42:45]
	v_mfma_f32_16x16x32_bf16 v[30:33], v[192:195], v[168:171], v[30:33]
	v_mfma_f32_16x16x32_bf16 v[26:29], v[200:203], v[168:171], v[26:29]
	v_mfma_f32_16x16x32_bf16 v[14:17], v[192:195], v[176:179], v[14:17]
	v_mfma_f32_16x16x32_bf16 v[10:13], v[200:203], v[176:179], v[10:13]
	v_mfma_f32_16x16x32_bf16 v[6:9], v[192:195], v[184:187], v[6:9]
	v_mfma_f32_16x16x32_bf16 v[2:5], v[200:203], v[184:187], v[2:5]
	v_mfma_f32_16x16x32_bf16 v[46:49], v[196:199], v[164:167], v[46:49]
	v_mfma_f32_16x16x32_bf16 v[42:45], v[204:207], v[164:167], v[42:45]
	v_mfma_f32_16x16x32_bf16 v[30:33], v[196:199], v[172:175], v[30:33]
	v_mfma_f32_16x16x32_bf16 v[26:29], v[204:207], v[172:175], v[26:29]
	v_mfma_f32_16x16x32_bf16 v[14:17], v[196:199], v[180:183], v[14:17]
	v_mfma_f32_16x16x32_bf16 v[10:13], v[204:207], v[180:183], v[10:13]
	v_mfma_f32_16x16x32_bf16 v[6:9], v[196:199], v[188:191], v[6:9]
	v_mfma_f32_16x16x32_bf16 v[2:5], v[204:207], v[188:191], v[2:5]
	s_setprio 0
	s_add_i32 s53, 0, 0x18000
	v_add_u32_e32 v156, s53, v141
	s_barrier
	ds_read_b128 v[144:147], v156
	ds_read_b128 v[148:151], v156 offset:1024
	ds_read_b128 v[152:155], v156 offset:2048
	ds_read_b128 v[156:159], v156 offset:3072
	s_add_u32 s20, s20, 0x80000
	s_addc_u32 s21, s21, 0
	s_mov_b32 m0, s44
	ds_read_b128 v[160:163], v143 offset:32768
	ds_read_b128 v[164:167], v143 offset:33792
	ds_read_b128 v[168:171], v143 offset:34816
	ds_read_b128 v[172:175], v143 offset:35840
	ds_read_b128 v[176:179], v143 offset:36864
	ds_read_b128 v[180:183], v143 offset:37888
	ds_read_b128 v[184:187], v143 offset:38912
	ds_read_b128 v[188:191], v143 offset:39936
	global_load_lds_dwordx4 v130, s[20:21]
	s_mov_b32 m0, s45
	s_nop 0
	global_load_lds_dwordx4 v132, s[20:21]
	s_waitcnt lgkmcnt(8)
	s_barrier
	s_waitcnt lgkmcnt(0)
	s_setprio 1
	v_mfma_f32_16x16x32_bf16 v[126:129], v[144:147], v[160:163], v[126:129]
	v_mfma_f32_16x16x32_bf16 v[122:125], v[152:155], v[160:163], v[122:125]
	v_mfma_f32_16x16x32_bf16 v[118:121], v[144:147], v[168:171], v[118:121]
	v_mfma_f32_16x16x32_bf16 v[114:117], v[152:155], v[168:171], v[114:117]
	v_mfma_f32_16x16x32_bf16 v[102:105], v[144:147], v[176:179], v[102:105]
	v_mfma_f32_16x16x32_bf16 v[98:101], v[152:155], v[176:179], v[98:101]
	v_mfma_f32_16x16x32_bf16 v[86:89], v[144:147], v[184:187], v[86:89]
	v_mfma_f32_16x16x32_bf16 v[82:85], v[152:155], v[184:187], v[82:85]
	v_mfma_f32_16x16x32_bf16 v[126:129], v[148:151], v[164:167], v[126:129]
	v_mfma_f32_16x16x32_bf16 v[122:125], v[156:159], v[164:167], v[122:125]
	v_mfma_f32_16x16x32_bf16 v[118:121], v[148:151], v[172:175], v[118:121]
	v_mfma_f32_16x16x32_bf16 v[114:117], v[156:159], v[172:175], v[114:117]
	v_mfma_f32_16x16x32_bf16 v[102:105], v[148:151], v[180:183], v[102:105]
	v_mfma_f32_16x16x32_bf16 v[98:101], v[156:159], v[180:183], v[98:101]
	v_mfma_f32_16x16x32_bf16 v[86:89], v[148:151], v[188:191], v[86:89]
	v_mfma_f32_16x16x32_bf16 v[82:85], v[156:159], v[188:191], v[82:85]
	s_setprio 0
	s_barrier
	s_add_i32 s20, 0, 0x1c000
	s_add_i32 s21, s53, s42
	v_add_u32_e32 v204, s20, v141
	v_lshl_add_u64 v[208:209], v[208:209], 0, s[36:37]
	s_mov_b32 m0, s21
	ds_read_b128 v[192:195], v204
	ds_read_b128 v[196:199], v204 offset:1024
	ds_read_b128 v[200:203], v204 offset:2048
	ds_read_b128 v[204:207], v204 offset:3072
	global_load_lds_dwordx4 v[208:209], off
	s_add_i32 m0, s21, 0x2000
	v_lshl_add_u64 v[208:209], v[210:211], 0, s[36:37]
	global_load_lds_dwordx4 v[208:209], off
	s_barrier
	s_waitcnt lgkmcnt(0)
	s_setprio 1
	v_mfma_f32_16x16x32_bf16 v[110:113], v[192:195], v[160:163], v[110:113]
	v_mfma_f32_16x16x32_bf16 v[106:109], v[200:203], v[160:163], v[106:109]
	v_mfma_f32_16x16x32_bf16 v[94:97], v[192:195], v[168:171], v[94:97]
	v_mfma_f32_16x16x32_bf16 v[90:93], v[200:203], v[168:171], v[90:93]
	v_mfma_f32_16x16x32_bf16 v[78:81], v[192:195], v[176:179], v[78:81]
	v_mfma_f32_16x16x32_bf16 v[74:77], v[200:203], v[176:179], v[74:77]
	v_mfma_f32_16x16x32_bf16 v[70:73], v[192:195], v[184:187], v[70:73]
	v_mfma_f32_16x16x32_bf16 v[66:69], v[200:203], v[184:187], v[66:69]
	v_mfma_f32_16x16x32_bf16 v[110:113], v[196:199], v[164:167], v[110:113]
	v_mfma_f32_16x16x32_bf16 v[106:109], v[204:207], v[164:167], v[106:109]
	v_mfma_f32_16x16x32_bf16 v[94:97], v[196:199], v[172:175], v[94:97]
	v_mfma_f32_16x16x32_bf16 v[90:93], v[204:207], v[172:175], v[90:93]
	v_mfma_f32_16x16x32_bf16 v[78:81], v[196:199], v[180:183], v[78:81]
	v_mfma_f32_16x16x32_bf16 v[74:77], v[204:207], v[180:183], v[74:77]
	v_mfma_f32_16x16x32_bf16 v[70:73], v[196:199], v[188:191], v[70:73]
	v_mfma_f32_16x16x32_bf16 v[66:69], v[204:207], v[188:191], v[66:69]
	s_setprio 0
	s_mov_b32 m0, s28
	v_lshl_add_u64 v[208:209], v[214:215], 0, s[36:37]
	s_barrier
	ds_read_b128 v[160:163], v143 offset:49152
	ds_read_b128 v[164:167], v143 offset:50176
	ds_read_b128 v[168:171], v143 offset:51200
	ds_read_b128 v[172:175], v143 offset:52224
	ds_read_b128 v[176:179], v143 offset:53248
	ds_read_b128 v[180:183], v143 offset:54272
	ds_read_b128 v[184:187], v143 offset:55296
	ds_read_b128 v[188:191], v143 offset:56320
	global_load_lds_dwordx4 v[208:209], off
	s_mov_b32 m0, s29
	v_lshl_add_u64 v[208:209], v[216:217], 0, s[36:37]
	global_load_lds_dwordx4 v[208:209], off
	s_barrier
; #define PG8_STAGE(bufoff, gbase, voff) do { _Pragma("unroll") for (int _i = 0; _i < 2; ++_i) \
;         __builtin_amdgcn_global_load_lds((const unsigned*)((const char*)(gbase) + (voff)[_i]), (LAS unsigned*)(lds + (bufoff) + ldsw + _i * 8192), 16, 0, 0); } while (0)
; #define PG8_MMA(ai, bj, At, Bt) do { __builtin_amdgcn_s_setprio(1); _Pragma("unroll") for (int m = 0; m < 4; ++m) _Pragma("unroll") for (int n = 0; n < 2; ++n) _Pragma("unroll") for (int k = 0; k < 2; ++k) \
;         acc[ai][bj][m][n] = __builtin_amdgcn_mfma_f32_16x16x32_bf16(Bt[n][k], At[m][k], acc[ai][bj][m][n], 0, 0, 0); __builtin_amdgcn_s_setprio(0); } while (0)
; #define PG8_WAIT_V(n) asm volatile("s_waitcnt vmcnt(" #n ")" ::: "memory")
; #define PG8_WAIT_L(n) asm volatile("s_waitcnt lgkmcnt(" #n ")" ::: "memory")
; #define PG8_BAR __builtin_amdgcn_s_barrier()
; #define PG8_SCHED __builtin_amdgcn_sched_barrier(0)
; template <class Epi, class Sched>
; __device__ __forceinline__ void gemm_phase(LAS unsigned char* lds, const Gemm g, const Sched& S, const Epi& E, const int tid) {
;     ...
;         for (int t = 0; t < nt; t += 2) {
;     ...
;             PG8_BAR; PG8_WAIT_L(0); PG8_MMA(1, 0, At, B0); PG8_BAR; PG8_SCHED;
;             PG8_STAGE(PG8_SB(1, 1), b3 + hstep, voffB);
;             PG8_WAIT_V(6); PG8_BAR; PG8_MMA(1, 1, At, B1); PG8_BAR;
	s_waitcnt lgkmcnt(0)
	s_setprio 1
	v_mfma_f32_16x16x32_bf16 v[62:65], v[144:147], v[160:163], v[62:65]
	v_mfma_f32_16x16x32_bf16 v[58:61], v[152:155], v[160:163], v[58:61]
	v_mfma_f32_16x16x32_bf16 v[54:57], v[144:147], v[168:171], v[54:57]
	v_mfma_f32_16x16x32_bf16 v[50:53], v[152:155], v[168:171], v[50:53]
	v_mfma_f32_16x16x32_bf16 v[38:41], v[144:147], v[176:179], v[38:41]
	v_mfma_f32_16x16x32_bf16 v[34:37], v[152:155], v[176:179], v[34:37]
	v_mfma_f32_16x16x32_bf16 v[22:25], v[144:147], v[184:187], v[22:25]
	v_mfma_f32_16x16x32_bf16 v[18:21], v[152:155], v[184:187], v[18:21]
	v_mfma_f32_16x16x32_bf16 v[62:65], v[148:151], v[164:167], v[62:65]
	v_mfma_f32_16x16x32_bf16 v[58:61], v[156:159], v[164:167], v[58:61]
	v_mfma_f32_16x16x32_bf16 v[54:57], v[148:151], v[172:175], v[54:57]
	v_mfma_f32_16x16x32_bf16 v[50:53], v[156:159], v[172:175], v[50:53]
	v_mfma_f32_16x16x32_bf16 v[38:41], v[148:151], v[180:183], v[38:41]
	v_mfma_f32_16x16x32_bf16 v[34:37], v[156:159], v[180:183], v[34:37]
	v_mfma_f32_16x16x32_bf16 v[22:25], v[148:151], v[188:191], v[22:25]
	v_mfma_f32_16x16x32_bf16 v[18:21], v[156:159], v[188:191], v[18:21]
	s_setprio 0
	s_barrier
	s_add_u32 s18, s18, 0x80080
	s_addc_u32 s19, s19, 0
	s_add_i32 s20, s20, s42
	s_mov_b32 m0, s20
	s_nop 0
	global_load_lds_dwordx4 v0, s[18:19]
	s_add_i32 m0, s20, 0x2000
	s_nop 0
	global_load_lds_dwordx4 v134, s[18:19]
	s_waitcnt vmcnt(6)
	s_barrier
	s_setprio 1
	v_mfma_f32_16x16x32_bf16 v[46:49], v[192:195], v[160:163], v[46:49]
	v_mfma_f32_16x16x32_bf16 v[42:45], v[200:203], v[160:163], v[42:45]
	v_mfma_f32_16x16x32_bf16 v[30:33], v[192:195], v[168:171], v[30:33]
	v_mfma_f32_16x16x32_bf16 v[26:29], v[200:203], v[168:171], v[26:29]
	v_mfma_f32_16x16x32_bf16 v[14:17], v[192:195], v[176:179], v[14:17]
	v_mfma_f32_16x16x32_bf16 v[10:13], v[200:203], v[176:179], v[10:13]
	v_mfma_f32_16x16x32_bf16 v[6:9], v[192:195], v[184:187], v[6:9]
	v_mfma_f32_16x16x32_bf16 v[2:5], v[200:203], v[184:187], v[2:5]
	v_mfma_f32_16x16x32_bf16 v[46:49], v[196:199], v[164:167], v[46:49]
	v_mfma_f32_16x16x32_bf16 v[42:45], v[204:207], v[164:167], v[42:45]
	v_mfma_f32_16x16x32_bf16 v[30:33], v[196:199], v[172:175], v[30:33]
	v_mfma_f32_16x16x32_bf16 v[26:29], v[204:207], v[172:175], v[26:29]
	v_mfma_f32_16x16x32_bf16 v[14:17], v[196:199], v[180:183], v[14:17]
	v_mfma_f32_16x16x32_bf16 v[10:13], v[204:207], v[180:183], v[10:13]
	v_mfma_f32_16x16x32_bf16 v[6:9], v[196:199], v[188:191], v[6:9]
	v_mfma_f32_16x16x32_bf16 v[2:5], v[204:207], v[188:191], v[2:5]
	s_setprio 0
	s_add_i32 s52, s52, 2
	s_add_u32 s16, s16, 0x100
	s_addc_u32 s17, s17, 0
	s_add_u32 s50, s50, 0x100
	s_addc_u32 s51, s51, 0
	s_cmp_gt_u32 s52, 29
	s_barrier
	s_cbranch_scc0 .LBB0_277
; DI unsigned cvtpk(float lo, float hi) { const f32x2 v = {lo, hi}; const bf16x2n r = __builtin_convertvector(v, bf16x2n); return __builtin_bit_cast(unsigned, r); }
; #define PG8_WAIT_V(n) asm volatile("s_waitcnt vmcnt(" #n ")" ::: "memory")
; #define PG8_BAR __builtin_amdgcn_s_barrier()
;     __device__ __forceinline__ void operator()(const f32x4 (&acc)[2][2][4][2], const Unit& u, int wr, int wc, int fr, int fq) const {
;     ...
; #pragma unroll
;         for (int ai = 0; ai < 2; ++ai)
; #pragma unroll
;             for (int m = 0; m < 4; ++m) { bf16_t* rowp = O + (size_t)(row0 + ai * HALF + m * 16) * ldc + col0;
; #pragma unroll
;                 for (int bj = 0; bj < 2; ++bj) { const f32x4 v0 = acc[ai][bj][m][0], v1 = acc[ai][bj][m][1];
;                     u32x4 w; w.x = cvtpk(v0[0], v0[1]); w.y = cvtpk(v0[2], v0[3]); w.z = cvtpk(v1[0], v1[1]); w.w = cvtpk(v1[2], v1[3]);
;                     *(u32x4*)(rowp + bj * HALF) = w; } }
; template <class Epi, class Sched>
; __device__ __forceinline__ void gemm_phase(LAS unsigned char* lds, const Gemm g, const Sched& S, const Epi& E, const int tid) {
;     ...
;         if constexpr (!Epi::AFTER_DRAIN) { if constexpr (Epi::PRELOAD) E(acc, cur, wr, wc, fr, fq, lds); else E(acc, cur, wr, wc, fr, fq); S.done(cur); }
;         if (!has_next) break;
;     ...
;     PG8_WAIT_V(0);
;     if (wr == 0) PG8_BAR;
	v_lshl_or_b32 v144, s24, 8, v142
	v_lshl_add_u32 v150, s4, 8, v140
	v_ashrrev_i32_e32 v145, 31, v144
	v_mov_b64_e32 v[146:147], s[2:3]
	s_movk_i32 s4, 0x2e00
	v_cvt_pk_bf16_f32 v70, v70, v71
	v_cvt_pk_bf16_f32 v71, v72, v73
	v_cvt_pk_bf16_f32 v72, v66, v67
	v_add_u32_e32 v66, 0x80, v150
	v_mad_i64_i32 v[148:149], s[16:17], v150, s4, v[146:147]
	v_lshlrev_b64 v[144:145], 1, v[144:145]
	v_cvt_pk_bf16_f32 v110, v110, v111
	v_cvt_pk_bf16_f32 v111, v112, v113
	v_cvt_pk_bf16_f32 v112, v106, v107
	v_or_b32_e32 v106, 16, v150
	v_mad_i64_i32 v[66:67], s[16:17], v66, s4, v[146:147]
	v_cvt_pk_bf16_f32 v46, v46, v47
	v_cvt_pk_bf16_f32 v47, v48, v49
	v_cvt_pk_bf16_f32 v48, v42, v43
	v_add_u32_e32 v42, 0x90, v150
	v_lshl_add_u64 v[148:149], v[148:149], 0, v[144:145]
	v_cvt_pk_bf16_f32 v113, v108, v109
	v_mad_i64_i32 v[106:107], s[16:17], v106, s4, v[146:147]
	v_cvt_pk_bf16_f32 v94, v94, v95
	v_cvt_pk_bf16_f32 v95, v96, v97
	v_cvt_pk_bf16_f32 v96, v90, v91
	v_or_b32_e32 v90, 32, v150
	v_lshl_add_u64 v[66:67], v[66:67], 0, v[144:145]
	v_cvt_pk_bf16_f32 v49, v44, v45
	v_mad_i64_i32 v[42:43], s[16:17], v42, s4, v[146:147]
	v_cvt_pk_bf16_f32 v30, v30, v31
	v_cvt_pk_bf16_f32 v31, v32, v33
	v_cvt_pk_bf16_f32 v32, v26, v27
	v_add_u32_e32 v26, 0xa0, v150
	global_store_dwordx4 v[148:149], v[110:113], off offset:256
	v_cvt_pk_bf16_f32 v97, v92, v93
	v_mad_i64_i32 v[90:91], s[16:17], v90, s4, v[146:147]
	v_lshl_add_u64 v[110:111], v[106:107], 0, v[144:145]
	v_cvt_pk_bf16_f32 v78, v78, v79
	v_cvt_pk_bf16_f32 v79, v80, v81
	v_cvt_pk_bf16_f32 v80, v74, v75
	v_or_b32_e32 v74, 48, v150
	global_store_dwordx4 v[66:67], v[46:49], off offset:256
	v_cvt_pk_bf16_f32 v33, v28, v29
	v_mad_i64_i32 v[26:27], s[16:17], v26, s4, v[146:147]
	v_lshl_add_u64 v[46:47], v[42:43], 0, v[144:145]
	v_cvt_pk_bf16_f32 v14, v14, v15
	v_cvt_pk_bf16_f32 v15, v16, v17
	v_cvt_pk_bf16_f32 v16, v10, v11
	v_add_u32_e32 v10, 0xb0, v150
	global_store_dwordx4 v[110:111], v[94:97], off offset:256
	v_cvt_pk_bf16_f32 v81, v76, v77
	v_mad_i64_i32 v[74:75], s[16:17], v74, s4, v[146:147]
	v_lshl_add_u64 v[94:95], v[90:91], 0, v[144:145]
	global_store_dwordx4 v[46:47], v[30:33], off offset:256
	v_cvt_pk_bf16_f32 v17, v12, v13
	v_mad_i64_i32 v[10:11], s[16:17], v10, s4, v[146:147]
	v_lshl_add_u64 v[30:31], v[26:27], 0, v[144:145]
	v_cvt_pk_bf16_f32 v126, v126, v127
	v_cvt_pk_bf16_f32 v127, v128, v129
	v_cvt_pk_bf16_f32 v128, v122, v123
	v_cvt_pk_bf16_f32 v129, v124, v125
	v_cvt_pk_bf16_f32 v106, v118, v119
	v_cvt_pk_bf16_f32 v107, v120, v121
	v_cvt_pk_bf16_f32 v108, v114, v115
	v_cvt_pk_bf16_f32 v109, v116, v117
	v_cvt_pk_bf16_f32 v90, v102, v103
	v_cvt_pk_bf16_f32 v91, v104, v105
	v_cvt_pk_bf16_f32 v92, v98, v99
	v_cvt_pk_bf16_f32 v93, v100, v101
	global_store_dwordx4 v[94:95], v[78:81], off offset:256
	v_cvt_pk_bf16_f32 v76, v82, v83
	v_cvt_pk_bf16_f32 v77, v84, v85
	v_lshl_add_u64 v[78:79], v[74:75], 0, v[144:145]
	v_cvt_pk_bf16_f32 v74, v86, v87
	v_cvt_pk_bf16_f32 v75, v88, v89
	v_cvt_pk_bf16_f32 v73, v68, v69
	v_cvt_pk_bf16_f32 v62, v62, v63
	v_cvt_pk_bf16_f32 v63, v64, v65
	v_cvt_pk_bf16_f32 v64, v58, v59
	v_cvt_pk_bf16_f32 v65, v60, v61
	v_cvt_pk_bf16_f32 v42, v54, v55
	v_cvt_pk_bf16_f32 v43, v56, v57
	v_cvt_pk_bf16_f32 v44, v50, v51
	v_cvt_pk_bf16_f32 v45, v52, v53
	v_cvt_pk_bf16_f32 v26, v38, v39
	v_cvt_pk_bf16_f32 v27, v40, v41
	v_cvt_pk_bf16_f32 v28, v34, v35
	v_cvt_pk_bf16_f32 v29, v36, v37
	global_store_dwordx4 v[30:31], v[14:17], off offset:256
	v_cvt_pk_bf16_f32 v12, v18, v19
	v_cvt_pk_bf16_f32 v13, v20, v21
	v_lshl_add_u64 v[14:15], v[10:11], 0, v[144:145]
	v_cvt_pk_bf16_f32 v10, v22, v23
	v_cvt_pk_bf16_f32 v11, v24, v25
	v_cvt_pk_bf16_f32 v6, v6, v7
	v_cvt_pk_bf16_f32 v7, v8, v9
	v_cvt_pk_bf16_f32 v8, v2, v3
	v_cvt_pk_bf16_f32 v9, v4, v5
	s_and_b64 vcc, exec, s[0:1]
	s_mov_b32 s24, s6
	s_mov_b32 s4, s10
	s_mov_b64 s[18:19], s[14:15]
	s_mov_b64 s[16:17], s[12:13]
	s_mov_b64 s[52:53], 0xc000
	s_mov_b64 s[54:55], 0x8000
	global_store_dwordx4 v[148:149], v[126:129], off
	global_store_dwordx4 v[110:111], v[106:109], off
	global_store_dwordx4 v[94:95], v[90:93], off
	global_store_dwordx4 v[78:79], v[74:77], off
	global_store_dwordx4 v[78:79], v[70:73], off offset:256
	global_store_dwordx4 v[66:67], v[62:65], off
	global_store_dwordx4 v[46:47], v[42:45], off
	global_store_dwordx4 v[30:31], v[26:29], off
	global_store_dwordx4 v[14:15], v[10:13], off
	global_store_dwordx4 v[14:15], v[6:9], off offset:256
	s_cbranch_vccz .LBB0_270
	s_waitcnt vmcnt(0)
	s_cmpk_gt_u32 s22, 0xff
	s_cbranch_scc1 .LBB0_281
	s_barrier

; #define PG8_STAGE(bufoff, gbase, voff) do { _Pragma("unroll") for (int _i = 0; _i < 2; ++_i) \
;         __builtin_amdgcn_global_load_lds((const unsigned*)((const char*)(gbase) + (voff)[_i]), (LAS unsigned*)(lds + (bufoff) + ldsw + _i * 8192), 16, 0, 0); } while (0)
; #define PG8_LDA(dst, b, h) do { _Pragma("unroll") for (int m = 0; m < 4; ++m) _Pragma("unroll") for (int k = 0; k < 2; ++k) dst[m][k] = *(const LAS bf16x8*)(lds + PG8_SA(b, h) + aoff + m * 2048 + k * 1024); } while (0)
; #define PG8_LDB(dst, b, h) do { _Pragma("unroll") for (int n = 0; n < 2; ++n) _Pragma("unroll") for (int k = 0; k < 2; ++k) dst[n][k] = *(const LAS bf16x8*)(lds + PG8_SB(b, h) + boff + n * 2048 + k * 1024); } while (0)
; #define PG8_MMA(ai, bj, At, Bt) do { __builtin_amdgcn_s_setprio(1); _Pragma("unroll") for (int m = 0; m < 4; ++m) _Pragma("unroll") for (int n = 0; n < 2; ++n) _Pragma("unroll") for (int k = 0; k < 2; ++k) \
;         acc[ai][bj][m][n] = __builtin_amdgcn_mfma_f32_16x16x32_bf16(Bt[n][k], At[m][k], acc[ai][bj][m][n], 0, 0, 0); __builtin_amdgcn_s_setprio(0); } while (0)
; #define PG8_WAIT_L(n) asm volatile("s_waitcnt lgkmcnt(" #n ")" ::: "memory")
; #define PG8_BAR __builtin_amdgcn_s_barrier()
; #define PG8_SCHED __builtin_amdgcn_sched_barrier(0)
; template <class Epi, class Sched>
; __device__ __forceinline__ void gemm_phase(LAS unsigned char* lds, const Gemm g, const Sched& S, const Epi& E, const int tid) {
;     ...
;             const bool last = (t == nt - 2);
;             const char* a1 = cA + (size_t)(t + 1) * kstep;
;             const char* a2 = last ? nA : cA + (size_t)(t + 2) * kstep; const char* b2 = last ? nB : cB + (size_t)(t + 2) * kstep;
;             const char* a3 = a2 + kstep; const char* b3 = b2 + kstep;
;             if (last && has_next) S.a_ready(nxt);
;             if constexpr (Epi::PRELOAD) { if (last) E.preload(cur, lds, wid, lane); }
;             PG8_LDB(B0, 0, 0); PG8_SCHED; PG8_LDA(At, 0, 0); PG8_STAGE(PG8_SA(1, 1), a1 + hstep, voffA);
;             PG8_WAIT_L(8); PG8_BAR; PG8_WAIT_L(0); PG8_MMA(0, 0, At, B0); PG8_BAR; PG8_SCHED;
;             PG8_LDB(B1, 0, 1); PG8_STAGE(PG8_SB(0, 0), b2, voffB);
;             PG8_BAR; PG8_WAIT_L(0); PG8_MMA(0, 1, At, B1); PG8_BAR;
;             PG8_LDA(At, 0, 1); PG8_STAGE(PG8_SA(0, 0), a2, voffA);
;             PG8_BAR; PG8_WAIT_L(0); PG8_MMA(1, 0, At, B0); PG8_BAR; PG8_SCHED;
.LBB0_538:
	s_add_i32 s74, s22, 2
	s_add_u32 s38, s2, 0x80
	s_addc_u32 s23, s3, 0
	s_add_i32 s75, 0, 0x10000
	v_add_u32_e32 v0, s75, v160
	ds_read_b128 v[144:147], v0
	ds_read_b128 v[164:167], v0 offset:1024
	ds_read_b128 v[168:171], v0 offset:2048
	ds_read_b128 v[172:175], v0 offset:3072
	s_cmp_eq_u32 s24, s22
	s_cselect_b32 s22, s20, s38
	s_cselect_b32 s23, s21, s23
	s_cselect_b32 s39, s5, s29
	s_cselect_b32 s38, s4, s25
	v_lshl_add_u64 v[148:149], s[2:3], 0, v[138:139]
	s_add_i32 m0, s56, 0xc000
	ds_read_b128 v[176:179], v162
	ds_read_b128 v[180:183], v162 offset:1024
	ds_read_b128 v[184:187], v162 offset:2048
	ds_read_b128 v[188:191], v162 offset:3072
	ds_read_b128 v[192:195], v162 offset:4096
	ds_read_b128 v[196:199], v162 offset:5120
	ds_read_b128 v[200:203], v162 offset:6144
	ds_read_b128 v[204:207], v162 offset:7168
	global_load_lds_dwordx4 v[148:149], off
	s_add_i32 m0, s56, 0xe000
	v_lshl_add_u64 v[148:149], s[2:3], 0, v[140:141]
	global_load_lds_dwordx4 v[148:149], off
	s_waitcnt lgkmcnt(8)
	s_barrier
	s_waitcnt lgkmcnt(0)
	s_setprio 1
	v_mfma_f32_16x16x32_bf16 v[126:129], v[144:147], v[176:179], v[126:129]
	v_mfma_f32_16x16x32_bf16 v[122:125], v[168:171], v[176:179], v[122:125]
	v_mfma_f32_16x16x32_bf16 v[110:113], v[144:147], v[184:187], v[110:113]
	v_mfma_f32_16x16x32_bf16 v[106:109], v[168:171], v[184:187], v[106:109]
	v_mfma_f32_16x16x32_bf16 v[94:97], v[144:147], v[192:195], v[94:97]
	v_mfma_f32_16x16x32_bf16 v[90:93], v[168:171], v[192:195], v[90:93]
	v_mfma_f32_16x16x32_bf16 v[78:81], v[144:147], v[200:203], v[78:81]
	v_mfma_f32_16x16x32_bf16 v[74:77], v[168:171], v[200:203], v[74:77]
	v_mfma_f32_16x16x32_bf16 v[126:129], v[164:167], v[180:183], v[126:129]
	v_mfma_f32_16x16x32_bf16 v[122:125], v[172:175], v[180:183], v[122:125]
	v_mfma_f32_16x16x32_bf16 v[110:113], v[164:167], v[188:191], v[110:113]
	v_mfma_f32_16x16x32_bf16 v[106:109], v[172:175], v[188:191], v[106:109]
	v_mfma_f32_16x16x32_bf16 v[94:97], v[164:167], v[196:199], v[94:97]
	v_mfma_f32_16x16x32_bf16 v[90:93], v[172:175], v[196:199], v[90:93]
	v_mfma_f32_16x16x32_bf16 v[78:81], v[164:167], v[204:207], v[78:81]
	v_mfma_f32_16x16x32_bf16 v[74:77], v[172:175], v[204:207], v[74:77]
	s_setprio 0
	s_barrier
	s_add_i32 s76, 0, 0x14000
	s_add_i32 s75, s75, s51
	v_add_u32_e32 v0, s76, v160
	v_lshl_add_u64 v[148:149], s[38:39], 0, v[132:133]
	s_mov_b32 m0, s75
	ds_read_b128 v[208:211], v0
	ds_read_b128 v[214:217], v0 offset:1024
	ds_read_b128 v[218:221], v0 offset:2048
	ds_read_b128 v[222:225], v0 offset:3072
	global_load_lds_dwordx4 v[148:149], off
	s_add_i32 m0, s75, 0x2000
	v_lshl_add_u64 v[226:227], s[38:39], 0, v[136:137]
	global_load_lds_dwordx4 v[226:227], off
	s_barrier
	s_waitcnt lgkmcnt(0)
	s_setprio 1
	v_mfma_f32_16x16x32_bf16 v[118:121], v[208:211], v[176:179], v[118:121]
	v_mfma_f32_16x16x32_bf16 v[114:117], v[218:221], v[176:179], v[114:117]
	v_mfma_f32_16x16x32_bf16 v[102:105], v[208:211], v[184:187], v[102:105]
	v_mfma_f32_16x16x32_bf16 v[98:101], v[218:221], v[184:187], v[98:101]
	v_mfma_f32_16x16x32_bf16 v[86:89], v[208:211], v[192:195], v[86:89]
	v_mfma_f32_16x16x32_bf16 v[82:85], v[218:221], v[192:195], v[82:85]
	v_mfma_f32_16x16x32_bf16 v[70:73], v[208:211], v[200:203], v[70:73]
	v_mfma_f32_16x16x32_bf16 v[66:69], v[218:221], v[200:203], v[66:69]
	v_mfma_f32_16x16x32_bf16 v[118:121], v[214:217], v[180:183], v[118:121]
	v_mfma_f32_16x16x32_bf16 v[114:117], v[222:225], v[180:183], v[114:117]
	v_mfma_f32_16x16x32_bf16 v[102:105], v[214:217], v[188:191], v[102:105]
	v_mfma_f32_16x16x32_bf16 v[98:101], v[222:225], v[188:191], v[98:101]
	v_mfma_f32_16x16x32_bf16 v[86:89], v[214:217], v[196:199], v[86:89]
	v_mfma_f32_16x16x32_bf16 v[82:85], v[222:225], v[196:199], v[82:85]
	v_mfma_f32_16x16x32_bf16 v[70:73], v[214:217], v[204:207], v[70:73]
	v_mfma_f32_16x16x32_bf16 v[66:69], v[222:225], v[204:207], v[66:69]
	s_setprio 0
	s_mov_b32 m0, s56
	v_lshl_add_u64 v[228:229], s[22:23], 0, v[130:131]
	s_barrier
	ds_read_b128 v[176:179], v162 offset:16384
	ds_read_b128 v[180:183], v162 offset:17408
	ds_read_b128 v[184:187], v162 offset:18432
	ds_read_b128 v[188:191], v162 offset:19456
	ds_read_b128 v[192:195], v162 offset:20480
	ds_read_b128 v[196:199], v162 offset:21504
	ds_read_b128 v[200:203], v162 offset:22528
	ds_read_b128 v[204:207], v162 offset:23552
	global_load_lds_dwordx4 v[228:229], off
	s_mov_b32 m0, s57
	v_lshl_add_u64 v[230:231], s[22:23], 0, v[134:135]
	global_load_lds_dwordx4 v[230:231], off
	s_barrier
	s_waitcnt lgkmcnt(0)
	s_setprio 1
	v_mfma_f32_16x16x32_bf16 v[62:65], v[144:147], v[176:179], v[62:65]
	v_mfma_f32_16x16x32_bf16 v[58:61], v[168:171], v[176:179], v[58:61]
	v_mfma_f32_16x16x32_bf16 v[46:49], v[144:147], v[184:187], v[46:49]
	v_mfma_f32_16x16x32_bf16 v[42:45], v[168:171], v[184:187], v[42:45]
	v_mfma_f32_16x16x32_bf16 v[30:33], v[144:147], v[192:195], v[30:33]
	v_mfma_f32_16x16x32_bf16 v[26:29], v[168:171], v[192:195], v[26:29]
	v_mfma_f32_16x16x32_bf16 v[14:17], v[144:147], v[200:203], v[14:17]
	v_mfma_f32_16x16x32_bf16 v[10:13], v[168:171], v[200:203], v[10:13]
	v_mfma_f32_16x16x32_bf16 v[62:65], v[164:167], v[180:183], v[62:65]
	v_mfma_f32_16x16x32_bf16 v[58:61], v[172:175], v[180:183], v[58:61]
	v_mfma_f32_16x16x32_bf16 v[46:49], v[164:167], v[188:191], v[46:49]
	v_mfma_f32_16x16x32_bf16 v[42:45], v[172:175], v[188:191], v[42:45]
	v_mfma_f32_16x16x32_bf16 v[30:33], v[164:167], v[196:199], v[30:33]
	v_mfma_f32_16x16x32_bf16 v[26:29], v[172:175], v[196:199], v[26:29]
	v_mfma_f32_16x16x32_bf16 v[14:17], v[164:167], v[204:207], v[14:17]
	v_mfma_f32_16x16x32_bf16 v[10:13], v[172:175], v[204:207], v[10:13]
	s_setprio 0
	s_barrier
; #define PG8_STAGE(bufoff, gbase, voff) do { _Pragma("unroll") for (int _i = 0; _i < 2; ++_i) \
;         __builtin_amdgcn_global_load_lds((const unsigned*)((const char*)(gbase) + (voff)[_i]), (LAS unsigned*)(lds + (bufoff) + ldsw + _i * 8192), 16, 0, 0); } while (0)
; #define PG8_LDA(dst, b, h) do { _Pragma("unroll") for (int m = 0; m < 4; ++m) _Pragma("unroll") for (int k = 0; k < 2; ++k) dst[m][k] = *(const LAS bf16x8*)(lds + PG8_SA(b, h) + aoff + m * 2048 + k * 1024); } while (0)
; #define PG8_LDB(dst, b, h) do { _Pragma("unroll") for (int n = 0; n < 2; ++n) _Pragma("unroll") for (int k = 0; k < 2; ++k) dst[n][k] = *(const LAS bf16x8*)(lds + PG8_SB(b, h) + boff + n * 2048 + k * 1024); } while (0)
; #define PG8_MMA(ai, bj, At, Bt) do { __builtin_amdgcn_s_setprio(1); _Pragma("unroll") for (int m = 0; m < 4; ++m) _Pragma("unroll") for (int n = 0; n < 2; ++n) _Pragma("unroll") for (int k = 0; k < 2; ++k) \
;         acc[ai][bj][m][n] = __builtin_amdgcn_mfma_f32_16x16x32_bf16(Bt[n][k], At[m][k], acc[ai][bj][m][n], 0, 0, 0); __builtin_amdgcn_s_setprio(0); } while (0)
; #define PG8_WAIT_V(n) asm volatile("s_waitcnt vmcnt(" #n ")" ::: "memory")
; #define PG8_WAIT_L(n) asm volatile("s_waitcnt lgkmcnt(" #n ")" ::: "memory")
; #define PG8_BAR __builtin_amdgcn_s_barrier()
; #define PG8_SCHED __builtin_amdgcn_sched_barrier(0)
; template <class Epi, class Sched>
; __device__ __forceinline__ void gemm_phase(LAS unsigned char* lds, const Gemm g, const Sched& S, const Epi& E, const int tid) {
;     ...
;             PG8_STAGE(PG8_SB(0, 1), b2 + hstep, voffB);
;             PG8_WAIT_V(6); PG8_BAR; PG8_MMA(1, 1, At, B1); PG8_BAR;
;             PG8_LDB(B0, 1, 0); PG8_SCHED; PG8_LDA(At, 1, 0); PG8_STAGE(PG8_SA(0, 1), a2 + hstep, voffA);
;             PG8_WAIT_L(8); PG8_BAR; PG8_WAIT_L(0); PG8_MMA(0, 0, At, B0); PG8_BAR; PG8_SCHED;
;             PG8_LDB(B1, 1, 1); PG8_STAGE(PG8_SB(1, 0), b3, voffB);
;             PG8_BAR; PG8_WAIT_L(0); PG8_MMA(0, 1, At, B1); PG8_BAR;
;             PG8_LDA(At, 1, 1); PG8_STAGE(PG8_SA(1, 0), a3, voffA);
	s_add_u32 s38, s38, s8
	s_addc_u32 s39, s39, 0
	s_add_i32 s75, s76, s51
	v_lshl_add_u64 v[244:245], s[38:39], 0, v[132:133]
	s_mov_b32 m0, s75
	v_lshl_add_u64 v[246:247], s[38:39], 0, v[136:137]
	global_load_lds_dwordx4 v[244:245], off
	s_add_i32 m0, s75, 0x2000
	s_nop 0
	global_load_lds_dwordx4 v[246:247], off
	s_waitcnt vmcnt(6)
	s_barrier
	s_setprio 1
	v_mfma_f32_16x16x32_bf16 v[54:57], v[208:211], v[176:179], v[54:57]
	v_mfma_f32_16x16x32_bf16 v[50:53], v[218:221], v[176:179], v[50:53]
	v_mfma_f32_16x16x32_bf16 v[38:41], v[208:211], v[184:187], v[38:41]
	v_mfma_f32_16x16x32_bf16 v[34:37], v[218:221], v[184:187], v[34:37]
	v_mfma_f32_16x16x32_bf16 v[22:25], v[208:211], v[192:195], v[22:25]
	v_mfma_f32_16x16x32_bf16 v[18:21], v[218:221], v[192:195], v[18:21]
	v_mfma_f32_16x16x32_bf16 v[6:9], v[208:211], v[200:203], v[6:9]
	v_mfma_f32_16x16x32_bf16 v[2:5], v[218:221], v[200:203], v[2:5]
	v_mfma_f32_16x16x32_bf16 v[54:57], v[214:217], v[180:183], v[54:57]
	v_mfma_f32_16x16x32_bf16 v[50:53], v[222:225], v[180:183], v[50:53]
	v_mfma_f32_16x16x32_bf16 v[38:41], v[214:217], v[188:191], v[38:41]
	v_mfma_f32_16x16x32_bf16 v[34:37], v[222:225], v[188:191], v[34:37]
	v_mfma_f32_16x16x32_bf16 v[22:25], v[214:217], v[196:199], v[22:25]
	v_mfma_f32_16x16x32_bf16 v[18:21], v[222:225], v[196:199], v[18:21]
	v_mfma_f32_16x16x32_bf16 v[6:9], v[214:217], v[204:207], v[6:9]
	v_mfma_f32_16x16x32_bf16 v[2:5], v[222:225], v[204:207], v[2:5]
	s_setprio 0
	s_add_i32 s38, 0, 0x18000
	v_add_u32_e32 v0, s38, v160
	s_barrier
	ds_read_b128 v[144:147], v0
	ds_read_b128 v[164:167], v0 offset:1024
	ds_read_b128 v[168:171], v0 offset:2048
	ds_read_b128 v[172:175], v0 offset:3072
	s_add_u32 s22, s22, s8
	s_addc_u32 s23, s23, 0
	s_mov_b32 m0, s58
	ds_read_b128 v[176:179], v162 offset:32768
	ds_read_b128 v[180:183], v162 offset:33792
	ds_read_b128 v[184:187], v162 offset:34816
	ds_read_b128 v[188:191], v162 offset:35840
	ds_read_b128 v[192:195], v162 offset:36864
	ds_read_b128 v[196:199], v162 offset:37888
	ds_read_b128 v[200:203], v162 offset:38912
	ds_read_b128 v[204:207], v162 offset:39936
	global_load_lds_dwordx4 v130, s[22:23]
	s_mov_b32 m0, s59
	s_nop 0
	global_load_lds_dwordx4 v134, s[22:23]
	s_waitcnt lgkmcnt(8)
	s_barrier
	s_waitcnt lgkmcnt(0)
	s_setprio 1
	v_mfma_f32_16x16x32_bf16 v[126:129], v[144:147], v[176:179], v[126:129]
	v_mfma_f32_16x16x32_bf16 v[122:125], v[168:171], v[176:179], v[122:125]
	v_mfma_f32_16x16x32_bf16 v[110:113], v[144:147], v[184:187], v[110:113]
	v_mfma_f32_16x16x32_bf16 v[106:109], v[168:171], v[184:187], v[106:109]
	v_mfma_f32_16x16x32_bf16 v[94:97], v[144:147], v[192:195], v[94:97]
	v_mfma_f32_16x16x32_bf16 v[90:93], v[168:171], v[192:195], v[90:93]
	v_mfma_f32_16x16x32_bf16 v[78:81], v[144:147], v[200:203], v[78:81]
	v_mfma_f32_16x16x32_bf16 v[74:77], v[168:171], v[200:203], v[74:77]
	v_mfma_f32_16x16x32_bf16 v[126:129], v[164:167], v[180:183], v[126:129]
	v_mfma_f32_16x16x32_bf16 v[122:125], v[172:175], v[180:183], v[122:125]
	v_mfma_f32_16x16x32_bf16 v[110:113], v[164:167], v[188:191], v[110:113]
	v_mfma_f32_16x16x32_bf16 v[106:109], v[172:175], v[188:191], v[106:109]
	v_mfma_f32_16x16x32_bf16 v[94:97], v[164:167], v[196:199], v[94:97]
	v_mfma_f32_16x16x32_bf16 v[90:93], v[172:175], v[196:199], v[90:93]
	v_mfma_f32_16x16x32_bf16 v[78:81], v[164:167], v[204:207], v[78:81]
	v_mfma_f32_16x16x32_bf16 v[74:77], v[172:175], v[204:207], v[74:77]
	s_setprio 0
	s_barrier
	s_add_i32 s22, 0, 0x1c000
	s_add_i32 s23, s38, s51
	v_add_u32_e32 v0, s22, v160
	v_lshl_add_u64 v[148:149], v[148:149], 0, s[36:37]
	s_mov_b32 m0, s23
	ds_read_b128 v[208:211], v0
	ds_read_b128 v[214:217], v0 offset:1024
	ds_read_b128 v[218:221], v0 offset:2048
	ds_read_b128 v[222:225], v0 offset:3072
	global_load_lds_dwordx4 v[148:149], off
	s_add_i32 m0, s23, 0x2000
	v_lshl_add_u64 v[148:149], v[226:227], 0, s[36:37]
	global_load_lds_dwordx4 v[148:149], off
	s_barrier
	s_waitcnt lgkmcnt(0)
	s_setprio 1
	v_mfma_f32_16x16x32_bf16 v[118:121], v[208:211], v[176:179], v[118:121]
	v_mfma_f32_16x16x32_bf16 v[114:117], v[218:221], v[176:179], v[114:117]
	v_mfma_f32_16x16x32_bf16 v[102:105], v[208:211], v[184:187], v[102:105]
	v_mfma_f32_16x16x32_bf16 v[98:101], v[218:221], v[184:187], v[98:101]
	v_mfma_f32_16x16x32_bf16 v[86:89], v[208:211], v[192:195], v[86:89]
	v_mfma_f32_16x16x32_bf16 v[82:85], v[218:221], v[192:195], v[82:85]
	v_mfma_f32_16x16x32_bf16 v[70:73], v[208:211], v[200:203], v[70:73]
	v_mfma_f32_16x16x32_bf16 v[66:69], v[218:221], v[200:203], v[66:69]
	v_mfma_f32_16x16x32_bf16 v[118:121], v[214:217], v[180:183], v[118:121]
	v_mfma_f32_16x16x32_bf16 v[114:117], v[222:225], v[180:183], v[114:117]
	v_mfma_f32_16x16x32_bf16 v[102:105], v[214:217], v[188:191], v[102:105]
	v_mfma_f32_16x16x32_bf16 v[98:101], v[222:225], v[188:191], v[98:101]
	v_mfma_f32_16x16x32_bf16 v[86:89], v[214:217], v[196:199], v[86:89]
	v_mfma_f32_16x16x32_bf16 v[82:85], v[222:225], v[196:199], v[82:85]
	v_mfma_f32_16x16x32_bf16 v[70:73], v[214:217], v[204:207], v[70:73]
	v_mfma_f32_16x16x32_bf16 v[66:69], v[222:225], v[204:207], v[66:69]
	s_setprio 0
	s_mov_b32 m0, s61
	v_lshl_add_u64 v[148:149], v[228:229], 0, s[36:37]
	s_barrier
; #define PG8_STAGE(bufoff, gbase, voff) do { _Pragma("unroll") for (int _i = 0; _i < 2; ++_i) \
;         __builtin_amdgcn_global_load_lds((const unsigned*)((const char*)(gbase) + (voff)[_i]), (LAS unsigned*)(lds + (bufoff) + ldsw + _i * 8192), 16, 0, 0); } while (0)
; #define PG8_MMA(ai, bj, At, Bt) do { __builtin_amdgcn_s_setprio(1); _Pragma("unroll") for (int m = 0; m < 4; ++m) _Pragma("unroll") for (int n = 0; n < 2; ++n) _Pragma("unroll") for (int k = 0; k < 2; ++k) \
;         acc[ai][bj][m][n] = __builtin_amdgcn_mfma_f32_16x16x32_bf16(Bt[n][k], At[m][k], acc[ai][bj][m][n], 0, 0, 0); __builtin_amdgcn_s_setprio(0); } while (0)
; #define PG8_WAIT_V(n) asm volatile("s_waitcnt vmcnt(" #n ")" ::: "memory")
; #define PG8_WAIT_L(n) asm volatile("s_waitcnt lgkmcnt(" #n ")" ::: "memory")
; #define PG8_BAR __builtin_amdgcn_s_barrier()
; #define PG8_SCHED __builtin_amdgcn_sched_barrier(0)
;     __device__ __forceinline__ void operator()(const f32x4 (&acc)[2][2][4][2], const Unit& u, int wr, int wc, int fr, int fq) const {
;         const int row0 = u.pm * BM + wr * 64 + fr; const int col0 = u.pn * BM + wc * 32 + 8 * fq;
; #pragma unroll
;         for (int ai = 0; ai < 2; ++ai)
; #pragma unroll
;             for (int m = 0; m < 4; ++m) { const int row = row0 + ai * HALF + m * 16; int b, tok; if (row < MLAT) { b = row >> 13; tok = CTX + (row & (SEQ - 1)); } else { b = (row - MLAT) >> 8; tok = (row - MLAT) & (CTX - 1); }
; #pragma unroll
;                 for (int bj = 0; bj < 2; ++bj) { const int col = col0 + bj * HALF; bf16_t* dst;
;                     if (mode == 0) { const int h = col / 192, d = col - h * 192; dst = Q + ((size_t)(b * 4 + h) * LTOT + tok) * 192 + d; }
;                     else { const int h = col >> 8, d = col & 255; dst = d < 128 ? K + ((size_t)(b * 4 + h) * LTOT + tok) * 192 + d : V + ((size_t)(b * 4 + h) * LTOT + tok) * 128 + (d - 128); }
; template <class Epi, class Sched>
; __device__ __forceinline__ void gemm_phase(LAS unsigned char* lds, const Gemm g, const Sched& S, const Epi& E, const int tid) {
;     ...
;             PG8_BAR; PG8_WAIT_L(0); PG8_MMA(1, 0, At, B0); PG8_BAR; PG8_SCHED;
;             PG8_STAGE(PG8_SB(1, 1), b3 + hstep, voffB);
;             PG8_WAIT_V(6); PG8_BAR; PG8_MMA(1, 1, At, B1); PG8_BAR;
	ds_read_b128 v[176:179], v162 offset:49152
	ds_read_b128 v[180:183], v162 offset:50176
	ds_read_b128 v[184:187], v162 offset:51200
	ds_read_b128 v[188:191], v162 offset:52224
	ds_read_b128 v[192:195], v162 offset:53248
	ds_read_b128 v[196:199], v162 offset:54272
	ds_read_b128 v[200:203], v162 offset:55296
	ds_read_b128 v[204:207], v162 offset:56320
	global_load_lds_dwordx4 v[148:149], off
	s_mov_b32 m0, s62
	v_lshl_add_u64 v[148:149], v[230:231], 0, s[36:37]
	global_load_lds_dwordx4 v[148:149], off
	s_barrier
	s_waitcnt lgkmcnt(0)
	s_setprio 1
	v_mfma_f32_16x16x32_bf16 v[62:65], v[144:147], v[176:179], v[62:65]
	v_mfma_f32_16x16x32_bf16 v[58:61], v[168:171], v[176:179], v[58:61]
	v_mfma_f32_16x16x32_bf16 v[46:49], v[144:147], v[184:187], v[46:49]
	v_mfma_f32_16x16x32_bf16 v[42:45], v[168:171], v[184:187], v[42:45]
	v_mfma_f32_16x16x32_bf16 v[30:33], v[144:147], v[192:195], v[30:33]
	v_mfma_f32_16x16x32_bf16 v[26:29], v[168:171], v[192:195], v[26:29]
	v_mfma_f32_16x16x32_bf16 v[14:17], v[144:147], v[200:203], v[14:17]
	v_mfma_f32_16x16x32_bf16 v[10:13], v[168:171], v[200:203], v[10:13]
	v_mfma_f32_16x16x32_bf16 v[62:65], v[164:167], v[180:183], v[62:65]
	v_mfma_f32_16x16x32_bf16 v[58:61], v[172:175], v[180:183], v[58:61]
	v_mfma_f32_16x16x32_bf16 v[46:49], v[164:167], v[188:191], v[46:49]
	v_mfma_f32_16x16x32_bf16 v[42:45], v[172:175], v[188:191], v[42:45]
	v_mfma_f32_16x16x32_bf16 v[30:33], v[164:167], v[196:199], v[30:33]
	v_mfma_f32_16x16x32_bf16 v[26:29], v[172:175], v[196:199], v[26:29]
	v_mfma_f32_16x16x32_bf16 v[14:17], v[164:167], v[204:207], v[14:17]
	v_mfma_f32_16x16x32_bf16 v[10:13], v[172:175], v[204:207], v[10:13]
	s_setprio 0
	s_barrier
	s_add_i32 s22, s22, s51
	s_mov_b32 m0, s22
	v_lshl_add_u64 v[144:145], v[244:245], 0, s[36:37]
	global_load_lds_dwordx4 v[144:145], off
	s_add_i32 m0, s22, 0x2000
	v_lshl_add_u64 v[144:145], v[246:247], 0, s[36:37]
	global_load_lds_dwordx4 v[144:145], off
	s_waitcnt vmcnt(6)
	s_barrier
	s_setprio 1
	v_mfma_f32_16x16x32_bf16 v[54:57], v[208:211], v[176:179], v[54:57]
	v_mfma_f32_16x16x32_bf16 v[50:53], v[218:221], v[176:179], v[50:53]
	v_mfma_f32_16x16x32_bf16 v[38:41], v[208:211], v[184:187], v[38:41]
	v_mfma_f32_16x16x32_bf16 v[34:37], v[218:221], v[184:187], v[34:37]
	v_mfma_f32_16x16x32_bf16 v[22:25], v[208:211], v[192:195], v[22:25]
	v_mfma_f32_16x16x32_bf16 v[18:21], v[218:221], v[192:195], v[18:21]
	v_mfma_f32_16x16x32_bf16 v[6:9], v[208:211], v[200:203], v[6:9]
	v_mfma_f32_16x16x32_bf16 v[2:5], v[218:221], v[200:203], v[2:5]
	v_mfma_f32_16x16x32_bf16 v[54:57], v[214:217], v[180:183], v[54:57]
	v_mfma_f32_16x16x32_bf16 v[50:53], v[222:225], v[180:183], v[50:53]
	v_mfma_f32_16x16x32_bf16 v[38:41], v[214:217], v[188:191], v[38:41]
	v_mfma_f32_16x16x32_bf16 v[34:37], v[222:225], v[188:191], v[34:37]
	v_mfma_f32_16x16x32_bf16 v[22:25], v[214:217], v[196:199], v[22:25]
	v_mfma_f32_16x16x32_bf16 v[18:21], v[222:225], v[196:199], v[18:21]
	v_mfma_f32_16x16x32_bf16 v[6:9], v[214:217], v[204:207], v[6:9]
	v_mfma_f32_16x16x32_bf16 v[2:5], v[222:225], v[204:207], v[2:5]
	s_setprio 0
	s_add_u32 s2, s2, 0x100
	s_addc_u32 s3, s3, 0
	s_add_u32 s25, s25, 0x100
	s_addc_u32 s29, s29, 0
	s_cmp_ge_i32 s74, s63
	s_mov_b32 s22, s74
	s_barrier
	s_cbranch_scc0 .LBB0_538
	s_lshl_b32 s24, s28, 8
	s_add_i32 s24, s24, s64
	s_add_i32 s2, s24, 0xffffc000
	v_mov_b32_e32 v0, 0x1fcf
	v_or_b32_e32 v163, s24, v156
	s_lshr_b32 s25, s2, 8
	v_bitop3_b32 v0, s24, v0, v156 bitop3:0xc8
	v_mov_b32_e32 v144, 0xcf
	s_movk_i32 s2, 0x4000
	s_ashr_i32 s28, s24, 13
	v_add_u32_e32 v0, 0x100, v0
	v_bitop3_b32 v144, s24, v144, v156 bitop3:0xc8
	v_cmp_gt_i32_e32 vcc, s2, v163
	v_mov_b32_e32 v145, s28
	v_lshl_or_b32 v142, s60, 8, v161
	v_cndmask_b32_e32 v0, v144, v0, vcc
	v_mov_b32_e32 v144, s25
	v_cndmask_b32_e32 v144, v144, v145, vcc
	v_lshlrev_b32_e32 v166, 2, v144
	v_add_u32_e32 v144, s60, v166
	v_mad_i64_i32 v[146:147], s[2:3], v144, s33, v[0:1]
	v_and_b32_e32 v144, 0x78, v142
	s_mov_b64 s[2:3], -1
	s_and_b64 vcc, exec, s[14:15]
	v_lshlrev_b32_e32 v144, 1, v144
	s_cbranch_vccz .LBB0_541
	v_mov_b64_e32 v[148:149], s[10:11]
	v_mad_u64_u32 v[148:149], s[2:3], v146, s27, v[148:149]
	v_mov_b32_e32 v164, v149
	v_mad_u64_u32 v[164:165], s[2:3], v147, s27, v[164:165]
	v_mov_b32_e32 v149, v164
	v_mov_b32_e32 v145, v1
	v_lshl_add_u64 v[148:149], v[148:149], 0, v[144:145]
	s_mov_b64 s[2:3], 0

; #define PG8_STAGE(bufoff, gbase, voff) do { _Pragma("unroll") for (int _i = 0; _i < 2; ++_i) \
;         __builtin_amdgcn_global_load_lds((const unsigned*)((const char*)(gbase) + (voff)[_i]), (LAS unsigned*)(lds + (bufoff) + ldsw + _i * 8192), 16, 0, 0); } while (0)
; #define PG8_LDA(dst, b, h) do { _Pragma("unroll") for (int m = 0; m < 4; ++m) _Pragma("unroll") for (int k = 0; k < 2; ++k) dst[m][k] = *(const LAS bf16x8*)(lds + PG8_SA(b, h) + aoff + m * 2048 + k * 1024); } while (0)
; #define PG8_LDB(dst, b, h) do { _Pragma("unroll") for (int n = 0; n < 2; ++n) _Pragma("unroll") for (int k = 0; k < 2; ++k) dst[n][k] = *(const LAS bf16x8*)(lds + PG8_SB(b, h) + boff + n * 2048 + k * 1024); } while (0)
; #define PG8_MMA(ai, bj, At, Bt) do { __builtin_amdgcn_s_setprio(1); _Pragma("unroll") for (int m = 0; m < 4; ++m) _Pragma("unroll") for (int n = 0; n < 2; ++n) _Pragma("unroll") for (int k = 0; k < 2; ++k) \
;         acc[ai][bj][m][n] = __builtin_amdgcn_mfma_f32_16x16x32_bf16(Bt[n][k], At[m][k], acc[ai][bj][m][n], 0, 0, 0); __builtin_amdgcn_s_setprio(0); } while (0)
; #define PG8_WAIT_L(n) asm volatile("s_waitcnt lgkmcnt(" #n ")" ::: "memory")
; #define PG8_BAR __builtin_amdgcn_s_barrier()
; #define PG8_SCHED __builtin_amdgcn_sched_barrier(0)
; template <class Epi, class Sched>
; __device__ __forceinline__ void gemm_phase(LAS unsigned char* lds, const Gemm g, const Sched& S, const Epi& E, const int tid) {
;     ...
;             const bool last = (t == nt - 2);
;             const char* a1 = cA + (size_t)(t + 1) * kstep;
;             const char* a2 = last ? nA : cA + (size_t)(t + 2) * kstep; const char* b2 = last ? nB : cB + (size_t)(t + 2) * kstep;
;             const char* a3 = a2 + kstep; const char* b3 = b2 + kstep;
;             if (last && has_next) S.a_ready(nxt);
;             if constexpr (Epi::PRELOAD) { if (last) E.preload(cur, lds, wid, lane); }
;             PG8_LDB(B0, 0, 0); PG8_SCHED; PG8_LDA(At, 0, 0); PG8_STAGE(PG8_SA(1, 1), a1 + hstep, voffA);
;             PG8_WAIT_L(8); PG8_BAR; PG8_WAIT_L(0); PG8_MMA(0, 0, At, B0); PG8_BAR; PG8_SCHED;
;             PG8_LDB(B1, 0, 1); PG8_STAGE(PG8_SB(0, 0), b2, voffB);
;             PG8_BAR; PG8_WAIT_L(0); PG8_MMA(0, 1, At, B1); PG8_BAR;
;             PG8_LDA(At, 0, 1); PG8_STAGE(PG8_SA(0, 0), a2, voffA);
;             PG8_BAR; PG8_WAIT_L(0); PG8_MMA(1, 0, At, B0); PG8_BAR; PG8_SCHED;
.LBB0_1208:
	s_add_u32 s20, s18, 0xe61bc080
	s_addc_u32 s21, s19, -1
	s_cmp_lg_u32 s45, 28
	s_cselect_b32 s20, s20, 0
	s_cselect_b32 s21, s21, 0
	s_add_u32 s22, s4, s20
	s_addc_u32 s23, s5, s21
	s_add_i32 s46, 0, 0x10000
	v_add_u32_e32 v154, s46, v140
	ds_read_b128 v[142:145], v154
	ds_read_b128 v[146:149], v154 offset:1024
	ds_read_b128 v[150:153], v154 offset:2048
	ds_read_b128 v[154:157], v154 offset:3072
	s_add_u32 s20, s0, s20
	s_addc_u32 s21, s1, s21
	v_lshl_add_u64 v[190:191], v[136:137], 0, s[18:19]
	s_add_i32 m0, s25, 0xc000
	ds_read_b128 v[158:161], v141
	ds_read_b128 v[162:165], v141 offset:1024
	ds_read_b128 v[166:169], v141 offset:2048
	ds_read_b128 v[170:173], v141 offset:3072
	ds_read_b128 v[174:177], v141 offset:4096
	ds_read_b128 v[178:181], v141 offset:5120
	ds_read_b128 v[182:185], v141 offset:6144
	ds_read_b128 v[186:189], v141 offset:7168
	global_load_lds_dwordx4 v[190:191], off
	s_add_i32 m0, s25, 0xe000
	v_lshl_add_u64 v[190:191], v[138:139], 0, s[18:19]
	global_load_lds_dwordx4 v[190:191], off
	s_waitcnt lgkmcnt(8)
	s_barrier
	s_waitcnt lgkmcnt(0)
	s_setprio 1
	v_mfma_f32_16x16x32_bf16 v[126:129], v[142:145], v[158:161], v[126:129]
	v_mfma_f32_16x16x32_bf16 v[122:125], v[150:153], v[158:161], v[122:125]
	v_mfma_f32_16x16x32_bf16 v[118:121], v[142:145], v[166:169], v[118:121]
	v_mfma_f32_16x16x32_bf16 v[110:113], v[150:153], v[166:169], v[110:113]
	v_mfma_f32_16x16x32_bf16 v[98:101], v[142:145], v[174:177], v[98:101]
	v_mfma_f32_16x16x32_bf16 v[90:93], v[150:153], v[174:177], v[90:93]
	v_mfma_f32_16x16x32_bf16 v[82:85], v[142:145], v[182:185], v[82:85]
	v_mfma_f32_16x16x32_bf16 v[74:77], v[150:153], v[182:185], v[74:77]
	v_mfma_f32_16x16x32_bf16 v[126:129], v[146:149], v[162:165], v[126:129]
	v_mfma_f32_16x16x32_bf16 v[122:125], v[154:157], v[162:165], v[122:125]
	v_mfma_f32_16x16x32_bf16 v[118:121], v[146:149], v[170:173], v[118:121]
	v_mfma_f32_16x16x32_bf16 v[110:113], v[154:157], v[170:173], v[110:113]
	v_mfma_f32_16x16x32_bf16 v[98:101], v[146:149], v[178:181], v[98:101]
	v_mfma_f32_16x16x32_bf16 v[90:93], v[154:157], v[178:181], v[90:93]
	v_mfma_f32_16x16x32_bf16 v[82:85], v[146:149], v[186:189], v[82:85]
	v_mfma_f32_16x16x32_bf16 v[74:77], v[154:157], v[186:189], v[74:77]
	s_setprio 0
	s_barrier
	s_add_i32 s48, 0, 0x14000
	s_add_i32 s46, s46, s24
	v_add_u32_e32 v202, s48, v140
	v_lshl_add_u64 v[206:207], s[20:21], 0, v[0:1]
	s_mov_b32 m0, s46
	ds_read_b128 v[190:193], v202
	ds_read_b128 v[194:197], v202 offset:1024
	ds_read_b128 v[198:201], v202 offset:2048
	ds_read_b128 v[202:205], v202 offset:3072
	global_load_lds_dwordx4 v[206:207], off
	s_add_i32 m0, s46, 0x2000
	v_lshl_add_u64 v[208:209], s[20:21], 0, v[134:135]
	global_load_lds_dwordx4 v[208:209], off
	s_barrier
	s_waitcnt lgkmcnt(0)
	s_setprio 1
	v_mfma_f32_16x16x32_bf16 v[114:117], v[190:193], v[158:161], v[114:117]
	v_mfma_f32_16x16x32_bf16 v[106:109], v[198:201], v[158:161], v[106:109]
	v_mfma_f32_16x16x32_bf16 v[102:105], v[190:193], v[166:169], v[102:105]
	v_mfma_f32_16x16x32_bf16 v[94:97], v[198:201], v[166:169], v[94:97]
	v_mfma_f32_16x16x32_bf16 v[86:89], v[190:193], v[174:177], v[86:89]
	v_mfma_f32_16x16x32_bf16 v[78:81], v[198:201], v[174:177], v[78:81]
	v_mfma_f32_16x16x32_bf16 v[70:73], v[190:193], v[182:185], v[70:73]
	v_mfma_f32_16x16x32_bf16 v[66:69], v[198:201], v[182:185], v[66:69]
	v_mfma_f32_16x16x32_bf16 v[114:117], v[194:197], v[162:165], v[114:117]
	v_mfma_f32_16x16x32_bf16 v[106:109], v[202:205], v[162:165], v[106:109]
	v_mfma_f32_16x16x32_bf16 v[102:105], v[194:197], v[170:173], v[102:105]
	v_mfma_f32_16x16x32_bf16 v[94:97], v[202:205], v[170:173], v[94:97]
	v_mfma_f32_16x16x32_bf16 v[86:89], v[194:197], v[178:181], v[86:89]
	v_mfma_f32_16x16x32_bf16 v[78:81], v[202:205], v[178:181], v[78:81]
	v_mfma_f32_16x16x32_bf16 v[70:73], v[194:197], v[186:189], v[70:73]
	v_mfma_f32_16x16x32_bf16 v[66:69], v[202:205], v[186:189], v[66:69]
	s_setprio 0
	s_mov_b32 m0, s25
	v_lshl_add_u64 v[210:211], s[22:23], 0, v[130:131]
	s_barrier
	ds_read_b128 v[158:161], v141 offset:16384
	ds_read_b128 v[162:165], v141 offset:17408
	ds_read_b128 v[166:169], v141 offset:18432
	ds_read_b128 v[170:173], v141 offset:19456
	ds_read_b128 v[174:177], v141 offset:20480
	ds_read_b128 v[178:181], v141 offset:21504
	ds_read_b128 v[182:185], v141 offset:22528
	ds_read_b128 v[186:189], v141 offset:23552
	global_load_lds_dwordx4 v[210:211], off
	s_mov_b32 m0, s28
	v_lshl_add_u64 v[214:215], s[22:23], 0, v[132:133]
	global_load_lds_dwordx4 v[214:215], off
	s_barrier
	s_waitcnt lgkmcnt(0)
	s_setprio 1
	v_mfma_f32_16x16x32_bf16 v[62:65], v[142:145], v[158:161], v[62:65]
	v_mfma_f32_16x16x32_bf16 v[58:61], v[150:153], v[158:161], v[58:61]
	v_mfma_f32_16x16x32_bf16 v[50:53], v[142:145], v[166:169], v[50:53]
	v_mfma_f32_16x16x32_bf16 v[42:45], v[150:153], v[166:169], v[42:45]
	v_mfma_f32_16x16x32_bf16 v[34:37], v[142:145], v[174:177], v[34:37]
	v_mfma_f32_16x16x32_bf16 v[26:29], v[150:153], v[174:177], v[26:29]
	v_mfma_f32_16x16x32_bf16 v[18:21], v[142:145], v[182:185], v[18:21]
	v_mfma_f32_16x16x32_bf16 v[10:13], v[150:153], v[182:185], v[10:13]
	v_mfma_f32_16x16x32_bf16 v[62:65], v[146:149], v[162:165], v[62:65]
	v_mfma_f32_16x16x32_bf16 v[58:61], v[154:157], v[162:165], v[58:61]
	v_mfma_f32_16x16x32_bf16 v[50:53], v[146:149], v[170:173], v[50:53]
	v_mfma_f32_16x16x32_bf16 v[42:45], v[154:157], v[170:173], v[42:45]
	v_mfma_f32_16x16x32_bf16 v[34:37], v[146:149], v[178:181], v[34:37]
	v_mfma_f32_16x16x32_bf16 v[26:29], v[154:157], v[178:181], v[26:29]
	v_mfma_f32_16x16x32_bf16 v[18:21], v[146:149], v[186:189], v[18:21]
	v_mfma_f32_16x16x32_bf16 v[10:13], v[154:157], v[186:189], v[10:13]
	s_setprio 0
	s_barrier
; #define PG8_STAGE(bufoff, gbase, voff) do { _Pragma("unroll") for (int _i = 0; _i < 2; ++_i) \
;         __builtin_amdgcn_global_load_lds((const unsigned*)((const char*)(gbase) + (voff)[_i]), (LAS unsigned*)(lds + (bufoff) + ldsw + _i * 8192), 16, 0, 0); } while (0)
; #define PG8_LDA(dst, b, h) do { _Pragma("unroll") for (int m = 0; m < 4; ++m) _Pragma("unroll") for (int k = 0; k < 2; ++k) dst[m][k] = *(const LAS bf16x8*)(lds + PG8_SA(b, h) + aoff + m * 2048 + k * 1024); } while (0)
; #define PG8_LDB(dst, b, h) do { _Pragma("unroll") for (int n = 0; n < 2; ++n) _Pragma("unroll") for (int k = 0; k < 2; ++k) dst[n][k] = *(const LAS bf16x8*)(lds + PG8_SB(b, h) + boff + n * 2048 + k * 1024); } while (0)
; #define PG8_MMA(ai, bj, At, Bt) do { __builtin_amdgcn_s_setprio(1); _Pragma("unroll") for (int m = 0; m < 4; ++m) _Pragma("unroll") for (int n = 0; n < 2; ++n) _Pragma("unroll") for (int k = 0; k < 2; ++k) \
;         acc[ai][bj][m][n] = __builtin_amdgcn_mfma_f32_16x16x32_bf16(Bt[n][k], At[m][k], acc[ai][bj][m][n], 0, 0, 0); __builtin_amdgcn_s_setprio(0); } while (0)
; #define PG8_WAIT_V(n) asm volatile("s_waitcnt vmcnt(" #n ")" ::: "memory")
; #define PG8_WAIT_L(n) asm volatile("s_waitcnt lgkmcnt(" #n ")" ::: "memory")
; #define PG8_BAR __builtin_amdgcn_s_barrier()
; #define PG8_SCHED __builtin_amdgcn_sched_barrier(0)
; template <class Epi, class Sched>
; __device__ __forceinline__ void gemm_phase(LAS unsigned char* lds, const Gemm g, const Sched& S, const Epi& E, const int tid) {
;     ...
;             PG8_STAGE(PG8_SB(0, 1), b2 + hstep, voffB);
;             PG8_WAIT_V(6); PG8_BAR; PG8_MMA(1, 1, At, B1); PG8_BAR;
;             PG8_LDB(B0, 1, 0); PG8_SCHED; PG8_LDA(At, 1, 0); PG8_STAGE(PG8_SA(0, 1), a2 + hstep, voffA);
;             PG8_WAIT_L(8); PG8_BAR; PG8_WAIT_L(0); PG8_MMA(0, 0, At, B0); PG8_BAR; PG8_SCHED;
;             PG8_LDB(B1, 1, 1); PG8_STAGE(PG8_SB(1, 0), b3, voffB);
;             PG8_BAR; PG8_WAIT_L(0); PG8_MMA(0, 1, At, B1); PG8_BAR;
;             PG8_LDA(At, 1, 1); PG8_STAGE(PG8_SA(1, 0), a3, voffA);
	s_add_u32 s46, s20, 0x80000
	s_addc_u32 s47, s21, 0
	s_add_i32 s48, s48, s24
	s_mov_b32 m0, s48
	s_nop 0
	global_load_lds_dwordx4 v0, s[46:47]
	s_add_i32 m0, s48, 0x2000
	s_nop 0
	global_load_lds_dwordx4 v134, s[46:47]
	s_waitcnt vmcnt(6)
	s_barrier
	s_setprio 1
	v_mfma_f32_16x16x32_bf16 v[54:57], v[190:193], v[158:161], v[54:57]
	v_mfma_f32_16x16x32_bf16 v[46:49], v[198:201], v[158:161], v[46:49]
	v_mfma_f32_16x16x32_bf16 v[38:41], v[190:193], v[166:169], v[38:41]
	v_mfma_f32_16x16x32_bf16 v[30:33], v[198:201], v[166:169], v[30:33]
	v_mfma_f32_16x16x32_bf16 v[22:25], v[190:193], v[174:177], v[22:25]
	v_mfma_f32_16x16x32_bf16 v[14:17], v[198:201], v[174:177], v[14:17]
	v_mfma_f32_16x16x32_bf16 v[6:9], v[190:193], v[182:185], v[6:9]
	v_mfma_f32_16x16x32_bf16 v[2:5], v[198:201], v[182:185], v[2:5]
	v_mfma_f32_16x16x32_bf16 v[54:57], v[194:197], v[162:165], v[54:57]
	v_mfma_f32_16x16x32_bf16 v[46:49], v[202:205], v[162:165], v[46:49]
	v_mfma_f32_16x16x32_bf16 v[38:41], v[194:197], v[170:173], v[38:41]
	v_mfma_f32_16x16x32_bf16 v[30:33], v[202:205], v[170:173], v[30:33]
	v_mfma_f32_16x16x32_bf16 v[22:25], v[194:197], v[178:181], v[22:25]
	v_mfma_f32_16x16x32_bf16 v[14:17], v[202:205], v[178:181], v[14:17]
	v_mfma_f32_16x16x32_bf16 v[6:9], v[194:197], v[186:189], v[6:9]
	v_mfma_f32_16x16x32_bf16 v[2:5], v[202:205], v[186:189], v[2:5]
	s_setprio 0
	s_add_i32 s46, 0, 0x18000
	v_add_u32_e32 v154, s46, v140
	s_barrier
	ds_read_b128 v[142:145], v154
	ds_read_b128 v[146:149], v154 offset:1024
	ds_read_b128 v[150:153], v154 offset:2048
	ds_read_b128 v[154:157], v154 offset:3072
	s_add_u32 s22, s22, 0x80000
	s_addc_u32 s23, s23, 0
	s_mov_b32 m0, s29
	ds_read_b128 v[158:161], v141 offset:32768
	ds_read_b128 v[162:165], v141 offset:33792
	ds_read_b128 v[166:169], v141 offset:34816
	ds_read_b128 v[170:173], v141 offset:35840
	ds_read_b128 v[174:177], v141 offset:36864
	ds_read_b128 v[178:181], v141 offset:37888
	ds_read_b128 v[182:185], v141 offset:38912
	ds_read_b128 v[186:189], v141 offset:39936
	global_load_lds_dwordx4 v130, s[22:23]
	s_mov_b32 m0, s42
	s_nop 0
	global_load_lds_dwordx4 v132, s[22:23]
	s_waitcnt lgkmcnt(8)
	s_barrier
	s_waitcnt lgkmcnt(0)
	s_setprio 1
	v_mfma_f32_16x16x32_bf16 v[126:129], v[142:145], v[158:161], v[126:129]
	v_mfma_f32_16x16x32_bf16 v[122:125], v[150:153], v[158:161], v[122:125]
	v_mfma_f32_16x16x32_bf16 v[118:121], v[142:145], v[166:169], v[118:121]
	v_mfma_f32_16x16x32_bf16 v[110:113], v[150:153], v[166:169], v[110:113]
	v_mfma_f32_16x16x32_bf16 v[98:101], v[142:145], v[174:177], v[98:101]
	v_mfma_f32_16x16x32_bf16 v[90:93], v[150:153], v[174:177], v[90:93]
	v_mfma_f32_16x16x32_bf16 v[82:85], v[142:145], v[182:185], v[82:85]
	v_mfma_f32_16x16x32_bf16 v[74:77], v[150:153], v[182:185], v[74:77]
	v_mfma_f32_16x16x32_bf16 v[126:129], v[146:149], v[162:165], v[126:129]
	v_mfma_f32_16x16x32_bf16 v[122:125], v[154:157], v[162:165], v[122:125]
	v_mfma_f32_16x16x32_bf16 v[118:121], v[146:149], v[170:173], v[118:121]
	v_mfma_f32_16x16x32_bf16 v[110:113], v[154:157], v[170:173], v[110:113]
	v_mfma_f32_16x16x32_bf16 v[98:101], v[146:149], v[178:181], v[98:101]
	v_mfma_f32_16x16x32_bf16 v[90:93], v[154:157], v[178:181], v[90:93]
	v_mfma_f32_16x16x32_bf16 v[82:85], v[146:149], v[186:189], v[82:85]
	v_mfma_f32_16x16x32_bf16 v[74:77], v[154:157], v[186:189], v[74:77]
	s_setprio 0
	s_barrier
	s_add_i32 s22, 0, 0x1c000
	s_add_i32 s23, s46, s24
	v_add_u32_e32 v202, s22, v140
	v_lshl_add_u64 v[206:207], v[206:207], 0, s[36:37]
	s_mov_b32 m0, s23
	ds_read_b128 v[190:193], v202
	ds_read_b128 v[194:197], v202 offset:1024
	ds_read_b128 v[198:201], v202 offset:2048
	ds_read_b128 v[202:205], v202 offset:3072
	global_load_lds_dwordx4 v[206:207], off
	s_add_i32 m0, s23, 0x2000
	v_lshl_add_u64 v[206:207], v[208:209], 0, s[36:37]
	global_load_lds_dwordx4 v[206:207], off
	s_barrier
; #define PG8_STAGE(bufoff, gbase, voff) do { _Pragma("unroll") for (int _i = 0; _i < 2; ++_i) \
;         __builtin_amdgcn_global_load_lds((const unsigned*)((const char*)(gbase) + (voff)[_i]), (LAS unsigned*)(lds + (bufoff) + ldsw + _i * 8192), 16, 0, 0); } while (0)
; #define PG8_MMA(ai, bj, At, Bt) do { __builtin_amdgcn_s_setprio(1); _Pragma("unroll") for (int m = 0; m < 4; ++m) _Pragma("unroll") for (int n = 0; n < 2; ++n) _Pragma("unroll") for (int k = 0; k < 2; ++k) \
;         acc[ai][bj][m][n] = __builtin_amdgcn_mfma_f32_16x16x32_bf16(Bt[n][k], At[m][k], acc[ai][bj][m][n], 0, 0, 0); __builtin_amdgcn_s_setprio(0); } while (0)
; #define PG8_WAIT_V(n) asm volatile("s_waitcnt vmcnt(" #n ")" ::: "memory")
; #define PG8_WAIT_L(n) asm volatile("s_waitcnt lgkmcnt(" #n ")" ::: "memory")
; #define PG8_BAR __builtin_amdgcn_s_barrier()
; #define PG8_SCHED __builtin_amdgcn_sched_barrier(0)
; template <class Epi, class Sched>
; __device__ __forceinline__ void gemm_phase(LAS unsigned char* lds, const Gemm g, const Sched& S, const Epi& E, const int tid) {
;     ...
;             PG8_BAR; PG8_WAIT_L(0); PG8_MMA(1, 0, At, B0); PG8_BAR; PG8_SCHED;
;             PG8_STAGE(PG8_SB(1, 1), b3 + hstep, voffB);
;             PG8_WAIT_V(6); PG8_BAR; PG8_MMA(1, 1, At, B1); PG8_BAR;
;     ...
;     PG8_WAIT_V(0);
;     if (wr == 0) PG8_BAR;
	s_waitcnt lgkmcnt(0)
	s_setprio 1
	v_mfma_f32_16x16x32_bf16 v[114:117], v[190:193], v[158:161], v[114:117]
	v_mfma_f32_16x16x32_bf16 v[106:109], v[198:201], v[158:161], v[106:109]
	v_mfma_f32_16x16x32_bf16 v[102:105], v[190:193], v[166:169], v[102:105]
	v_mfma_f32_16x16x32_bf16 v[94:97], v[198:201], v[166:169], v[94:97]
	v_mfma_f32_16x16x32_bf16 v[86:89], v[190:193], v[174:177], v[86:89]
	v_mfma_f32_16x16x32_bf16 v[78:81], v[198:201], v[174:177], v[78:81]
	v_mfma_f32_16x16x32_bf16 v[70:73], v[190:193], v[182:185], v[70:73]
	v_mfma_f32_16x16x32_bf16 v[66:69], v[198:201], v[182:185], v[66:69]
	v_mfma_f32_16x16x32_bf16 v[114:117], v[194:197], v[162:165], v[114:117]
	v_mfma_f32_16x16x32_bf16 v[106:109], v[202:205], v[162:165], v[106:109]
	v_mfma_f32_16x16x32_bf16 v[102:105], v[194:197], v[170:173], v[102:105]
	v_mfma_f32_16x16x32_bf16 v[94:97], v[202:205], v[170:173], v[94:97]
	v_mfma_f32_16x16x32_bf16 v[86:89], v[194:197], v[178:181], v[86:89]
	v_mfma_f32_16x16x32_bf16 v[78:81], v[202:205], v[178:181], v[78:81]
	v_mfma_f32_16x16x32_bf16 v[70:73], v[194:197], v[186:189], v[70:73]
	v_mfma_f32_16x16x32_bf16 v[66:69], v[202:205], v[186:189], v[66:69]
	s_setprio 0
	s_mov_b32 m0, s43
	v_lshl_add_u64 v[206:207], v[210:211], 0, s[36:37]
	s_barrier
	ds_read_b128 v[158:161], v141 offset:49152
	ds_read_b128 v[162:165], v141 offset:50176
	ds_read_b128 v[166:169], v141 offset:51200
	ds_read_b128 v[170:173], v141 offset:52224
	ds_read_b128 v[174:177], v141 offset:53248
	ds_read_b128 v[178:181], v141 offset:54272
	ds_read_b128 v[182:185], v141 offset:55296
	ds_read_b128 v[186:189], v141 offset:56320
	global_load_lds_dwordx4 v[206:207], off
	s_mov_b32 m0, s44
	v_lshl_add_u64 v[206:207], v[214:215], 0, s[36:37]
	global_load_lds_dwordx4 v[206:207], off
	s_barrier
	s_waitcnt lgkmcnt(0)
	s_setprio 1
	v_mfma_f32_16x16x32_bf16 v[62:65], v[142:145], v[158:161], v[62:65]
	v_mfma_f32_16x16x32_bf16 v[58:61], v[150:153], v[158:161], v[58:61]
	v_mfma_f32_16x16x32_bf16 v[50:53], v[142:145], v[166:169], v[50:53]
	v_mfma_f32_16x16x32_bf16 v[42:45], v[150:153], v[166:169], v[42:45]
	v_mfma_f32_16x16x32_bf16 v[34:37], v[142:145], v[174:177], v[34:37]
	v_mfma_f32_16x16x32_bf16 v[26:29], v[150:153], v[174:177], v[26:29]
	v_mfma_f32_16x16x32_bf16 v[18:21], v[142:145], v[182:185], v[18:21]
	v_mfma_f32_16x16x32_bf16 v[10:13], v[150:153], v[182:185], v[10:13]
	v_mfma_f32_16x16x32_bf16 v[62:65], v[146:149], v[162:165], v[62:65]
	v_mfma_f32_16x16x32_bf16 v[58:61], v[154:157], v[162:165], v[58:61]
	v_mfma_f32_16x16x32_bf16 v[50:53], v[146:149], v[170:173], v[50:53]
	v_mfma_f32_16x16x32_bf16 v[42:45], v[154:157], v[170:173], v[42:45]
	v_mfma_f32_16x16x32_bf16 v[34:37], v[146:149], v[178:181], v[34:37]
	v_mfma_f32_16x16x32_bf16 v[26:29], v[154:157], v[178:181], v[26:29]
	v_mfma_f32_16x16x32_bf16 v[18:21], v[146:149], v[186:189], v[18:21]
	v_mfma_f32_16x16x32_bf16 v[10:13], v[154:157], v[186:189], v[10:13]
	s_setprio 0
	s_barrier
	s_add_u32 s20, s20, 0x80080
	s_addc_u32 s21, s21, 0
	s_add_i32 s22, s22, s24
	s_mov_b32 m0, s22
	s_nop 0
	global_load_lds_dwordx4 v0, s[20:21]
	s_add_i32 m0, s22, 0x2000
	s_nop 0
	global_load_lds_dwordx4 v134, s[20:21]
	s_waitcnt vmcnt(6)
	s_barrier
	s_setprio 1
	v_mfma_f32_16x16x32_bf16 v[54:57], v[190:193], v[158:161], v[54:57]
	v_mfma_f32_16x16x32_bf16 v[46:49], v[198:201], v[158:161], v[46:49]
	v_mfma_f32_16x16x32_bf16 v[38:41], v[190:193], v[166:169], v[38:41]
	v_mfma_f32_16x16x32_bf16 v[30:33], v[198:201], v[166:169], v[30:33]
	v_mfma_f32_16x16x32_bf16 v[22:25], v[190:193], v[174:177], v[22:25]
	v_mfma_f32_16x16x32_bf16 v[14:17], v[198:201], v[174:177], v[14:17]
	v_mfma_f32_16x16x32_bf16 v[6:9], v[190:193], v[182:185], v[6:9]
	v_mfma_f32_16x16x32_bf16 v[2:5], v[198:201], v[182:185], v[2:5]
	v_mfma_f32_16x16x32_bf16 v[54:57], v[194:197], v[162:165], v[54:57]
	v_mfma_f32_16x16x32_bf16 v[46:49], v[202:205], v[162:165], v[46:49]
	v_mfma_f32_16x16x32_bf16 v[38:41], v[194:197], v[170:173], v[38:41]
	v_mfma_f32_16x16x32_bf16 v[30:33], v[202:205], v[170:173], v[30:33]
	v_mfma_f32_16x16x32_bf16 v[22:25], v[194:197], v[178:181], v[22:25]
	v_mfma_f32_16x16x32_bf16 v[14:17], v[202:205], v[178:181], v[14:17]
	v_mfma_f32_16x16x32_bf16 v[6:9], v[194:197], v[186:189], v[6:9]
	v_mfma_f32_16x16x32_bf16 v[2:5], v[202:205], v[186:189], v[2:5]
	s_setprio 0
	s_add_i32 s45, s45, 2
	s_add_u32 s18, s18, 0x100
	s_addc_u32 s19, s19, 0
	s_cmp_lt_u32 s45, 30
	s_barrier
	s_cbranch_scc1 .LBB0_1208
	s_waitcnt vmcnt(0)
	s_cmpk_gt_u32 s38, 0xff
	s_cbranch_scc1 .LBB0_1211
	s_barrier

; #define PG8_STAGE(bufoff, gbase, voff) do { _Pragma("unroll") for (int _i = 0; _i < 2; ++_i) \
;         __builtin_amdgcn_global_load_lds((const unsigned*)((const char*)(gbase) + (voff)[_i]), (LAS unsigned*)(lds + (bufoff) + ldsw + _i * 8192), 16, 0, 0); } while (0)
; #define PG8_LDA(dst, b, h) do { _Pragma("unroll") for (int m = 0; m < 4; ++m) _Pragma("unroll") for (int k = 0; k < 2; ++k) dst[m][k] = *(const LAS bf16x8*)(lds + PG8_SA(b, h) + aoff + m * 2048 + k * 1024); } while (0)
; #define PG8_LDB(dst, b, h) do { _Pragma("unroll") for (int n = 0; n < 2; ++n) _Pragma("unroll") for (int k = 0; k < 2; ++k) dst[n][k] = *(const LAS bf16x8*)(lds + PG8_SB(b, h) + boff + n * 2048 + k * 1024); } while (0)
; #define PG8_WAIT_L(n) asm volatile("s_waitcnt lgkmcnt(" #n ")" ::: "memory")
; #define PG8_BAR __builtin_amdgcn_s_barrier()
; #define PG8_SCHED __builtin_amdgcn_sched_barrier(0)
; template <class Epi, class Sched>
; __device__ __forceinline__ void gemm_phase(LAS unsigned char* lds, const Gemm g, const Sched& S, const Epi& E, const int tid) {
;     ...
;         const char* nA = has_next ? (const char*)g.A + (size_t)nxt.pm * tstep + (size_t)nxt.ks * nxt.nt * kstep : cA; const char* nB = has_next ? (const char*)g.Bt + (size_t)nxt.pn * tstep + (size_t)nxt.ks * nxt.nt * kstep : cB;
;         const int nt = cur.nt;
;         for (int t = 0; t < nt; t += 2) {
;             const bool last = (t == nt - 2);
;             const char* a1 = cA + (size_t)(t + 1) * kstep;
;             const char* a2 = last ? nA : cA + (size_t)(t + 2) * kstep; const char* b2 = last ? nB : cB + (size_t)(t + 2) * kstep;
;             const char* a3 = a2 + kstep; const char* b3 = b2 + kstep;
;             if (last && has_next) S.a_ready(nxt);
;             if constexpr (Epi::PRELOAD) { if (last) E.preload(cur, lds, wid, lane); }
;             PG8_LDB(B0, 0, 0); PG8_SCHED; PG8_LDA(At, 0, 0); PG8_STAGE(PG8_SA(1, 1), a1 + hstep, voffA);
;             PG8_WAIT_L(8); PG8_BAR; PG8_WAIT_L(0); PG8_MMA(0, 0, At, B0); PG8_BAR; PG8_SCHED;
;             PG8_LDB(B1, 0, 1); PG8_STAGE(PG8_SB(0, 0), b2, voffB);
;             PG8_BAR; PG8_WAIT_L(0); PG8_MMA(0, 1, At, B1); PG8_BAR;
;             PG8_LDA(At, 0, 1); PG8_STAGE(PG8_SA(0, 0), a2, voffA);
;             PG8_BAR; PG8_WAIT_L(0); PG8_MMA(1, 0, At, B0); PG8_BAR; PG8_SCHED;
.LBB0_1261:
	s_add_u32 s17, s12, s7
	s_addc_u32 s19, s13, 0
	s_add_u32 s40, s17, 0x100
	s_addc_u32 s41, s19, 0
	s_and_b64 s[38:39], s[22:23], exec
	s_cselect_b32 s43, s15, s41
	s_cselect_b32 s42, s14, s40
	s_add_u32 s7, s10, s7
	s_addc_u32 s38, s11, 0
	s_add_u32 s7, s7, 0x100
	s_addc_u32 s38, s38, 0
	s_add_i32 s68, 0, 0x10000
	s_and_b64 s[22:23], s[22:23], exec
	s_cselect_b32 s45, s3, s38
	s_cselect_b32 s44, s2, s7
	s_add_u32 s46, s17, 0x80080
	s_addc_u32 s47, s19, 0
	s_add_i32 s72, s68, s53
	s_add_i32 m0, s5, 0xc000
	s_add_i32 s73, s5, 0xe000
	s_add_i32 s71, 0, 0x14000
	s_add_i32 s70, s72, 0x2000
	s_add_u32 s40, s44, 0x80000
	v_add_u32_e32 v148, s68, v133
	s_addc_u32 s41, s45, 0
	s_add_i32 s67, s71, s53
	ds_read_b128 v[136:139], v148
	ds_read_b128 v[140:143], v148 offset:1024
	ds_read_b128 v[144:147], v148 offset:2048
	ds_read_b128 v[148:151], v148 offset:3072
	s_add_i32 s66, s67, 0x2000
	s_add_i32 s65, 0, 0x18000
	s_add_u32 s38, s42, 0x80000
	s_addc_u32 s39, s43, 0
	s_add_i32 s19, s65, s53
	s_add_i32 s17, 0, 0x1c000
	s_add_i32 s7, s19, 0x2000
	s_add_u32 s22, s44, 0x80080
	s_addc_u32 s23, s45, 0
	s_add_i32 s69, s17, s53
	s_add_i32 s68, s69, 0x2000
	ds_read_b128 v[152:155], v135
	ds_read_b128 v[156:159], v135 offset:1024
	ds_read_b128 v[160:163], v135 offset:2048
	ds_read_b128 v[164:167], v135 offset:3072
	ds_read_b128 v[168:171], v135 offset:4096
	ds_read_b128 v[172:175], v135 offset:5120
	ds_read_b128 v[176:179], v135 offset:6144
	ds_read_b128 v[180:183], v135 offset:7168
	global_load_lds_dwordx4 v0, s[46:47]
	s_mov_b32 m0, s73
	s_nop 0
	global_load_lds_dwordx4 v130, s[46:47]
	s_waitcnt lgkmcnt(8)
	s_barrier
	s_waitcnt lgkmcnt(0)
	s_setprio 1
	v_mfma_f32_16x16x32_bf16 v[126:129], v[136:139], v[152:155], v[126:129]
	v_mfma_f32_16x16x32_bf16 v[122:125], v[144:147], v[152:155], v[122:125]
	v_mfma_f32_16x16x32_bf16 v[118:121], v[136:139], v[160:163], v[118:121]
	v_mfma_f32_16x16x32_bf16 v[114:117], v[144:147], v[160:163], v[114:117]
	v_mfma_f32_16x16x32_bf16 v[106:109], v[136:139], v[168:171], v[106:109]
	v_mfma_f32_16x16x32_bf16 v[98:101], v[144:147], v[168:171], v[98:101]
	v_mfma_f32_16x16x32_bf16 v[90:93], v[136:139], v[176:179], v[90:93]
	v_mfma_f32_16x16x32_bf16 v[82:85], v[144:147], v[176:179], v[82:85]
	v_mfma_f32_16x16x32_bf16 v[126:129], v[140:143], v[156:159], v[126:129]
	v_mfma_f32_16x16x32_bf16 v[122:125], v[148:151], v[156:159], v[122:125]
	v_mfma_f32_16x16x32_bf16 v[118:121], v[140:143], v[164:167], v[118:121]
	v_mfma_f32_16x16x32_bf16 v[114:117], v[148:151], v[164:167], v[114:117]
	v_mfma_f32_16x16x32_bf16 v[106:109], v[140:143], v[172:175], v[106:109]
	v_mfma_f32_16x16x32_bf16 v[98:101], v[148:151], v[172:175], v[98:101]
	v_mfma_f32_16x16x32_bf16 v[90:93], v[140:143], v[180:183], v[90:93]
	v_mfma_f32_16x16x32_bf16 v[82:85], v[148:151], v[180:183], v[82:85]
	s_setprio 0
	s_barrier
	s_mov_b32 m0, s72
	v_add_u32_e32 v196, s71, v133
	v_lshl_add_u64 v[200:201], s[44:45], 0, v[0:1]
	ds_read_b128 v[184:187], v196
	ds_read_b128 v[188:191], v196 offset:1024
	ds_read_b128 v[192:195], v196 offset:2048
	ds_read_b128 v[196:199], v196 offset:3072
	global_load_lds_dwordx4 v[200:201], off
	s_mov_b32 m0, s70
	v_lshl_add_u64 v[202:203], s[44:45], 0, v[130:131]
	global_load_lds_dwordx4 v[202:203], off
	s_barrier
	s_waitcnt lgkmcnt(0)
	s_setprio 1
	v_mfma_f32_16x16x32_bf16 v[110:113], v[184:187], v[152:155], v[110:113]
	v_mfma_f32_16x16x32_bf16 v[102:105], v[192:195], v[152:155], v[102:105]
	v_mfma_f32_16x16x32_bf16 v[94:97], v[184:187], v[160:163], v[94:97]
	v_mfma_f32_16x16x32_bf16 v[86:89], v[192:195], v[160:163], v[86:89]
	v_mfma_f32_16x16x32_bf16 v[78:81], v[184:187], v[168:171], v[78:81]
	v_mfma_f32_16x16x32_bf16 v[74:77], v[192:195], v[168:171], v[74:77]
	v_mfma_f32_16x16x32_bf16 v[70:73], v[184:187], v[176:179], v[70:73]
	v_mfma_f32_16x16x32_bf16 v[66:69], v[192:195], v[176:179], v[66:69]
	v_mfma_f32_16x16x32_bf16 v[110:113], v[188:191], v[156:159], v[110:113]
	v_mfma_f32_16x16x32_bf16 v[102:105], v[196:199], v[156:159], v[102:105]
	v_mfma_f32_16x16x32_bf16 v[94:97], v[188:191], v[164:167], v[94:97]
	v_mfma_f32_16x16x32_bf16 v[86:89], v[196:199], v[164:167], v[86:89]
	v_mfma_f32_16x16x32_bf16 v[78:81], v[188:191], v[172:175], v[78:81]
	v_mfma_f32_16x16x32_bf16 v[74:77], v[196:199], v[172:175], v[74:77]
	v_mfma_f32_16x16x32_bf16 v[70:73], v[188:191], v[180:183], v[70:73]
	v_mfma_f32_16x16x32_bf16 v[66:69], v[196:199], v[180:183], v[66:69]
	s_setprio 0
	s_mov_b32 m0, s5
	v_lshl_add_u64 v[204:205], s[42:43], 0, v[0:1]
	s_barrier
	ds_read_b128 v[152:155], v135 offset:16384
	ds_read_b128 v[156:159], v135 offset:17408
	ds_read_b128 v[160:163], v135 offset:18432
	ds_read_b128 v[164:167], v135 offset:19456
	ds_read_b128 v[168:171], v135 offset:20480
	ds_read_b128 v[172:175], v135 offset:21504
	ds_read_b128 v[176:179], v135 offset:22528
	ds_read_b128 v[180:183], v135 offset:23552
	global_load_lds_dwordx4 v[204:205], off
	s_mov_b32 m0, s28
	v_lshl_add_u64 v[206:207], s[42:43], 0, v[130:131]
	global_load_lds_dwordx4 v[206:207], off
	s_barrier
	s_waitcnt lgkmcnt(0)
	s_setprio 1
	v_mfma_f32_16x16x32_bf16 v[62:65], v[136:139], v[152:155], v[62:65]
	v_mfma_f32_16x16x32_bf16 v[58:61], v[144:147], v[152:155], v[58:61]
	v_mfma_f32_16x16x32_bf16 v[54:57], v[136:139], v[160:163], v[54:57]
	v_mfma_f32_16x16x32_bf16 v[50:53], v[144:147], v[160:163], v[50:53]
	v_mfma_f32_16x16x32_bf16 v[38:41], v[136:139], v[168:171], v[38:41]
	v_mfma_f32_16x16x32_bf16 v[34:37], v[144:147], v[168:171], v[34:37]
	v_mfma_f32_16x16x32_bf16 v[22:25], v[136:139], v[176:179], v[22:25]
	v_mfma_f32_16x16x32_bf16 v[18:21], v[144:147], v[176:179], v[18:21]
	v_mfma_f32_16x16x32_bf16 v[62:65], v[140:143], v[156:159], v[62:65]
	v_mfma_f32_16x16x32_bf16 v[58:61], v[148:151], v[156:159], v[58:61]
	v_mfma_f32_16x16x32_bf16 v[54:57], v[140:143], v[164:167], v[54:57]
	v_mfma_f32_16x16x32_bf16 v[50:53], v[148:151], v[164:167], v[50:53]
	v_mfma_f32_16x16x32_bf16 v[38:41], v[140:143], v[172:175], v[38:41]
	v_mfma_f32_16x16x32_bf16 v[34:37], v[148:151], v[172:175], v[34:37]
	v_mfma_f32_16x16x32_bf16 v[22:25], v[140:143], v[180:183], v[22:25]
	v_mfma_f32_16x16x32_bf16 v[18:21], v[148:151], v[180:183], v[18:21]
	s_setprio 0
	s_barrier
; #define PG8_STAGE(bufoff, gbase, voff) do { _Pragma("unroll") for (int _i = 0; _i < 2; ++_i) \
;         __builtin_amdgcn_global_load_lds((const unsigned*)((const char*)(gbase) + (voff)[_i]), (LAS unsigned*)(lds + (bufoff) + ldsw + _i * 8192), 16, 0, 0); } while (0)
; #define PG8_LDA(dst, b, h) do { _Pragma("unroll") for (int m = 0; m < 4; ++m) _Pragma("unroll") for (int k = 0; k < 2; ++k) dst[m][k] = *(const LAS bf16x8*)(lds + PG8_SA(b, h) + aoff + m * 2048 + k * 1024); } while (0)
; #define PG8_LDB(dst, b, h) do { _Pragma("unroll") for (int n = 0; n < 2; ++n) _Pragma("unroll") for (int k = 0; k < 2; ++k) dst[n][k] = *(const LAS bf16x8*)(lds + PG8_SB(b, h) + boff + n * 2048 + k * 1024); } while (0)
; #define PG8_MMA(ai, bj, At, Bt) do { __builtin_amdgcn_s_setprio(1); _Pragma("unroll") for (int m = 0; m < 4; ++m) _Pragma("unroll") for (int n = 0; n < 2; ++n) _Pragma("unroll") for (int k = 0; k < 2; ++k) \
;         acc[ai][bj][m][n] = __builtin_amdgcn_mfma_f32_16x16x32_bf16(Bt[n][k], At[m][k], acc[ai][bj][m][n], 0, 0, 0); __builtin_amdgcn_s_setprio(0); } while (0)
; #define PG8_WAIT_V(n) asm volatile("s_waitcnt vmcnt(" #n ")" ::: "memory")
; #define PG8_WAIT_L(n) asm volatile("s_waitcnt lgkmcnt(" #n ")" ::: "memory")
; #define PG8_BAR __builtin_amdgcn_s_barrier()
; #define PG8_SCHED __builtin_amdgcn_sched_barrier(0)
; template <class Epi, class Sched>
; __device__ __forceinline__ void gemm_phase(LAS unsigned char* lds, const Gemm g, const Sched& S, const Epi& E, const int tid) {
;     ...
;             PG8_STAGE(PG8_SB(0, 1), b2 + hstep, voffB);
;             PG8_WAIT_V(6); PG8_BAR; PG8_MMA(1, 1, At, B1); PG8_BAR;
;             PG8_LDB(B0, 1, 0); PG8_SCHED; PG8_LDA(At, 1, 0); PG8_STAGE(PG8_SA(0, 1), a2 + hstep, voffA);
;             PG8_WAIT_L(8); PG8_BAR; PG8_WAIT_L(0); PG8_MMA(0, 0, At, B0); PG8_BAR; PG8_SCHED;
;             PG8_LDB(B1, 1, 1); PG8_STAGE(PG8_SB(1, 0), b3, voffB);
;             PG8_BAR; PG8_WAIT_L(0); PG8_MMA(0, 1, At, B1); PG8_BAR;
;             PG8_LDA(At, 1, 1); PG8_STAGE(PG8_SA(1, 0), a3, voffA);
	s_mov_b32 m0, s67
	s_nop 0
	global_load_lds_dwordx4 v0, s[40:41]
	s_mov_b32 m0, s66
	s_nop 0
	global_load_lds_dwordx4 v130, s[40:41]
	s_waitcnt vmcnt(6)
	s_barrier
	s_setprio 1
	v_mfma_f32_16x16x32_bf16 v[46:49], v[184:187], v[152:155], v[46:49]
	v_mfma_f32_16x16x32_bf16 v[42:45], v[192:195], v[152:155], v[42:45]
	v_mfma_f32_16x16x32_bf16 v[30:33], v[184:187], v[160:163], v[30:33]
	v_mfma_f32_16x16x32_bf16 v[26:29], v[192:195], v[160:163], v[26:29]
	v_mfma_f32_16x16x32_bf16 v[14:17], v[184:187], v[168:171], v[14:17]
	v_mfma_f32_16x16x32_bf16 v[10:13], v[192:195], v[168:171], v[10:13]
	v_mfma_f32_16x16x32_bf16 v[6:9], v[184:187], v[176:179], v[6:9]
	v_mfma_f32_16x16x32_bf16 v[2:5], v[192:195], v[176:179], v[2:5]
	v_mfma_f32_16x16x32_bf16 v[46:49], v[188:191], v[156:159], v[46:49]
	v_mfma_f32_16x16x32_bf16 v[42:45], v[196:199], v[156:159], v[42:45]
	v_mfma_f32_16x16x32_bf16 v[30:33], v[188:191], v[164:167], v[30:33]
	v_mfma_f32_16x16x32_bf16 v[26:29], v[196:199], v[164:167], v[26:29]
	v_mfma_f32_16x16x32_bf16 v[14:17], v[188:191], v[172:175], v[14:17]
	v_mfma_f32_16x16x32_bf16 v[10:13], v[196:199], v[172:175], v[10:13]
	v_mfma_f32_16x16x32_bf16 v[6:9], v[188:191], v[180:183], v[6:9]
	v_mfma_f32_16x16x32_bf16 v[2:5], v[196:199], v[180:183], v[2:5]
	s_setprio 0
	v_add_u32_e32 v148, s65, v133
	s_barrier
	ds_read_b128 v[136:139], v148
	ds_read_b128 v[140:143], v148 offset:1024
	ds_read_b128 v[144:147], v148 offset:2048
	ds_read_b128 v[148:151], v148 offset:3072
	s_mov_b32 m0, s54
	ds_read_b128 v[152:155], v135 offset:32768
	ds_read_b128 v[156:159], v135 offset:33792
	ds_read_b128 v[160:163], v135 offset:34816
	ds_read_b128 v[164:167], v135 offset:35840
	ds_read_b128 v[168:171], v135 offset:36864
	ds_read_b128 v[172:175], v135 offset:37888
	ds_read_b128 v[176:179], v135 offset:38912
	ds_read_b128 v[180:183], v135 offset:39936
	global_load_lds_dwordx4 v0, s[38:39]
	s_mov_b32 m0, s55
	s_nop 0
	global_load_lds_dwordx4 v130, s[38:39]
	s_waitcnt lgkmcnt(8)
	s_barrier
	s_waitcnt lgkmcnt(0)
	s_setprio 1
	v_mfma_f32_16x16x32_bf16 v[126:129], v[136:139], v[152:155], v[126:129]
	v_mfma_f32_16x16x32_bf16 v[122:125], v[144:147], v[152:155], v[122:125]
	v_mfma_f32_16x16x32_bf16 v[118:121], v[136:139], v[160:163], v[118:121]
	v_mfma_f32_16x16x32_bf16 v[114:117], v[144:147], v[160:163], v[114:117]
	v_mfma_f32_16x16x32_bf16 v[106:109], v[136:139], v[168:171], v[106:109]
	v_mfma_f32_16x16x32_bf16 v[98:101], v[144:147], v[168:171], v[98:101]
	v_mfma_f32_16x16x32_bf16 v[90:93], v[136:139], v[176:179], v[90:93]
	v_mfma_f32_16x16x32_bf16 v[82:85], v[144:147], v[176:179], v[82:85]
	v_mfma_f32_16x16x32_bf16 v[126:129], v[140:143], v[156:159], v[126:129]
	v_mfma_f32_16x16x32_bf16 v[122:125], v[148:151], v[156:159], v[122:125]
	v_mfma_f32_16x16x32_bf16 v[118:121], v[140:143], v[164:167], v[118:121]
	v_mfma_f32_16x16x32_bf16 v[114:117], v[148:151], v[164:167], v[114:117]
	v_mfma_f32_16x16x32_bf16 v[106:109], v[140:143], v[172:175], v[106:109]
	v_mfma_f32_16x16x32_bf16 v[98:101], v[148:151], v[172:175], v[98:101]
	v_mfma_f32_16x16x32_bf16 v[90:93], v[140:143], v[180:183], v[90:93]
	v_mfma_f32_16x16x32_bf16 v[82:85], v[148:151], v[180:183], v[82:85]
	s_setprio 0
	s_barrier
	s_mov_b32 m0, s19
	v_add_u32_e32 v196, s17, v133
	v_lshl_add_u64 v[200:201], v[200:201], 0, s[36:37]
	ds_read_b128 v[184:187], v196
	ds_read_b128 v[188:191], v196 offset:1024
	ds_read_b128 v[192:195], v196 offset:2048
	ds_read_b128 v[196:199], v196 offset:3072
	global_load_lds_dwordx4 v[200:201], off
	s_mov_b32 m0, s7
	v_lshl_add_u64 v[200:201], v[202:203], 0, s[36:37]
	global_load_lds_dwordx4 v[200:201], off
	s_barrier
	s_waitcnt lgkmcnt(0)
	s_setprio 1
	v_mfma_f32_16x16x32_bf16 v[110:113], v[184:187], v[152:155], v[110:113]
	v_mfma_f32_16x16x32_bf16 v[102:105], v[192:195], v[152:155], v[102:105]
	v_mfma_f32_16x16x32_bf16 v[94:97], v[184:187], v[160:163], v[94:97]
	v_mfma_f32_16x16x32_bf16 v[86:89], v[192:195], v[160:163], v[86:89]
	v_mfma_f32_16x16x32_bf16 v[78:81], v[184:187], v[168:171], v[78:81]
	v_mfma_f32_16x16x32_bf16 v[74:77], v[192:195], v[168:171], v[74:77]
	v_mfma_f32_16x16x32_bf16 v[70:73], v[184:187], v[176:179], v[70:73]
	v_mfma_f32_16x16x32_bf16 v[66:69], v[192:195], v[176:179], v[66:69]
	v_mfma_f32_16x16x32_bf16 v[110:113], v[188:191], v[156:159], v[110:113]
	v_mfma_f32_16x16x32_bf16 v[102:105], v[196:199], v[156:159], v[102:105]
	v_mfma_f32_16x16x32_bf16 v[94:97], v[188:191], v[164:167], v[94:97]
	v_mfma_f32_16x16x32_bf16 v[86:89], v[196:199], v[164:167], v[86:89]
	v_mfma_f32_16x16x32_bf16 v[78:81], v[188:191], v[172:175], v[78:81]
	v_mfma_f32_16x16x32_bf16 v[74:77], v[196:199], v[172:175], v[74:77]
	v_mfma_f32_16x16x32_bf16 v[70:73], v[188:191], v[180:183], v[70:73]
	v_mfma_f32_16x16x32_bf16 v[66:69], v[196:199], v[180:183], v[66:69]
	s_setprio 0
	s_mov_b32 m0, s59
	v_lshl_add_u64 v[200:201], v[204:205], 0, s[36:37]
	s_barrier
	ds_read_b128 v[152:155], v135 offset:49152
	ds_read_b128 v[156:159], v135 offset:50176
	ds_read_b128 v[160:163], v135 offset:51200
	ds_read_b128 v[164:167], v135 offset:52224
	ds_read_b128 v[168:171], v135 offset:53248
	ds_read_b128 v[172:175], v135 offset:54272
	ds_read_b128 v[176:179], v135 offset:55296
	ds_read_b128 v[180:183], v135 offset:56320
	global_load_lds_dwordx4 v[200:201], off
	s_mov_b32 m0, s60
	v_lshl_add_u64 v[200:201], v[206:207], 0, s[36:37]
	global_load_lds_dwordx4 v[200:201], off
	s_barrier
; #define PG8_STAGE(bufoff, gbase, voff) do { _Pragma("unroll") for (int _i = 0; _i < 2; ++_i) \
;         __builtin_amdgcn_global_load_lds((const unsigned*)((const char*)(gbase) + (voff)[_i]), (LAS unsigned*)(lds + (bufoff) + ldsw + _i * 8192), 16, 0, 0); } while (0)
; #define PG8_MMA(ai, bj, At, Bt) do { __builtin_amdgcn_s_setprio(1); _Pragma("unroll") for (int m = 0; m < 4; ++m) _Pragma("unroll") for (int n = 0; n < 2; ++n) _Pragma("unroll") for (int k = 0; k < 2; ++k) \
;         acc[ai][bj][m][n] = __builtin_amdgcn_mfma_f32_16x16x32_bf16(Bt[n][k], At[m][k], acc[ai][bj][m][n], 0, 0, 0); __builtin_amdgcn_s_setprio(0); } while (0)
; #define PG8_WAIT_V(n) asm volatile("s_waitcnt vmcnt(" #n ")" ::: "memory")
; #define PG8_WAIT_L(n) asm volatile("s_waitcnt lgkmcnt(" #n ")" ::: "memory")
; #define PG8_BAR __builtin_amdgcn_s_barrier()
; #define PG8_SCHED __builtin_amdgcn_sched_barrier(0)
;     __device__ __forceinline__ void operator()(const f32x4 (&acc)[2][2][4][2], const Unit& u, int wr, int wc, int fr, int fq) const {
;         const int row0 = u.pm * BM + wr * 64 + fr, col0 = u.pn * BM + wc * 32 + 4 * fq;
;         float* base = (u.nt < ntfull) ? part + ((size_t)u.ks * MCTX - MLAT) * ldc : C;
; #pragma unroll
;         for (int ai = 0; ai < 2; ++ai)
; #pragma unroll
;             for (int m = 0; m < 4; ++m) { float* rowp = base + (size_t)(row0 + ai * HALF + m * 16) * ldc + col0;
; #pragma unroll
;                 for (int bj = 0; bj < 2; ++bj)
; #pragma unroll
;                     for (int n = 0; n < 2; ++n) *(f32x4*)(rowp + bj * HALF + n * 16) = acc[ai][bj][m][n]; }
; template <class Epi, class Sched>
; __device__ __forceinline__ void gemm_phase(LAS unsigned char* lds, const Gemm g, const Sched& S, const Epi& E, const int tid) {
;     ...
;             PG8_BAR; PG8_WAIT_L(0); PG8_MMA(1, 0, At, B0); PG8_BAR; PG8_SCHED;
;             PG8_STAGE(PG8_SB(1, 1), b3 + hstep, voffB);
;             PG8_WAIT_V(6); PG8_BAR; PG8_MMA(1, 1, At, B1); PG8_BAR;
	s_waitcnt lgkmcnt(0)
	s_setprio 1
	v_mfma_f32_16x16x32_bf16 v[62:65], v[136:139], v[152:155], v[62:65]
	v_mfma_f32_16x16x32_bf16 v[58:61], v[144:147], v[152:155], v[58:61]
	v_mfma_f32_16x16x32_bf16 v[54:57], v[136:139], v[160:163], v[54:57]
	v_mfma_f32_16x16x32_bf16 v[50:53], v[144:147], v[160:163], v[50:53]
	v_mfma_f32_16x16x32_bf16 v[38:41], v[136:139], v[168:171], v[38:41]
	v_mfma_f32_16x16x32_bf16 v[34:37], v[144:147], v[168:171], v[34:37]
	v_mfma_f32_16x16x32_bf16 v[22:25], v[136:139], v[176:179], v[22:25]
	v_mfma_f32_16x16x32_bf16 v[18:21], v[144:147], v[176:179], v[18:21]
	v_mfma_f32_16x16x32_bf16 v[62:65], v[140:143], v[156:159], v[62:65]
	v_mfma_f32_16x16x32_bf16 v[58:61], v[148:151], v[156:159], v[58:61]
	v_mfma_f32_16x16x32_bf16 v[54:57], v[140:143], v[164:167], v[54:57]
	v_mfma_f32_16x16x32_bf16 v[50:53], v[148:151], v[164:167], v[50:53]
	v_mfma_f32_16x16x32_bf16 v[38:41], v[140:143], v[172:175], v[38:41]
	v_mfma_f32_16x16x32_bf16 v[34:37], v[148:151], v[172:175], v[34:37]
	v_mfma_f32_16x16x32_bf16 v[22:25], v[140:143], v[180:183], v[22:25]
	v_mfma_f32_16x16x32_bf16 v[18:21], v[148:151], v[180:183], v[18:21]
	s_setprio 0
	s_barrier
	s_mov_b32 m0, s69
	s_nop 0
	global_load_lds_dwordx4 v0, s[22:23]
	s_mov_b32 m0, s68
	s_nop 0
	global_load_lds_dwordx4 v130, s[22:23]
	s_waitcnt vmcnt(6)
	s_barrier
	s_setprio 1
	v_mfma_f32_16x16x32_bf16 v[46:49], v[184:187], v[152:155], v[46:49]
	v_mfma_f32_16x16x32_bf16 v[42:45], v[192:195], v[152:155], v[42:45]
	v_mfma_f32_16x16x32_bf16 v[30:33], v[184:187], v[160:163], v[30:33]
	v_mfma_f32_16x16x32_bf16 v[26:29], v[192:195], v[160:163], v[26:29]
	v_mfma_f32_16x16x32_bf16 v[14:17], v[184:187], v[168:171], v[14:17]
	v_mfma_f32_16x16x32_bf16 v[10:13], v[192:195], v[168:171], v[10:13]
	v_mfma_f32_16x16x32_bf16 v[6:9], v[184:187], v[176:179], v[6:9]
	v_mfma_f32_16x16x32_bf16 v[2:5], v[192:195], v[176:179], v[2:5]
	v_mfma_f32_16x16x32_bf16 v[46:49], v[188:191], v[156:159], v[46:49]
	v_mfma_f32_16x16x32_bf16 v[42:45], v[196:199], v[156:159], v[42:45]
	v_mfma_f32_16x16x32_bf16 v[30:33], v[188:191], v[164:167], v[30:33]
	v_mfma_f32_16x16x32_bf16 v[26:29], v[196:199], v[164:167], v[26:29]
	v_mfma_f32_16x16x32_bf16 v[14:17], v[188:191], v[172:175], v[14:17]
	v_mfma_f32_16x16x32_bf16 v[10:13], v[196:199], v[172:175], v[10:13]
	v_mfma_f32_16x16x32_bf16 v[6:9], v[188:191], v[180:183], v[6:9]
	v_mfma_f32_16x16x32_bf16 v[2:5], v[196:199], v[180:183], v[2:5]
	s_setprio 0
	s_movk_i32 s7, 0x100
	s_andn2_b64 vcc, exec, s[20:21]
	s_mov_b64 s[22:23], -1
	s_mov_b64 s[20:21], 0
	s_barrier
	s_cbranch_vccz .LBB0_1261
	s_ashr_i32 s7, s6, 31
	s_lshl_b64 s[6:7], s[6:7], 22
	s_add_u32 s6, s61, s6
	v_lshl_or_b32 v136, s4, 8, v134
	v_lshl_add_u32 v138, s29, 8, v132
	s_addc_u32 s7, s62, s7
	v_ashrrev_i32_e32 v137, 31, v136
	v_ashrrev_i32_e32 v139, 31, v138
	v_lshl_add_u64 v[136:137], v[136:137], 2, s[6:7]
	v_lshlrev_b64 v[140:141], 13, v[138:139]
	v_lshl_add_u64 v[140:141], v[136:137], 0, v[140:141]
	global_store_dwordx4 v[140:141], v[126:129], off
	global_store_dwordx4 v[140:141], v[122:125], off offset:64
	global_store_dwordx4 v[140:141], v[110:113], off offset:512
	global_store_dwordx4 v[140:141], v[102:105], off offset:576
	s_mov_b32 s4, 0x100000
	s_mov_b64 s[6:7], 0x100000
	v_or_b32_e32 v102, 16, v138
	v_ashrrev_i32_e32 v103, 31, v102
	v_lshlrev_b64 v[102:103], 13, v[102:103]
	v_lshl_add_u64 v[102:103], v[136:137], 0, v[102:103]
	global_store_dwordx4 v[102:103], v[118:121], off
	global_store_dwordx4 v[102:103], v[114:117], off offset:64
	global_store_dwordx4 v[102:103], v[94:97], off offset:512
	global_store_dwordx4 v[102:103], v[86:89], off offset:576
	s_mov_b32 s29, s64
	s_mov_b64 s[10:11], s[2:3]
	v_or_b32_e32 v86, 32, v138
	v_ashrrev_i32_e32 v87, 31, v86
	v_lshlrev_b64 v[86:87], 13, v[86:87]
	v_lshl_add_u64 v[86:87], v[136:137], 0, v[86:87]
	global_store_dwordx4 v[86:87], v[106:109], off
	global_store_dwordx4 v[86:87], v[98:101], off offset:64
	global_store_dwordx4 v[86:87], v[78:81], off offset:512
	global_store_dwordx4 v[86:87], v[74:77], off offset:576
	s_mov_b64 s[12:13], s[14:15]
	s_nop 0
	v_or_b32_e32 v74, 48, v138
	v_ashrrev_i32_e32 v75, 31, v74
	v_lshlrev_b64 v[74:75], 13, v[74:75]
	v_lshl_add_u64 v[74:75], v[136:137], 0, v[74:75]
	global_store_dwordx4 v[74:75], v[90:93], off
	global_store_dwordx4 v[74:75], v[82:85], off offset:64
	global_store_dwordx4 v[74:75], v[70:73], off offset:512
	global_store_dwordx4 v[74:75], v[66:69], off offset:576
	s_nop 1
	v_add_co_u32_e32 v68, vcc, s4, v140
	s_mov_b32 s4, 0x120000
	s_nop 0
	v_addc_co_u32_e32 v69, vcc, 0, v141, vcc
	v_lshl_add_u64 v[66:67], v[140:141], 0, s[6:7]
	global_store_dwordx4 v[68:69], v[62:65], off
	global_store_dwordx4 v[66:67], v[58:61], off offset:64
	global_store_dwordx4 v[66:67], v[46:49], off offset:512
	global_store_dwordx4 v[66:67], v[42:45], off offset:576
	s_mov_b64 s[6:7], 0x120000
	s_nop 0
	v_add_co_u32_e32 v44, vcc, s4, v140
	s_mov_b32 s4, 0x140000
	s_nop 0
	v_addc_co_u32_e32 v45, vcc, 0, v141, vcc
	v_lshl_add_u64 v[42:43], v[140:141], 0, s[6:7]
	global_store_dwordx4 v[44:45], v[54:57], off
	global_store_dwordx4 v[42:43], v[50:53], off offset:64
	global_store_dwordx4 v[42:43], v[30:33], off offset:512
	global_store_dwordx4 v[42:43], v[26:29], off offset:576
	s_mov_b64 s[6:7], 0x140000
	s_nop 0
	v_add_co_u32_e32 v28, vcc, s4, v140
	v_lshl_add_u64 v[26:27], v[140:141], 0, s[6:7]
	s_nop 0
	v_addc_co_u32_e32 v29, vcc, 0, v141, vcc
	global_store_dwordx4 v[28:29], v[38:41], off
	global_store_dwordx4 v[26:27], v[34:37], off offset:64
	global_store_dwordx4 v[26:27], v[14:17], off offset:512
	global_store_dwordx4 v[26:27], v[10:13], off offset:576
	s_mov_b64 s[6:7], 0x160000
	s_mov_b32 s4, s18
	v_add_co_u32_e32 v12, vcc, 0x160000, v140
	v_lshl_add_u64 v[10:11], v[140:141], 0, s[6:7]
	s_nop 0
	v_addc_co_u32_e32 v13, vcc, 0, v141, vcc
	s_and_b64 vcc, exec, s[0:1]
	s_mov_b32 s6, s16
	global_store_dwordx4 v[12:13], v[22:25], off
	global_store_dwordx4 v[10:11], v[18:21], off offset:64
	global_store_dwordx4 v[10:11], v[6:9], off offset:512
	global_store_dwordx4 v[10:11], v[2:5], off offset:576
	s_cbranch_vccz .LBB0_1256
	s_waitcnt vmcnt(0)
	s_cmpk_gt_u32 s49, 0xff
	s_cbranch_scc1 .LBB0_1265
	s_barrier

; #define PG8_STAGE(bufoff, gbase, voff) do { _Pragma("unroll") for (int _i = 0; _i < 2; ++_i) \
;         __builtin_amdgcn_global_load_lds((const unsigned*)((const char*)(gbase) + (voff)[_i]), (LAS unsigned*)(lds + (bufoff) + ldsw + _i * 8192), 16, 0, 0); } while (0)
; #define PG8_LDA(dst, b, h) do { _Pragma("unroll") for (int m = 0; m < 4; ++m) _Pragma("unroll") for (int k = 0; k < 2; ++k) dst[m][k] = *(const LAS bf16x8*)(lds + PG8_SA(b, h) + aoff + m * 2048 + k * 1024); } while (0)
; #define PG8_LDB(dst, b, h) do { _Pragma("unroll") for (int n = 0; n < 2; ++n) _Pragma("unroll") for (int k = 0; k < 2; ++k) dst[n][k] = *(const LAS bf16x8*)(lds + PG8_SB(b, h) + boff + n * 2048 + k * 1024); } while (0)
; #define PG8_MMA(ai, bj, At, Bt) do { __builtin_amdgcn_s_setprio(1); _Pragma("unroll") for (int m = 0; m < 4; ++m) _Pragma("unroll") for (int n = 0; n < 2; ++n) _Pragma("unroll") for (int k = 0; k < 2; ++k) \
;         acc[ai][bj][m][n] = __builtin_amdgcn_mfma_f32_16x16x32_bf16(Bt[n][k], At[m][k], acc[ai][bj][m][n], 0, 0, 0); __builtin_amdgcn_s_setprio(0); } while (0)
; #define PG8_WAIT_L(n) asm volatile("s_waitcnt lgkmcnt(" #n ")" ::: "memory")
; #define PG8_BAR __builtin_amdgcn_s_barrier()
; #define PG8_SCHED __builtin_amdgcn_sched_barrier(0)
; template <class Epi, class Sched>
; __device__ __forceinline__ void gemm_phase(LAS unsigned char* lds, const Gemm g, const Sched& S, const Epi& E, const int tid) {
;     ...
;             const bool last = (t == nt - 2);
;             const char* a1 = cA + (size_t)(t + 1) * kstep;
;             const char* a2 = last ? nA : cA + (size_t)(t + 2) * kstep; const char* b2 = last ? nB : cB + (size_t)(t + 2) * kstep;
;             const char* a3 = a2 + kstep; const char* b3 = b2 + kstep;
;             if (last && has_next) S.a_ready(nxt);
;             if constexpr (Epi::PRELOAD) { if (last) E.preload(cur, lds, wid, lane); }
;             PG8_LDB(B0, 0, 0); PG8_SCHED; PG8_LDA(At, 0, 0); PG8_STAGE(PG8_SA(1, 1), a1 + hstep, voffA);
;             PG8_WAIT_L(8); PG8_BAR; PG8_WAIT_L(0); PG8_MMA(0, 0, At, B0); PG8_BAR; PG8_SCHED;
;             PG8_LDB(B1, 0, 1); PG8_STAGE(PG8_SB(0, 0), b2, voffB);
;             PG8_BAR; PG8_WAIT_L(0); PG8_MMA(0, 1, At, B1); PG8_BAR;
;             PG8_LDA(At, 0, 1); PG8_STAGE(PG8_SA(0, 0), a2, voffA);
;             PG8_BAR; PG8_WAIT_L(0); PG8_MMA(1, 0, At, B0); PG8_BAR; PG8_SCHED;
.LBB0_1393:
	s_add_u32 s50, s48, 0x100
	s_addc_u32 s51, s49, 0
	s_and_b64 s[24:25], s[52:53], exec
	s_cselect_b32 s55, s45, s51
	s_cselect_b32 s54, s44, s50
	s_cselect_b32 s53, s3, s23
	s_cselect_b32 s52, s2, s5
	s_add_i32 s24, 0, 0x10000
	v_add_u32_e32 v144, s24, v209
	ds_read_b128 v[132:135], v144
	ds_read_b128 v[136:139], v144 offset:1024
	ds_read_b128 v[140:143], v144 offset:2048
	ds_read_b128 v[144:147], v144 offset:3072
	v_lshl_add_u64 v[176:177], s[48:49], 0, v[186:187]
	s_add_i32 m0, s7, 0xc000
	ds_read_b128 v[148:151], v216
	ds_read_b128 v[152:155], v216 offset:1024
	ds_read_b128 v[156:159], v216 offset:2048
	ds_read_b128 v[160:163], v216 offset:3072
	ds_read_b128 v[164:167], v216 offset:4096
	ds_read_b128 v[168:171], v216 offset:5120
	ds_read_b128 v[172:175], v216 offset:6144
	ds_read_b128 v[190:193], v216 offset:7168
	global_load_lds_dwordx4 v[176:177], off
	s_add_i32 m0, s7, 0xe000
	v_lshl_add_u64 v[176:177], s[48:49], 0, v[188:189]
	global_load_lds_dwordx4 v[176:177], off
	s_waitcnt lgkmcnt(8)
	s_barrier
	s_waitcnt lgkmcnt(0)
	s_setprio 1
	v_mfma_f32_16x16x32_bf16 v[126:129], v[132:135], v[148:151], v[126:129]
	v_mfma_f32_16x16x32_bf16 v[122:125], v[140:143], v[148:151], v[122:125]
	v_mfma_f32_16x16x32_bf16 v[118:121], v[132:135], v[156:159], v[118:121]
	v_mfma_f32_16x16x32_bf16 v[114:117], v[140:143], v[156:159], v[114:117]
	v_mfma_f32_16x16x32_bf16 v[102:105], v[132:135], v[164:167], v[102:105]
	v_mfma_f32_16x16x32_bf16 v[98:101], v[140:143], v[164:167], v[98:101]
	v_mfma_f32_16x16x32_bf16 v[86:89], v[132:135], v[172:175], v[86:89]
	v_mfma_f32_16x16x32_bf16 v[82:85], v[140:143], v[172:175], v[82:85]
	v_mfma_f32_16x16x32_bf16 v[126:129], v[136:139], v[152:155], v[126:129]
	v_mfma_f32_16x16x32_bf16 v[122:125], v[144:147], v[152:155], v[122:125]
	v_mfma_f32_16x16x32_bf16 v[118:121], v[136:139], v[160:163], v[118:121]
	v_mfma_f32_16x16x32_bf16 v[114:117], v[144:147], v[160:163], v[114:117]
	v_mfma_f32_16x16x32_bf16 v[102:105], v[136:139], v[168:171], v[102:105]
	v_mfma_f32_16x16x32_bf16 v[98:101], v[144:147], v[168:171], v[98:101]
	v_mfma_f32_16x16x32_bf16 v[86:89], v[136:139], v[190:193], v[86:89]
	v_mfma_f32_16x16x32_bf16 v[82:85], v[144:147], v[190:193], v[82:85]
	s_setprio 0
	s_barrier
	s_add_i32 s28, 0, 0x14000
	v_add_u32_e32 v176, s28, v209
	s_add_i32 s24, s24, s66
	ds_read_b128 v[194:197], v176
	ds_read_b128 v[198:201], v176 offset:1024
	ds_read_b128 v[202:205], v176 offset:2048
	ds_read_b128 v[218:221], v176 offset:3072
	v_lshl_add_u64 v[176:177], s[52:53], 0, v[0:1]
	s_mov_b32 m0, s24
	v_lshl_add_u64 v[206:207], s[52:53], 0, v[182:183]
	global_load_lds_dwordx4 v[176:177], off
	s_add_i32 m0, s24, 0x2000
	s_nop 0
	global_load_lds_dwordx4 v[206:207], off
	s_barrier
	s_waitcnt lgkmcnt(0)
	s_setprio 1
	v_mfma_f32_16x16x32_bf16 v[110:113], v[194:197], v[148:151], v[110:113]
	v_mfma_f32_16x16x32_bf16 v[106:109], v[202:205], v[148:151], v[106:109]
	v_mfma_f32_16x16x32_bf16 v[94:97], v[194:197], v[156:159], v[94:97]
	v_mfma_f32_16x16x32_bf16 v[90:93], v[202:205], v[156:159], v[90:93]
	v_mfma_f32_16x16x32_bf16 v[78:81], v[194:197], v[164:167], v[78:81]
	v_mfma_f32_16x16x32_bf16 v[74:77], v[202:205], v[164:167], v[74:77]
	v_mfma_f32_16x16x32_bf16 v[70:73], v[194:197], v[172:175], v[70:73]
	v_mfma_f32_16x16x32_bf16 v[66:69], v[202:205], v[172:175], v[66:69]
	v_mfma_f32_16x16x32_bf16 v[110:113], v[198:201], v[152:155], v[110:113]
	v_mfma_f32_16x16x32_bf16 v[106:109], v[218:221], v[152:155], v[106:109]
	v_mfma_f32_16x16x32_bf16 v[94:97], v[198:201], v[160:163], v[94:97]
	v_mfma_f32_16x16x32_bf16 v[90:93], v[218:221], v[160:163], v[90:93]
	v_mfma_f32_16x16x32_bf16 v[78:81], v[198:201], v[168:171], v[78:81]
	v_mfma_f32_16x16x32_bf16 v[74:77], v[218:221], v[168:171], v[74:77]
	v_mfma_f32_16x16x32_bf16 v[70:73], v[198:201], v[190:193], v[70:73]
	v_mfma_f32_16x16x32_bf16 v[66:69], v[218:221], v[190:193], v[66:69]
	s_setprio 0
	s_mov_b32 m0, s7
	v_lshl_add_u64 v[222:223], s[54:55], 0, v[178:179]
	s_barrier
	ds_read_b128 v[148:151], v216 offset:16384
	ds_read_b128 v[152:155], v216 offset:17408
	ds_read_b128 v[156:159], v216 offset:18432
	ds_read_b128 v[160:163], v216 offset:19456
	ds_read_b128 v[164:167], v216 offset:20480
	ds_read_b128 v[168:171], v216 offset:21504
	ds_read_b128 v[172:175], v216 offset:22528
	ds_read_b128 v[190:193], v216 offset:23552
	global_load_lds_dwordx4 v[222:223], off
	s_mov_b32 m0, s11
	v_lshl_add_u64 v[224:225], s[54:55], 0, v[180:181]
	global_load_lds_dwordx4 v[224:225], off
	s_barrier
	s_waitcnt lgkmcnt(0)
	s_setprio 1
	v_mfma_f32_16x16x32_bf16 v[62:65], v[132:135], v[148:151], v[62:65]
	v_mfma_f32_16x16x32_bf16 v[58:61], v[140:143], v[148:151], v[58:61]
	v_mfma_f32_16x16x32_bf16 v[54:57], v[132:135], v[156:159], v[54:57]
	v_mfma_f32_16x16x32_bf16 v[50:53], v[140:143], v[156:159], v[50:53]
	v_mfma_f32_16x16x32_bf16 v[38:41], v[132:135], v[164:167], v[38:41]
	v_mfma_f32_16x16x32_bf16 v[34:37], v[140:143], v[164:167], v[34:37]
	v_mfma_f32_16x16x32_bf16 v[22:25], v[132:135], v[172:175], v[22:25]
	v_mfma_f32_16x16x32_bf16 v[18:21], v[140:143], v[172:175], v[18:21]
	v_mfma_f32_16x16x32_bf16 v[62:65], v[136:139], v[152:155], v[62:65]
	v_mfma_f32_16x16x32_bf16 v[58:61], v[144:147], v[152:155], v[58:61]
	v_mfma_f32_16x16x32_bf16 v[54:57], v[136:139], v[160:163], v[54:57]
	v_mfma_f32_16x16x32_bf16 v[50:53], v[144:147], v[160:163], v[50:53]
	v_mfma_f32_16x16x32_bf16 v[38:41], v[136:139], v[168:171], v[38:41]
	v_mfma_f32_16x16x32_bf16 v[34:37], v[144:147], v[168:171], v[34:37]
	v_mfma_f32_16x16x32_bf16 v[22:25], v[136:139], v[190:193], v[22:25]
	v_mfma_f32_16x16x32_bf16 v[18:21], v[144:147], v[190:193], v[18:21]
	s_setprio 0
	s_barrier
; #define PG8_STAGE(bufoff, gbase, voff) do { _Pragma("unroll") for (int _i = 0; _i < 2; ++_i) \
;         __builtin_amdgcn_global_load_lds((const unsigned*)((const char*)(gbase) + (voff)[_i]), (LAS unsigned*)(lds + (bufoff) + ldsw + _i * 8192), 16, 0, 0); } while (0)
; #define PG8_LDA(dst, b, h) do { _Pragma("unroll") for (int m = 0; m < 4; ++m) _Pragma("unroll") for (int k = 0; k < 2; ++k) dst[m][k] = *(const LAS bf16x8*)(lds + PG8_SA(b, h) + aoff + m * 2048 + k * 1024); } while (0)
; #define PG8_LDB(dst, b, h) do { _Pragma("unroll") for (int n = 0; n < 2; ++n) _Pragma("unroll") for (int k = 0; k < 2; ++k) dst[n][k] = *(const LAS bf16x8*)(lds + PG8_SB(b, h) + boff + n * 2048 + k * 1024); } while (0)
; #define PG8_MMA(ai, bj, At, Bt) do { __builtin_amdgcn_s_setprio(1); _Pragma("unroll") for (int m = 0; m < 4; ++m) _Pragma("unroll") for (int n = 0; n < 2; ++n) _Pragma("unroll") for (int k = 0; k < 2; ++k) \
;         acc[ai][bj][m][n] = __builtin_amdgcn_mfma_f32_16x16x32_bf16(Bt[n][k], At[m][k], acc[ai][bj][m][n], 0, 0, 0); __builtin_amdgcn_s_setprio(0); } while (0)
; #define PG8_WAIT_V(n) asm volatile("s_waitcnt vmcnt(" #n ")" ::: "memory")
; #define PG8_WAIT_L(n) asm volatile("s_waitcnt lgkmcnt(" #n ")" ::: "memory")
; #define PG8_BAR __builtin_amdgcn_s_barrier()
; #define PG8_SCHED __builtin_amdgcn_sched_barrier(0)
; template <class Epi, class Sched>
; __device__ __forceinline__ void gemm_phase(LAS unsigned char* lds, const Gemm g, const Sched& S, const Epi& E, const int tid) {
;     ...
;             PG8_STAGE(PG8_SB(0, 1), b2 + hstep, voffB);
;             PG8_WAIT_V(6); PG8_BAR; PG8_MMA(1, 1, At, B1); PG8_BAR;
;             PG8_LDB(B0, 1, 0); PG8_SCHED; PG8_LDA(At, 1, 0); PG8_STAGE(PG8_SA(0, 1), a2 + hstep, voffA);
;             PG8_WAIT_L(8); PG8_BAR; PG8_WAIT_L(0); PG8_MMA(0, 0, At, B0); PG8_BAR; PG8_SCHED;
;             PG8_LDB(B1, 1, 1); PG8_STAGE(PG8_SB(1, 0), b3, voffB);
;             PG8_BAR; PG8_WAIT_L(0); PG8_MMA(0, 1, At, B1); PG8_BAR;
;             PG8_LDA(At, 1, 1); PG8_STAGE(PG8_SA(1, 0), a3, voffA);
	s_add_u32 s24, s52, 0x80000
	s_addc_u32 s25, s53, 0
	s_add_i32 s28, s28, s66
	s_mov_b32 m0, s28
	s_nop 0
	global_load_lds_dwordx4 v0, s[24:25]
	s_add_i32 m0, s28, 0x2000
	s_nop 0
	global_load_lds_dwordx4 v182, s[24:25]
	s_waitcnt vmcnt(6)
	s_barrier
	s_setprio 1
	v_mfma_f32_16x16x32_bf16 v[46:49], v[194:197], v[148:151], v[46:49]
	v_mfma_f32_16x16x32_bf16 v[42:45], v[202:205], v[148:151], v[42:45]
	v_mfma_f32_16x16x32_bf16 v[30:33], v[194:197], v[156:159], v[30:33]
	v_mfma_f32_16x16x32_bf16 v[26:29], v[202:205], v[156:159], v[26:29]
	v_mfma_f32_16x16x32_bf16 v[14:17], v[194:197], v[164:167], v[14:17]
	v_mfma_f32_16x16x32_bf16 v[10:13], v[202:205], v[164:167], v[10:13]
	v_mfma_f32_16x16x32_bf16 v[6:9], v[194:197], v[172:175], v[6:9]
	v_mfma_f32_16x16x32_bf16 v[2:5], v[202:205], v[172:175], v[2:5]
	v_mfma_f32_16x16x32_bf16 v[46:49], v[198:201], v[152:155], v[46:49]
	v_mfma_f32_16x16x32_bf16 v[42:45], v[218:221], v[152:155], v[42:45]
	v_mfma_f32_16x16x32_bf16 v[30:33], v[198:201], v[160:163], v[30:33]
	v_mfma_f32_16x16x32_bf16 v[26:29], v[218:221], v[160:163], v[26:29]
	v_mfma_f32_16x16x32_bf16 v[14:17], v[198:201], v[168:171], v[14:17]
	v_mfma_f32_16x16x32_bf16 v[10:13], v[218:221], v[168:171], v[10:13]
	v_mfma_f32_16x16x32_bf16 v[6:9], v[198:201], v[190:193], v[6:9]
	v_mfma_f32_16x16x32_bf16 v[2:5], v[218:221], v[190:193], v[2:5]
	s_setprio 0
	s_add_i32 s28, 0, 0x18000
	v_add_u32_e32 v144, s28, v209
	s_barrier
	ds_read_b128 v[132:135], v144
	ds_read_b128 v[136:139], v144 offset:1024
	ds_read_b128 v[140:143], v144 offset:2048
	ds_read_b128 v[144:147], v144 offset:3072
	s_add_u32 s24, s54, 0x80000
	s_addc_u32 s25, s55, 0
	s_mov_b32 m0, s67
	ds_read_b128 v[148:151], v216 offset:32768
	ds_read_b128 v[152:155], v216 offset:33792
	ds_read_b128 v[156:159], v216 offset:34816
	ds_read_b128 v[160:163], v216 offset:35840
	ds_read_b128 v[164:167], v216 offset:36864
	ds_read_b128 v[168:171], v216 offset:37888
	ds_read_b128 v[172:175], v216 offset:38912
	ds_read_b128 v[190:193], v216 offset:39936
	global_load_lds_dwordx4 v178, s[24:25]
	s_mov_b32 m0, s68
	s_nop 0
	global_load_lds_dwordx4 v180, s[24:25]
	s_waitcnt lgkmcnt(8)
	s_barrier
	s_waitcnt lgkmcnt(0)
	s_setprio 1
	v_mfma_f32_16x16x32_bf16 v[126:129], v[132:135], v[148:151], v[126:129]
	v_mfma_f32_16x16x32_bf16 v[122:125], v[140:143], v[148:151], v[122:125]
	v_mfma_f32_16x16x32_bf16 v[118:121], v[132:135], v[156:159], v[118:121]
	v_mfma_f32_16x16x32_bf16 v[114:117], v[140:143], v[156:159], v[114:117]
	v_mfma_f32_16x16x32_bf16 v[102:105], v[132:135], v[164:167], v[102:105]
	v_mfma_f32_16x16x32_bf16 v[98:101], v[140:143], v[164:167], v[98:101]
	v_mfma_f32_16x16x32_bf16 v[86:89], v[132:135], v[172:175], v[86:89]
	v_mfma_f32_16x16x32_bf16 v[82:85], v[140:143], v[172:175], v[82:85]
	v_mfma_f32_16x16x32_bf16 v[126:129], v[136:139], v[152:155], v[126:129]
	v_mfma_f32_16x16x32_bf16 v[122:125], v[144:147], v[152:155], v[122:125]
	v_mfma_f32_16x16x32_bf16 v[118:121], v[136:139], v[160:163], v[118:121]
	v_mfma_f32_16x16x32_bf16 v[114:117], v[144:147], v[160:163], v[114:117]
	v_mfma_f32_16x16x32_bf16 v[102:105], v[136:139], v[168:171], v[102:105]
	v_mfma_f32_16x16x32_bf16 v[98:101], v[144:147], v[168:171], v[98:101]
	v_mfma_f32_16x16x32_bf16 v[86:89], v[136:139], v[190:193], v[86:89]
	v_mfma_f32_16x16x32_bf16 v[82:85], v[144:147], v[190:193], v[82:85]
	s_setprio 0
	s_barrier
	s_add_i32 s29, 0, 0x1c000
	s_add_i32 s24, s28, s66
	v_add_u32_e32 v217, s29, v209
	v_lshl_add_u64 v[176:177], v[176:177], 0, s[36:37]
	s_mov_b32 m0, s24
	ds_read_b128 v[194:197], v217
	ds_read_b128 v[198:201], v217 offset:1024
	ds_read_b128 v[202:205], v217 offset:2048
	ds_read_b128 v[218:221], v217 offset:3072
	global_load_lds_dwordx4 v[176:177], off
	s_add_i32 m0, s24, 0x2000
	v_lshl_add_u64 v[176:177], v[206:207], 0, s[36:37]
	global_load_lds_dwordx4 v[176:177], off
	s_barrier
; #define PG8_STAGE(bufoff, gbase, voff) do { _Pragma("unroll") for (int _i = 0; _i < 2; ++_i) \
;         __builtin_amdgcn_global_load_lds((const unsigned*)((const char*)(gbase) + (voff)[_i]), (LAS unsigned*)(lds + (bufoff) + ldsw + _i * 8192), 16, 0, 0); } while (0)
; #define PG8_MMA(ai, bj, At, Bt) do { __builtin_amdgcn_s_setprio(1); _Pragma("unroll") for (int m = 0; m < 4; ++m) _Pragma("unroll") for (int n = 0; n < 2; ++n) _Pragma("unroll") for (int k = 0; k < 2; ++k) \
;         acc[ai][bj][m][n] = __builtin_amdgcn_mfma_f32_16x16x32_bf16(Bt[n][k], At[m][k], acc[ai][bj][m][n], 0, 0, 0); __builtin_amdgcn_s_setprio(0); } while (0)
; #define PG8_WAIT_V(n) asm volatile("s_waitcnt vmcnt(" #n ")" ::: "memory")
; #define PG8_WAIT_L(n) asm volatile("s_waitcnt lgkmcnt(" #n ")" ::: "memory")
; #define PG8_BAR __builtin_amdgcn_s_barrier()
; #define PG8_SCHED __builtin_amdgcn_sched_barrier(0)
; template <class Epi, class Sched>
; __device__ __forceinline__ void gemm_phase(LAS unsigned char* lds, const Gemm g, const Sched& S, const Epi& E, const int tid) {
;     ...
;             PG8_BAR; PG8_WAIT_L(0); PG8_MMA(1, 0, At, B0); PG8_BAR; PG8_SCHED;
;             PG8_STAGE(PG8_SB(1, 1), b3 + hstep, voffB);
;             PG8_WAIT_V(6); PG8_BAR; PG8_MMA(1, 1, At, B1); PG8_BAR;
	s_waitcnt lgkmcnt(0)
	s_setprio 1
	v_mfma_f32_16x16x32_bf16 v[110:113], v[194:197], v[148:151], v[110:113]
	v_mfma_f32_16x16x32_bf16 v[106:109], v[202:205], v[148:151], v[106:109]
	v_mfma_f32_16x16x32_bf16 v[94:97], v[194:197], v[156:159], v[94:97]
	v_mfma_f32_16x16x32_bf16 v[90:93], v[202:205], v[156:159], v[90:93]
	v_mfma_f32_16x16x32_bf16 v[78:81], v[194:197], v[164:167], v[78:81]
	v_mfma_f32_16x16x32_bf16 v[74:77], v[202:205], v[164:167], v[74:77]
	v_mfma_f32_16x16x32_bf16 v[70:73], v[194:197], v[172:175], v[70:73]
	v_mfma_f32_16x16x32_bf16 v[66:69], v[202:205], v[172:175], v[66:69]
	v_mfma_f32_16x16x32_bf16 v[110:113], v[198:201], v[152:155], v[110:113]
	v_mfma_f32_16x16x32_bf16 v[106:109], v[218:221], v[152:155], v[106:109]
	v_mfma_f32_16x16x32_bf16 v[94:97], v[198:201], v[160:163], v[94:97]
	v_mfma_f32_16x16x32_bf16 v[90:93], v[218:221], v[160:163], v[90:93]
	v_mfma_f32_16x16x32_bf16 v[78:81], v[198:201], v[168:171], v[78:81]
	v_mfma_f32_16x16x32_bf16 v[74:77], v[218:221], v[168:171], v[74:77]
	v_mfma_f32_16x16x32_bf16 v[70:73], v[198:201], v[190:193], v[70:73]
	v_mfma_f32_16x16x32_bf16 v[66:69], v[218:221], v[190:193], v[66:69]
	s_setprio 0
	s_mov_b32 m0, s72
	v_lshl_add_u64 v[176:177], v[222:223], 0, s[36:37]
	s_barrier
	ds_read_b128 v[148:151], v216 offset:49152
	ds_read_b128 v[152:155], v216 offset:50176
	ds_read_b128 v[156:159], v216 offset:51200
	ds_read_b128 v[160:163], v216 offset:52224
	ds_read_b128 v[164:167], v216 offset:53248
	ds_read_b128 v[168:171], v216 offset:54272
	ds_read_b128 v[172:175], v216 offset:55296
	ds_read_b128 v[190:193], v216 offset:56320
	global_load_lds_dwordx4 v[176:177], off
	s_mov_b32 m0, s73
	v_lshl_add_u64 v[176:177], v[224:225], 0, s[36:37]
	global_load_lds_dwordx4 v[176:177], off
	s_barrier
	s_waitcnt lgkmcnt(0)
	s_setprio 1
	v_mfma_f32_16x16x32_bf16 v[62:65], v[132:135], v[148:151], v[62:65]
	v_mfma_f32_16x16x32_bf16 v[58:61], v[140:143], v[148:151], v[58:61]
	v_mfma_f32_16x16x32_bf16 v[54:57], v[132:135], v[156:159], v[54:57]
	v_mfma_f32_16x16x32_bf16 v[50:53], v[140:143], v[156:159], v[50:53]
	v_mfma_f32_16x16x32_bf16 v[38:41], v[132:135], v[164:167], v[38:41]
	v_mfma_f32_16x16x32_bf16 v[34:37], v[140:143], v[164:167], v[34:37]
	v_mfma_f32_16x16x32_bf16 v[22:25], v[132:135], v[172:175], v[22:25]
	v_mfma_f32_16x16x32_bf16 v[18:21], v[140:143], v[172:175], v[18:21]
	v_mfma_f32_16x16x32_bf16 v[62:65], v[136:139], v[152:155], v[62:65]
	v_mfma_f32_16x16x32_bf16 v[58:61], v[144:147], v[152:155], v[58:61]
	v_mfma_f32_16x16x32_bf16 v[54:57], v[136:139], v[160:163], v[54:57]
	v_mfma_f32_16x16x32_bf16 v[50:53], v[144:147], v[160:163], v[50:53]
	v_mfma_f32_16x16x32_bf16 v[38:41], v[136:139], v[168:171], v[38:41]
	v_mfma_f32_16x16x32_bf16 v[34:37], v[144:147], v[168:171], v[34:37]
	v_mfma_f32_16x16x32_bf16 v[22:25], v[136:139], v[190:193], v[22:25]
	v_mfma_f32_16x16x32_bf16 v[18:21], v[144:147], v[190:193], v[18:21]
	s_setprio 0
	s_barrier
	s_add_u32 s24, s52, 0x80080
	s_addc_u32 s25, s53, 0
	s_add_i32 s28, s29, s66
	s_mov_b32 m0, s28
	s_nop 0
	global_load_lds_dwordx4 v0, s[24:25]
	s_add_i32 m0, s28, 0x2000
	s_nop 0
	global_load_lds_dwordx4 v182, s[24:25]
	s_waitcnt vmcnt(6)
	s_barrier
	s_setprio 1
	v_mfma_f32_16x16x32_bf16 v[46:49], v[194:197], v[148:151], v[46:49]
	v_mfma_f32_16x16x32_bf16 v[42:45], v[202:205], v[148:151], v[42:45]
	v_mfma_f32_16x16x32_bf16 v[30:33], v[194:197], v[156:159], v[30:33]
	v_mfma_f32_16x16x32_bf16 v[26:29], v[202:205], v[156:159], v[26:29]
	v_mfma_f32_16x16x32_bf16 v[14:17], v[194:197], v[164:167], v[14:17]
	v_mfma_f32_16x16x32_bf16 v[10:13], v[202:205], v[164:167], v[10:13]
	v_mfma_f32_16x16x32_bf16 v[6:9], v[194:197], v[172:175], v[6:9]
	v_mfma_f32_16x16x32_bf16 v[2:5], v[202:205], v[172:175], v[2:5]
	v_mfma_f32_16x16x32_bf16 v[46:49], v[198:201], v[152:155], v[46:49]
	v_mfma_f32_16x16x32_bf16 v[42:45], v[218:221], v[152:155], v[42:45]
	v_mfma_f32_16x16x32_bf16 v[30:33], v[198:201], v[160:163], v[30:33]
	v_mfma_f32_16x16x32_bf16 v[26:29], v[218:221], v[160:163], v[26:29]
	v_mfma_f32_16x16x32_bf16 v[14:17], v[198:201], v[168:171], v[14:17]
	v_mfma_f32_16x16x32_bf16 v[10:13], v[218:221], v[168:171], v[10:13]
	v_mfma_f32_16x16x32_bf16 v[6:9], v[198:201], v[190:193], v[6:9]
	v_mfma_f32_16x16x32_bf16 v[2:5], v[218:221], v[190:193], v[2:5]
	s_setprio 0
	s_add_i32 s24, s21, 2
	s_add_u32 s5, s5, 0x100
	s_addc_u32 s23, s23, 0
	s_cmp_ge_i32 s21, s78
	s_mov_b64 s[48:49], s[50:51]
	s_mov_b32 s21, s24
	s_barrier
	s_cbranch_scc1 .LBB0_1396

; #define PG8_STAGE(bufoff, gbase, voff) do { _Pragma("unroll") for (int _i = 0; _i < 2; ++_i) \
;         __builtin_amdgcn_global_load_lds((const unsigned*)((const char*)(gbase) + (voff)[_i]), (LAS unsigned*)(lds + (bufoff) + ldsw + _i * 8192), 16, 0, 0); } while (0)
; #define PG8_LDA(dst, b, h) do { _Pragma("unroll") for (int m = 0; m < 4; ++m) _Pragma("unroll") for (int k = 0; k < 2; ++k) dst[m][k] = *(const LAS bf16x8*)(lds + PG8_SA(b, h) + aoff + m * 2048 + k * 1024); } while (0)
; #define PG8_LDB(dst, b, h) do { _Pragma("unroll") for (int n = 0; n < 2; ++n) _Pragma("unroll") for (int k = 0; k < 2; ++k) dst[n][k] = *(const LAS bf16x8*)(lds + PG8_SB(b, h) + boff + n * 2048 + k * 1024); } while (0)
; #define PG8_MMA(ai, bj, At, Bt) do { __builtin_amdgcn_s_setprio(1); _Pragma("unroll") for (int m = 0; m < 4; ++m) _Pragma("unroll") for (int n = 0; n < 2; ++n) _Pragma("unroll") for (int k = 0; k < 2; ++k) \
;         acc[ai][bj][m][n] = __builtin_amdgcn_mfma_f32_16x16x32_bf16(Bt[n][k], At[m][k], acc[ai][bj][m][n], 0, 0, 0); __builtin_amdgcn_s_setprio(0); } while (0)
; #define PG8_WAIT_L(n) asm volatile("s_waitcnt lgkmcnt(" #n ")" ::: "memory")
; #define PG8_BAR __builtin_amdgcn_s_barrier()
; #define PG8_SCHED __builtin_amdgcn_sched_barrier(0)
; template <class Epi, class Sched>
; __device__ __forceinline__ void gemm_phase(LAS unsigned char* lds, const Gemm g, const Sched& S, const Epi& E, const int tid) {
;     ...
;             const bool last = (t == nt - 2);
;             const char* a1 = cA + (size_t)(t + 1) * kstep;
;             const char* a2 = last ? nA : cA + (size_t)(t + 2) * kstep; const char* b2 = last ? nB : cB + (size_t)(t + 2) * kstep;
;             const char* a3 = a2 + kstep; const char* b3 = b2 + kstep;
;             if (last && has_next) S.a_ready(nxt);
;             if constexpr (Epi::PRELOAD) { if (last) E.preload(cur, lds, wid, lane); }
;             PG8_LDB(B0, 0, 0); PG8_SCHED; PG8_LDA(At, 0, 0); PG8_STAGE(PG8_SA(1, 1), a1 + hstep, voffA);
;             PG8_WAIT_L(8); PG8_BAR; PG8_WAIT_L(0); PG8_MMA(0, 0, At, B0); PG8_BAR; PG8_SCHED;
;             PG8_LDB(B1, 0, 1); PG8_STAGE(PG8_SB(0, 0), b2, voffB);
;             PG8_BAR; PG8_WAIT_L(0); PG8_MMA(0, 1, At, B1); PG8_BAR;
;             PG8_LDA(At, 0, 1); PG8_STAGE(PG8_SA(0, 0), a2, voffA);
;             PG8_BAR; PG8_WAIT_L(0); PG8_MMA(1, 0, At, B0); PG8_BAR; PG8_SCHED;
.LBB0_1573:
	s_add_u32 s40, s38, 0xe1edc080
	s_addc_u32 s41, s39, -1
	s_cmpk_lg_i32 s65, 0x54
	s_cselect_b32 s40, s40, 0
	s_cselect_b32 s41, s41, 0
	s_add_u32 s42, s4, s40
	s_addc_u32 s43, s5, s41
	s_add_i32 s66, 0, 0x10000
	v_add_u32_e32 v154, s66, v140
	ds_read_b128 v[142:145], v154
	ds_read_b128 v[146:149], v154 offset:1024
	ds_read_b128 v[150:153], v154 offset:2048
	ds_read_b128 v[154:157], v154 offset:3072
	s_add_u32 s40, s0, s40
	s_addc_u32 s41, s1, s41
	v_lshl_add_u64 v[190:191], v[136:137], 0, s[38:39]
	s_add_i32 m0, s25, 0xc000
	ds_read_b128 v[158:161], v141
	ds_read_b128 v[162:165], v141 offset:1024
	ds_read_b128 v[166:169], v141 offset:2048
	ds_read_b128 v[170:173], v141 offset:3072
	ds_read_b128 v[174:177], v141 offset:4096
	ds_read_b128 v[178:181], v141 offset:5120
	ds_read_b128 v[182:185], v141 offset:6144
	ds_read_b128 v[186:189], v141 offset:7168
	global_load_lds_dwordx4 v[190:191], off
	s_add_i32 m0, s25, 0xe000
	v_lshl_add_u64 v[190:191], v[138:139], 0, s[38:39]
	global_load_lds_dwordx4 v[190:191], off
	s_waitcnt lgkmcnt(8)
	s_barrier
	s_waitcnt lgkmcnt(0)
	s_setprio 1
	v_mfma_f32_16x16x32_bf16 v[126:129], v[142:145], v[158:161], v[126:129]
	v_mfma_f32_16x16x32_bf16 v[122:125], v[150:153], v[158:161], v[122:125]
	v_mfma_f32_16x16x32_bf16 v[118:121], v[142:145], v[166:169], v[118:121]
	v_mfma_f32_16x16x32_bf16 v[110:113], v[150:153], v[166:169], v[110:113]
	v_mfma_f32_16x16x32_bf16 v[98:101], v[142:145], v[174:177], v[98:101]
	v_mfma_f32_16x16x32_bf16 v[90:93], v[150:153], v[174:177], v[90:93]
	v_mfma_f32_16x16x32_bf16 v[82:85], v[142:145], v[182:185], v[82:85]
	v_mfma_f32_16x16x32_bf16 v[74:77], v[150:153], v[182:185], v[74:77]
	v_mfma_f32_16x16x32_bf16 v[126:129], v[146:149], v[162:165], v[126:129]
	v_mfma_f32_16x16x32_bf16 v[122:125], v[154:157], v[162:165], v[122:125]
	v_mfma_f32_16x16x32_bf16 v[118:121], v[146:149], v[170:173], v[118:121]
	v_mfma_f32_16x16x32_bf16 v[110:113], v[154:157], v[170:173], v[110:113]
	v_mfma_f32_16x16x32_bf16 v[98:101], v[146:149], v[178:181], v[98:101]
	v_mfma_f32_16x16x32_bf16 v[90:93], v[154:157], v[178:181], v[90:93]
	v_mfma_f32_16x16x32_bf16 v[82:85], v[146:149], v[186:189], v[82:85]
	v_mfma_f32_16x16x32_bf16 v[74:77], v[154:157], v[186:189], v[74:77]
	s_setprio 0
	s_barrier
	s_add_i32 s68, 0, 0x14000
	s_add_i32 s66, s66, s24
	v_add_u32_e32 v202, s68, v140
	v_lshl_add_u64 v[206:207], s[40:41], 0, v[0:1]
	s_mov_b32 m0, s66
	ds_read_b128 v[190:193], v202
	ds_read_b128 v[194:197], v202 offset:1024
	ds_read_b128 v[198:201], v202 offset:2048
	ds_read_b128 v[202:205], v202 offset:3072
	global_load_lds_dwordx4 v[206:207], off
	s_add_i32 m0, s66, 0x2000
	v_lshl_add_u64 v[208:209], s[40:41], 0, v[134:135]
	global_load_lds_dwordx4 v[208:209], off
	s_barrier
	s_waitcnt lgkmcnt(0)
	s_setprio 1
	v_mfma_f32_16x16x32_bf16 v[114:117], v[190:193], v[158:161], v[114:117]
	v_mfma_f32_16x16x32_bf16 v[106:109], v[198:201], v[158:161], v[106:109]
	v_mfma_f32_16x16x32_bf16 v[102:105], v[190:193], v[166:169], v[102:105]
	v_mfma_f32_16x16x32_bf16 v[94:97], v[198:201], v[166:169], v[94:97]
	v_mfma_f32_16x16x32_bf16 v[86:89], v[190:193], v[174:177], v[86:89]
	v_mfma_f32_16x16x32_bf16 v[78:81], v[198:201], v[174:177], v[78:81]
	v_mfma_f32_16x16x32_bf16 v[70:73], v[190:193], v[182:185], v[70:73]
	v_mfma_f32_16x16x32_bf16 v[66:69], v[198:201], v[182:185], v[66:69]
	v_mfma_f32_16x16x32_bf16 v[114:117], v[194:197], v[162:165], v[114:117]
	v_mfma_f32_16x16x32_bf16 v[106:109], v[202:205], v[162:165], v[106:109]
	v_mfma_f32_16x16x32_bf16 v[102:105], v[194:197], v[170:173], v[102:105]
	v_mfma_f32_16x16x32_bf16 v[94:97], v[202:205], v[170:173], v[94:97]
	v_mfma_f32_16x16x32_bf16 v[86:89], v[194:197], v[178:181], v[86:89]
	v_mfma_f32_16x16x32_bf16 v[78:81], v[202:205], v[178:181], v[78:81]
	v_mfma_f32_16x16x32_bf16 v[70:73], v[194:197], v[186:189], v[70:73]
	v_mfma_f32_16x16x32_bf16 v[66:69], v[202:205], v[186:189], v[66:69]
	s_setprio 0
	s_mov_b32 m0, s25
	v_lshl_add_u64 v[210:211], s[42:43], 0, v[130:131]
	s_barrier
	ds_read_b128 v[158:161], v141 offset:16384
	ds_read_b128 v[162:165], v141 offset:17408
	ds_read_b128 v[166:169], v141 offset:18432
	ds_read_b128 v[170:173], v141 offset:19456
	ds_read_b128 v[174:177], v141 offset:20480
	ds_read_b128 v[178:181], v141 offset:21504
	ds_read_b128 v[182:185], v141 offset:22528
	ds_read_b128 v[186:189], v141 offset:23552
	global_load_lds_dwordx4 v[210:211], off
	s_mov_b32 m0, s28
	v_lshl_add_u64 v[214:215], s[42:43], 0, v[132:133]
	global_load_lds_dwordx4 v[214:215], off
	s_barrier
	s_waitcnt lgkmcnt(0)
	s_setprio 1
	v_mfma_f32_16x16x32_bf16 v[62:65], v[142:145], v[158:161], v[62:65]
	v_mfma_f32_16x16x32_bf16 v[58:61], v[150:153], v[158:161], v[58:61]
	v_mfma_f32_16x16x32_bf16 v[50:53], v[142:145], v[166:169], v[50:53]
	v_mfma_f32_16x16x32_bf16 v[42:45], v[150:153], v[166:169], v[42:45]
	v_mfma_f32_16x16x32_bf16 v[34:37], v[142:145], v[174:177], v[34:37]
	v_mfma_f32_16x16x32_bf16 v[26:29], v[150:153], v[174:177], v[26:29]
	v_mfma_f32_16x16x32_bf16 v[18:21], v[142:145], v[182:185], v[18:21]
	v_mfma_f32_16x16x32_bf16 v[10:13], v[150:153], v[182:185], v[10:13]
	v_mfma_f32_16x16x32_bf16 v[62:65], v[146:149], v[162:165], v[62:65]
	v_mfma_f32_16x16x32_bf16 v[58:61], v[154:157], v[162:165], v[58:61]
	v_mfma_f32_16x16x32_bf16 v[50:53], v[146:149], v[170:173], v[50:53]
	v_mfma_f32_16x16x32_bf16 v[42:45], v[154:157], v[170:173], v[42:45]
	v_mfma_f32_16x16x32_bf16 v[34:37], v[146:149], v[178:181], v[34:37]
	v_mfma_f32_16x16x32_bf16 v[26:29], v[154:157], v[178:181], v[26:29]
	v_mfma_f32_16x16x32_bf16 v[18:21], v[146:149], v[186:189], v[18:21]
	v_mfma_f32_16x16x32_bf16 v[10:13], v[154:157], v[186:189], v[10:13]
	s_setprio 0
	s_barrier
; #define PG8_STAGE(bufoff, gbase, voff) do { _Pragma("unroll") for (int _i = 0; _i < 2; ++_i) \
;         __builtin_amdgcn_global_load_lds((const unsigned*)((const char*)(gbase) + (voff)[_i]), (LAS unsigned*)(lds + (bufoff) + ldsw + _i * 8192), 16, 0, 0); } while (0)
; #define PG8_LDA(dst, b, h) do { _Pragma("unroll") for (int m = 0; m < 4; ++m) _Pragma("unroll") for (int k = 0; k < 2; ++k) dst[m][k] = *(const LAS bf16x8*)(lds + PG8_SA(b, h) + aoff + m * 2048 + k * 1024); } while (0)
; #define PG8_LDB(dst, b, h) do { _Pragma("unroll") for (int n = 0; n < 2; ++n) _Pragma("unroll") for (int k = 0; k < 2; ++k) dst[n][k] = *(const LAS bf16x8*)(lds + PG8_SB(b, h) + boff + n * 2048 + k * 1024); } while (0)
; #define PG8_MMA(ai, bj, At, Bt) do { __builtin_amdgcn_s_setprio(1); _Pragma("unroll") for (int m = 0; m < 4; ++m) _Pragma("unroll") for (int n = 0; n < 2; ++n) _Pragma("unroll") for (int k = 0; k < 2; ++k) \
;         acc[ai][bj][m][n] = __builtin_amdgcn_mfma_f32_16x16x32_bf16(Bt[n][k], At[m][k], acc[ai][bj][m][n], 0, 0, 0); __builtin_amdgcn_s_setprio(0); } while (0)
; #define PG8_WAIT_V(n) asm volatile("s_waitcnt vmcnt(" #n ")" ::: "memory")
; #define PG8_WAIT_L(n) asm volatile("s_waitcnt lgkmcnt(" #n ")" ::: "memory")
; #define PG8_BAR __builtin_amdgcn_s_barrier()
; #define PG8_SCHED __builtin_amdgcn_sched_barrier(0)
; template <class Epi, class Sched>
; __device__ __forceinline__ void gemm_phase(LAS unsigned char* lds, const Gemm g, const Sched& S, const Epi& E, const int tid) {
;     ...
;             PG8_STAGE(PG8_SB(0, 1), b2 + hstep, voffB);
;             PG8_WAIT_V(6); PG8_BAR; PG8_MMA(1, 1, At, B1); PG8_BAR;
;             PG8_LDB(B0, 1, 0); PG8_SCHED; PG8_LDA(At, 1, 0); PG8_STAGE(PG8_SA(0, 1), a2 + hstep, voffA);
;             PG8_WAIT_L(8); PG8_BAR; PG8_WAIT_L(0); PG8_MMA(0, 0, At, B0); PG8_BAR; PG8_SCHED;
;             PG8_LDB(B1, 1, 1); PG8_STAGE(PG8_SB(1, 0), b3, voffB);
;             PG8_BAR; PG8_WAIT_L(0); PG8_MMA(0, 1, At, B1); PG8_BAR;
;             PG8_LDA(At, 1, 1); PG8_STAGE(PG8_SA(1, 0), a3, voffA);
	s_add_u32 s66, s40, 0x160000
	s_addc_u32 s67, s41, 0
	s_add_i32 s68, s68, s24
	s_mov_b32 m0, s68
	s_nop 0
	global_load_lds_dwordx4 v0, s[66:67]
	s_add_i32 m0, s68, 0x2000
	s_nop 0
	global_load_lds_dwordx4 v134, s[66:67]
	s_waitcnt vmcnt(6)
	s_barrier
	s_setprio 1
	v_mfma_f32_16x16x32_bf16 v[54:57], v[190:193], v[158:161], v[54:57]
	v_mfma_f32_16x16x32_bf16 v[46:49], v[198:201], v[158:161], v[46:49]
	v_mfma_f32_16x16x32_bf16 v[38:41], v[190:193], v[166:169], v[38:41]
	v_mfma_f32_16x16x32_bf16 v[30:33], v[198:201], v[166:169], v[30:33]
	v_mfma_f32_16x16x32_bf16 v[22:25], v[190:193], v[174:177], v[22:25]
	v_mfma_f32_16x16x32_bf16 v[14:17], v[198:201], v[174:177], v[14:17]
	v_mfma_f32_16x16x32_bf16 v[6:9], v[190:193], v[182:185], v[6:9]
	v_mfma_f32_16x16x32_bf16 v[2:5], v[198:201], v[182:185], v[2:5]
	v_mfma_f32_16x16x32_bf16 v[54:57], v[194:197], v[162:165], v[54:57]
	v_mfma_f32_16x16x32_bf16 v[46:49], v[202:205], v[162:165], v[46:49]
	v_mfma_f32_16x16x32_bf16 v[38:41], v[194:197], v[170:173], v[38:41]
	v_mfma_f32_16x16x32_bf16 v[30:33], v[202:205], v[170:173], v[30:33]
	v_mfma_f32_16x16x32_bf16 v[22:25], v[194:197], v[178:181], v[22:25]
	v_mfma_f32_16x16x32_bf16 v[14:17], v[202:205], v[178:181], v[14:17]
	v_mfma_f32_16x16x32_bf16 v[6:9], v[194:197], v[186:189], v[6:9]
	v_mfma_f32_16x16x32_bf16 v[2:5], v[202:205], v[186:189], v[2:5]
	s_setprio 0
	s_add_i32 s66, 0, 0x18000
	v_add_u32_e32 v154, s66, v140
	s_barrier
	ds_read_b128 v[142:145], v154
	ds_read_b128 v[146:149], v154 offset:1024
	ds_read_b128 v[150:153], v154 offset:2048
	ds_read_b128 v[154:157], v154 offset:3072
	s_add_u32 s42, s42, 0x160000
	s_addc_u32 s43, s43, 0
	s_mov_b32 m0, s29
	ds_read_b128 v[158:161], v141 offset:32768
	ds_read_b128 v[162:165], v141 offset:33792
	ds_read_b128 v[166:169], v141 offset:34816
	ds_read_b128 v[170:173], v141 offset:35840
	ds_read_b128 v[174:177], v141 offset:36864
	ds_read_b128 v[178:181], v141 offset:37888
	ds_read_b128 v[182:185], v141 offset:38912
	ds_read_b128 v[186:189], v141 offset:39936
	global_load_lds_dwordx4 v130, s[42:43]
	s_mov_b32 m0, s62
	s_nop 0
	global_load_lds_dwordx4 v132, s[42:43]
	s_waitcnt lgkmcnt(8)
	s_barrier
	s_waitcnt lgkmcnt(0)
	s_setprio 1
	v_mfma_f32_16x16x32_bf16 v[126:129], v[142:145], v[158:161], v[126:129]
	v_mfma_f32_16x16x32_bf16 v[122:125], v[150:153], v[158:161], v[122:125]
	v_mfma_f32_16x16x32_bf16 v[118:121], v[142:145], v[166:169], v[118:121]
	v_mfma_f32_16x16x32_bf16 v[110:113], v[150:153], v[166:169], v[110:113]
	v_mfma_f32_16x16x32_bf16 v[98:101], v[142:145], v[174:177], v[98:101]
	v_mfma_f32_16x16x32_bf16 v[90:93], v[150:153], v[174:177], v[90:93]
	v_mfma_f32_16x16x32_bf16 v[82:85], v[142:145], v[182:185], v[82:85]
	v_mfma_f32_16x16x32_bf16 v[74:77], v[150:153], v[182:185], v[74:77]
	v_mfma_f32_16x16x32_bf16 v[126:129], v[146:149], v[162:165], v[126:129]
	v_mfma_f32_16x16x32_bf16 v[122:125], v[154:157], v[162:165], v[122:125]
	v_mfma_f32_16x16x32_bf16 v[118:121], v[146:149], v[170:173], v[118:121]
	v_mfma_f32_16x16x32_bf16 v[110:113], v[154:157], v[170:173], v[110:113]
	v_mfma_f32_16x16x32_bf16 v[98:101], v[146:149], v[178:181], v[98:101]
	v_mfma_f32_16x16x32_bf16 v[90:93], v[154:157], v[178:181], v[90:93]
	v_mfma_f32_16x16x32_bf16 v[82:85], v[146:149], v[186:189], v[82:85]
	v_mfma_f32_16x16x32_bf16 v[74:77], v[154:157], v[186:189], v[74:77]
	s_setprio 0
	s_barrier
	s_add_i32 s42, 0, 0x1c000
	s_add_i32 s43, s66, s24
	v_add_u32_e32 v202, s42, v140
	v_lshl_add_u64 v[206:207], v[206:207], 0, s[36:37]
	s_mov_b32 m0, s43
	ds_read_b128 v[190:193], v202
	ds_read_b128 v[194:197], v202 offset:1024
	ds_read_b128 v[198:201], v202 offset:2048
	ds_read_b128 v[202:205], v202 offset:3072
	global_load_lds_dwordx4 v[206:207], off
	s_add_i32 m0, s43, 0x2000
	v_lshl_add_u64 v[206:207], v[208:209], 0, s[36:37]
	global_load_lds_dwordx4 v[206:207], off
	s_barrier
; #define PG8_STAGE(bufoff, gbase, voff) do { _Pragma("unroll") for (int _i = 0; _i < 2; ++_i) \
;         __builtin_amdgcn_global_load_lds((const unsigned*)((const char*)(gbase) + (voff)[_i]), (LAS unsigned*)(lds + (bufoff) + ldsw + _i * 8192), 16, 0, 0); } while (0)
; #define PG8_MMA(ai, bj, At, Bt) do { __builtin_amdgcn_s_setprio(1); _Pragma("unroll") for (int m = 0; m < 4; ++m) _Pragma("unroll") for (int n = 0; n < 2; ++n) _Pragma("unroll") for (int k = 0; k < 2; ++k) \
;         acc[ai][bj][m][n] = __builtin_amdgcn_mfma_f32_16x16x32_bf16(Bt[n][k], At[m][k], acc[ai][bj][m][n], 0, 0, 0); __builtin_amdgcn_s_setprio(0); } while (0)
; #define PG8_WAIT_V(n) asm volatile("s_waitcnt vmcnt(" #n ")" ::: "memory")
; #define PG8_WAIT_L(n) asm volatile("s_waitcnt lgkmcnt(" #n ")" ::: "memory")
; #define PG8_BAR __builtin_amdgcn_s_barrier()
; #define PG8_SCHED __builtin_amdgcn_sched_barrier(0)
; template <class Epi, class Sched>
; __device__ __forceinline__ void gemm_phase(LAS unsigned char* lds, const Gemm g, const Sched& S, const Epi& E, const int tid) {
;     ...
;             PG8_BAR; PG8_WAIT_L(0); PG8_MMA(1, 0, At, B0); PG8_BAR; PG8_SCHED;
;             PG8_STAGE(PG8_SB(1, 1), b3 + hstep, voffB);
;             PG8_WAIT_V(6); PG8_BAR; PG8_MMA(1, 1, At, B1); PG8_BAR;
;     ...
;     PG8_WAIT_V(0);
;     if (wr == 0) PG8_BAR;
	s_waitcnt lgkmcnt(0)
	s_setprio 1
	v_mfma_f32_16x16x32_bf16 v[114:117], v[190:193], v[158:161], v[114:117]
	v_mfma_f32_16x16x32_bf16 v[106:109], v[198:201], v[158:161], v[106:109]
	v_mfma_f32_16x16x32_bf16 v[102:105], v[190:193], v[166:169], v[102:105]
	v_mfma_f32_16x16x32_bf16 v[94:97], v[198:201], v[166:169], v[94:97]
	v_mfma_f32_16x16x32_bf16 v[86:89], v[190:193], v[174:177], v[86:89]
	v_mfma_f32_16x16x32_bf16 v[78:81], v[198:201], v[174:177], v[78:81]
	v_mfma_f32_16x16x32_bf16 v[70:73], v[190:193], v[182:185], v[70:73]
	v_mfma_f32_16x16x32_bf16 v[66:69], v[198:201], v[182:185], v[66:69]
	v_mfma_f32_16x16x32_bf16 v[114:117], v[194:197], v[162:165], v[114:117]
	v_mfma_f32_16x16x32_bf16 v[106:109], v[202:205], v[162:165], v[106:109]
	v_mfma_f32_16x16x32_bf16 v[102:105], v[194:197], v[170:173], v[102:105]
	v_mfma_f32_16x16x32_bf16 v[94:97], v[202:205], v[170:173], v[94:97]
	v_mfma_f32_16x16x32_bf16 v[86:89], v[194:197], v[178:181], v[86:89]
	v_mfma_f32_16x16x32_bf16 v[78:81], v[202:205], v[178:181], v[78:81]
	v_mfma_f32_16x16x32_bf16 v[70:73], v[194:197], v[186:189], v[70:73]
	v_mfma_f32_16x16x32_bf16 v[66:69], v[202:205], v[186:189], v[66:69]
	s_setprio 0
	s_mov_b32 m0, s63
	v_lshl_add_u64 v[206:207], v[210:211], 0, s[36:37]
	s_barrier
	ds_read_b128 v[158:161], v141 offset:49152
	ds_read_b128 v[162:165], v141 offset:50176
	ds_read_b128 v[166:169], v141 offset:51200
	ds_read_b128 v[170:173], v141 offset:52224
	ds_read_b128 v[174:177], v141 offset:53248
	ds_read_b128 v[178:181], v141 offset:54272
	ds_read_b128 v[182:185], v141 offset:55296
	ds_read_b128 v[186:189], v141 offset:56320
	global_load_lds_dwordx4 v[206:207], off
	s_mov_b32 m0, s64
	v_lshl_add_u64 v[206:207], v[214:215], 0, s[36:37]
	global_load_lds_dwordx4 v[206:207], off
	s_barrier
	s_waitcnt lgkmcnt(0)
	s_setprio 1
	v_mfma_f32_16x16x32_bf16 v[62:65], v[142:145], v[158:161], v[62:65]
	v_mfma_f32_16x16x32_bf16 v[58:61], v[150:153], v[158:161], v[58:61]
	v_mfma_f32_16x16x32_bf16 v[50:53], v[142:145], v[166:169], v[50:53]
	v_mfma_f32_16x16x32_bf16 v[42:45], v[150:153], v[166:169], v[42:45]
	v_mfma_f32_16x16x32_bf16 v[34:37], v[142:145], v[174:177], v[34:37]
	v_mfma_f32_16x16x32_bf16 v[26:29], v[150:153], v[174:177], v[26:29]
	v_mfma_f32_16x16x32_bf16 v[18:21], v[142:145], v[182:185], v[18:21]
	v_mfma_f32_16x16x32_bf16 v[10:13], v[150:153], v[182:185], v[10:13]
	v_mfma_f32_16x16x32_bf16 v[62:65], v[146:149], v[162:165], v[62:65]
	v_mfma_f32_16x16x32_bf16 v[58:61], v[154:157], v[162:165], v[58:61]
	v_mfma_f32_16x16x32_bf16 v[50:53], v[146:149], v[170:173], v[50:53]
	v_mfma_f32_16x16x32_bf16 v[42:45], v[154:157], v[170:173], v[42:45]
	v_mfma_f32_16x16x32_bf16 v[34:37], v[146:149], v[178:181], v[34:37]
	v_mfma_f32_16x16x32_bf16 v[26:29], v[154:157], v[178:181], v[26:29]
	v_mfma_f32_16x16x32_bf16 v[18:21], v[146:149], v[186:189], v[18:21]
	v_mfma_f32_16x16x32_bf16 v[10:13], v[154:157], v[186:189], v[10:13]
	s_setprio 0
	s_barrier
	s_add_u32 s40, s40, 0x160080
	s_addc_u32 s41, s41, 0
	s_add_i32 s42, s42, s24
	s_mov_b32 m0, s42
	s_nop 0
	global_load_lds_dwordx4 v0, s[40:41]
	s_add_i32 m0, s42, 0x2000
	s_nop 0
	global_load_lds_dwordx4 v134, s[40:41]
	s_waitcnt vmcnt(6)
	s_barrier
	s_setprio 1
	v_mfma_f32_16x16x32_bf16 v[54:57], v[190:193], v[158:161], v[54:57]
	v_mfma_f32_16x16x32_bf16 v[46:49], v[198:201], v[158:161], v[46:49]
	v_mfma_f32_16x16x32_bf16 v[38:41], v[190:193], v[166:169], v[38:41]
	v_mfma_f32_16x16x32_bf16 v[30:33], v[198:201], v[166:169], v[30:33]
	v_mfma_f32_16x16x32_bf16 v[22:25], v[190:193], v[174:177], v[22:25]
	v_mfma_f32_16x16x32_bf16 v[14:17], v[198:201], v[174:177], v[14:17]
	v_mfma_f32_16x16x32_bf16 v[6:9], v[190:193], v[182:185], v[6:9]
	v_mfma_f32_16x16x32_bf16 v[2:5], v[198:201], v[182:185], v[2:5]
	v_mfma_f32_16x16x32_bf16 v[54:57], v[194:197], v[162:165], v[54:57]
	v_mfma_f32_16x16x32_bf16 v[46:49], v[202:205], v[162:165], v[46:49]
	v_mfma_f32_16x16x32_bf16 v[38:41], v[194:197], v[170:173], v[38:41]
	v_mfma_f32_16x16x32_bf16 v[30:33], v[202:205], v[170:173], v[30:33]
	v_mfma_f32_16x16x32_bf16 v[22:25], v[194:197], v[178:181], v[22:25]
	v_mfma_f32_16x16x32_bf16 v[14:17], v[202:205], v[178:181], v[14:17]
	v_mfma_f32_16x16x32_bf16 v[6:9], v[194:197], v[186:189], v[6:9]
	v_mfma_f32_16x16x32_bf16 v[2:5], v[202:205], v[186:189], v[2:5]
	s_setprio 0
	s_add_i32 s65, s65, 2
	s_add_u32 s38, s38, 0x100
	s_addc_u32 s39, s39, 0
	s_cmpk_lt_u32 s65, 0x56
	s_barrier
	s_cbranch_scc1 .LBB0_1573
	s_waitcnt vmcnt(0)
	s_cmpk_gt_u32 s44, 0xff
	s_cbranch_scc1 .LBB0_1576
	s_barrier

; #define PG8_STAGE(bufoff, gbase, voff) do { _Pragma("unroll") for (int _i = 0; _i < 2; ++_i) \
;         __builtin_amdgcn_global_load_lds((const unsigned*)((const char*)(gbase) + (voff)[_i]), (LAS unsigned*)(lds + (bufoff) + ldsw + _i * 8192), 16, 0, 0); } while (0)
; #define PG8_LDA(dst, b, h) do { _Pragma("unroll") for (int m = 0; m < 4; ++m) _Pragma("unroll") for (int k = 0; k < 2; ++k) dst[m][k] = *(const LAS bf16x8*)(lds + PG8_SA(b, h) + aoff + m * 2048 + k * 1024); } while (0)
; #define PG8_LDB(dst, b, h) do { _Pragma("unroll") for (int n = 0; n < 2; ++n) _Pragma("unroll") for (int k = 0; k < 2; ++k) dst[n][k] = *(const LAS bf16x8*)(lds + PG8_SB(b, h) + boff + n * 2048 + k * 1024); } while (0)
; #define PG8_MMA(ai, bj, At, Bt) do { __builtin_amdgcn_s_setprio(1); _Pragma("unroll") for (int m = 0; m < 4; ++m) _Pragma("unroll") for (int n = 0; n < 2; ++n) _Pragma("unroll") for (int k = 0; k < 2; ++k) \
;         acc[ai][bj][m][n] = __builtin_amdgcn_mfma_f32_16x16x32_bf16(Bt[n][k], At[m][k], acc[ai][bj][m][n], 0, 0, 0); __builtin_amdgcn_s_setprio(0); } while (0)
; #define PG8_WAIT_L(n) asm volatile("s_waitcnt lgkmcnt(" #n ")" ::: "memory")
; #define PG8_BAR __builtin_amdgcn_s_barrier()
; #define PG8_SCHED __builtin_amdgcn_sched_barrier(0)
; template <class Epi, class Sched>
; __device__ __forceinline__ void gemm_phase(LAS unsigned char* lds, const Gemm g, const Sched& S, const Epi& E, const int tid) {
;     ...
;             const bool last = (t == nt - 2);
;             const char* a1 = cA + (size_t)(t + 1) * kstep;
;             const char* a2 = last ? nA : cA + (size_t)(t + 2) * kstep; const char* b2 = last ? nB : cB + (size_t)(t + 2) * kstep;
;             const char* a3 = a2 + kstep; const char* b3 = b2 + kstep;
;             if (last && has_next) S.a_ready(nxt);
;             if constexpr (Epi::PRELOAD) { if (last) E.preload(cur, lds, wid, lane); }
;             PG8_LDB(B0, 0, 0); PG8_SCHED; PG8_LDA(At, 0, 0); PG8_STAGE(PG8_SA(1, 1), a1 + hstep, voffA);
;             PG8_WAIT_L(8); PG8_BAR; PG8_WAIT_L(0); PG8_MMA(0, 0, At, B0); PG8_BAR; PG8_SCHED;
;             PG8_LDB(B1, 0, 1); PG8_STAGE(PG8_SB(0, 0), b2, voffB);
;             PG8_BAR; PG8_WAIT_L(0); PG8_MMA(0, 1, At, B1); PG8_BAR;
;             PG8_LDA(At, 0, 1); PG8_STAGE(PG8_SA(0, 0), a2, voffA);
;             PG8_BAR; PG8_WAIT_L(0); PG8_MMA(1, 0, At, B0); PG8_BAR; PG8_SCHED;
.LBB0_1627:
	s_add_u32 s38, s22, 0xe1edc080
	s_addc_u32 s39, s23, -1
	s_cmpk_lg_i32 s51, 0x54
	s_cselect_b32 s38, s38, 0
	s_cselect_b32 s39, s39, 0
	s_add_u32 s40, s4, s38
	s_addc_u32 s41, s5, s39
	s_add_i32 s59, 0, 0x10000
	v_add_u32_e32 v154, s59, v140
	ds_read_b128 v[142:145], v154
	ds_read_b128 v[146:149], v154 offset:1024
	ds_read_b128 v[150:153], v154 offset:2048
	ds_read_b128 v[154:157], v154 offset:3072
	s_add_u32 s38, s0, s38
	s_addc_u32 s39, s1, s39
	v_lshl_add_u64 v[178:179], v[136:137], 0, s[22:23]
	s_add_i32 m0, s25, 0xc000
	ds_read_b128 v[158:161], v141
	ds_read_b128 v[162:165], v141 offset:1024
	ds_read_b128 v[166:169], v141 offset:2048
	ds_read_b128 v[170:173], v141 offset:3072
	ds_read_b128 v[174:177], v141 offset:4096
	ds_read_b128 v[182:185], v141 offset:5120
	ds_read_b128 v[186:189], v141 offset:6144
	ds_read_b128 v[190:193], v141 offset:7168
	global_load_lds_dwordx4 v[178:179], off
	s_add_i32 m0, s25, 0xe000
	v_lshl_add_u64 v[178:179], v[138:139], 0, s[22:23]
	global_load_lds_dwordx4 v[178:179], off
	s_waitcnt lgkmcnt(8)
	s_barrier
	s_waitcnt lgkmcnt(0)
	s_setprio 1
	v_mfma_f32_16x16x32_bf16 v[6:9], v[142:145], v[158:161], v[6:9]
	v_mfma_f32_16x16x32_bf16 v[14:17], v[150:153], v[158:161], v[14:17]
	v_mfma_f32_16x16x32_bf16 v[18:21], v[142:145], v[166:169], v[18:21]
	v_mfma_f32_16x16x32_bf16 v[22:25], v[150:153], v[166:169], v[22:25]
	v_mfma_f32_16x16x32_bf16 v[34:37], v[142:145], v[174:177], v[34:37]
	v_mfma_f32_16x16x32_bf16 v[38:41], v[150:153], v[174:177], v[38:41]
	v_mfma_f32_16x16x32_bf16 v[50:53], v[142:145], v[186:189], v[50:53]
	v_mfma_f32_16x16x32_bf16 v[54:57], v[150:153], v[186:189], v[54:57]
	v_mfma_f32_16x16x32_bf16 v[6:9], v[146:149], v[162:165], v[6:9]
	v_mfma_f32_16x16x32_bf16 v[14:17], v[154:157], v[162:165], v[14:17]
	v_mfma_f32_16x16x32_bf16 v[18:21], v[146:149], v[170:173], v[18:21]
	v_mfma_f32_16x16x32_bf16 v[22:25], v[154:157], v[170:173], v[22:25]
	v_mfma_f32_16x16x32_bf16 v[34:37], v[146:149], v[182:185], v[34:37]
	v_mfma_f32_16x16x32_bf16 v[38:41], v[154:157], v[182:185], v[38:41]
	v_mfma_f32_16x16x32_bf16 v[50:53], v[146:149], v[190:193], v[50:53]
	v_mfma_f32_16x16x32_bf16 v[54:57], v[154:157], v[190:193], v[54:57]
	s_setprio 0
	s_barrier
	s_add_i32 s62, 0, 0x14000
	v_add_u32_e32 v178, s62, v140
	s_add_i32 s59, s59, s24
	ds_read_b128 v[194:197], v178
	ds_read_b128 v[198:201], v178 offset:1024
	ds_read_b128 v[202:205], v178 offset:2048
	ds_read_b128 v[206:209], v178 offset:3072
	v_lshl_add_u64 v[178:179], s[38:39], 0, v[0:1]
	s_mov_b32 m0, s59
	v_lshl_add_u64 v[210:211], s[38:39], 0, v[134:135]
	global_load_lds_dwordx4 v[178:179], off
	s_add_i32 m0, s59, 0x2000
	s_nop 0
	global_load_lds_dwordx4 v[210:211], off
	s_barrier
	s_waitcnt lgkmcnt(0)
	s_setprio 1
	v_mfma_f32_16x16x32_bf16 v[2:5], v[194:197], v[158:161], v[2:5]
	v_mfma_f32_16x16x32_bf16 v[10:13], v[202:205], v[158:161], v[10:13]
	v_mfma_f32_16x16x32_bf16 v[26:29], v[194:197], v[166:169], v[26:29]
	v_mfma_f32_16x16x32_bf16 v[30:33], v[202:205], v[166:169], v[30:33]
	v_mfma_f32_16x16x32_bf16 v[42:45], v[194:197], v[174:177], v[42:45]
	v_mfma_f32_16x16x32_bf16 v[46:49], v[202:205], v[174:177], v[46:49]
	v_mfma_f32_16x16x32_bf16 v[58:61], v[194:197], v[186:189], v[58:61]
	v_mfma_f32_16x16x32_bf16 v[62:65], v[202:205], v[186:189], v[62:65]
	v_mfma_f32_16x16x32_bf16 v[2:5], v[198:201], v[162:165], v[2:5]
	v_mfma_f32_16x16x32_bf16 v[10:13], v[206:209], v[162:165], v[10:13]
	v_mfma_f32_16x16x32_bf16 v[26:29], v[198:201], v[170:173], v[26:29]
	v_mfma_f32_16x16x32_bf16 v[30:33], v[206:209], v[170:173], v[30:33]
	v_mfma_f32_16x16x32_bf16 v[42:45], v[198:201], v[182:185], v[42:45]
	v_mfma_f32_16x16x32_bf16 v[46:49], v[206:209], v[182:185], v[46:49]
	v_mfma_f32_16x16x32_bf16 v[58:61], v[198:201], v[190:193], v[58:61]
	v_mfma_f32_16x16x32_bf16 v[62:65], v[206:209], v[190:193], v[62:65]
	s_setprio 0
	s_mov_b32 m0, s25
	v_lshl_add_u64 v[214:215], s[40:41], 0, v[130:131]
	s_barrier
	ds_read_b128 v[158:161], v141 offset:16384
	ds_read_b128 v[162:165], v141 offset:17408
	ds_read_b128 v[166:169], v141 offset:18432
	ds_read_b128 v[170:173], v141 offset:19456
	ds_read_b128 v[174:177], v141 offset:20480
	ds_read_b128 v[182:185], v141 offset:21504
	ds_read_b128 v[186:189], v141 offset:22528
	ds_read_b128 v[190:193], v141 offset:23552
	global_load_lds_dwordx4 v[214:215], off
	s_mov_b32 m0, s29
	v_lshl_add_u64 v[216:217], s[40:41], 0, v[132:133]
	global_load_lds_dwordx4 v[216:217], off
	s_barrier
	s_waitcnt lgkmcnt(0)
	s_setprio 1
	v_mfma_f32_16x16x32_bf16 v[66:69], v[142:145], v[158:161], v[66:69]
	v_mfma_f32_16x16x32_bf16 v[70:73], v[150:153], v[158:161], v[70:73]
	v_mfma_f32_16x16x32_bf16 v[82:85], v[142:145], v[166:169], v[82:85]
	v_mfma_f32_16x16x32_bf16 v[86:89], v[150:153], v[166:169], v[86:89]
	v_mfma_f32_16x16x32_bf16 v[102:105], v[142:145], v[174:177], v[102:105]
	v_mfma_f32_16x16x32_bf16 v[106:109], v[150:153], v[174:177], v[106:109]
	v_mfma_f32_16x16x32_bf16 v[122:125], v[142:145], v[186:189], v[122:125]
	v_mfma_f32_16x16x32_bf16 v[126:129], v[150:153], v[186:189], v[126:129]
	v_mfma_f32_16x16x32_bf16 v[66:69], v[146:149], v[162:165], v[66:69]
	v_mfma_f32_16x16x32_bf16 v[70:73], v[154:157], v[162:165], v[70:73]
	v_mfma_f32_16x16x32_bf16 v[82:85], v[146:149], v[170:173], v[82:85]
	v_mfma_f32_16x16x32_bf16 v[86:89], v[154:157], v[170:173], v[86:89]
	v_mfma_f32_16x16x32_bf16 v[102:105], v[146:149], v[182:185], v[102:105]
	v_mfma_f32_16x16x32_bf16 v[106:109], v[154:157], v[182:185], v[106:109]
	v_mfma_f32_16x16x32_bf16 v[122:125], v[146:149], v[190:193], v[122:125]
	v_mfma_f32_16x16x32_bf16 v[126:129], v[154:157], v[190:193], v[126:129]
	s_setprio 0
	s_barrier
; #define PG8_STAGE(bufoff, gbase, voff) do { _Pragma("unroll") for (int _i = 0; _i < 2; ++_i) \
;         __builtin_amdgcn_global_load_lds((const unsigned*)((const char*)(gbase) + (voff)[_i]), (LAS unsigned*)(lds + (bufoff) + ldsw + _i * 8192), 16, 0, 0); } while (0)
; #define PG8_LDA(dst, b, h) do { _Pragma("unroll") for (int m = 0; m < 4; ++m) _Pragma("unroll") for (int k = 0; k < 2; ++k) dst[m][k] = *(const LAS bf16x8*)(lds + PG8_SA(b, h) + aoff + m * 2048 + k * 1024); } while (0)
; #define PG8_LDB(dst, b, h) do { _Pragma("unroll") for (int n = 0; n < 2; ++n) _Pragma("unroll") for (int k = 0; k < 2; ++k) dst[n][k] = *(const LAS bf16x8*)(lds + PG8_SB(b, h) + boff + n * 2048 + k * 1024); } while (0)
; #define PG8_MMA(ai, bj, At, Bt) do { __builtin_amdgcn_s_setprio(1); _Pragma("unroll") for (int m = 0; m < 4; ++m) _Pragma("unroll") for (int n = 0; n < 2; ++n) _Pragma("unroll") for (int k = 0; k < 2; ++k) \
;         acc[ai][bj][m][n] = __builtin_amdgcn_mfma_f32_16x16x32_bf16(Bt[n][k], At[m][k], acc[ai][bj][m][n], 0, 0, 0); __builtin_amdgcn_s_setprio(0); } while (0)
; #define PG8_WAIT_V(n) asm volatile("s_waitcnt vmcnt(" #n ")" ::: "memory")
; #define PG8_WAIT_L(n) asm volatile("s_waitcnt lgkmcnt(" #n ")" ::: "memory")
; #define PG8_BAR __builtin_amdgcn_s_barrier()
; #define PG8_SCHED __builtin_amdgcn_sched_barrier(0)
; template <class Epi, class Sched>
; __device__ __forceinline__ void gemm_phase(LAS unsigned char* lds, const Gemm g, const Sched& S, const Epi& E, const int tid) {
;     ...
;             PG8_STAGE(PG8_SB(0, 1), b2 + hstep, voffB);
;             PG8_WAIT_V(6); PG8_BAR; PG8_MMA(1, 1, At, B1); PG8_BAR;
;             PG8_LDB(B0, 1, 0); PG8_SCHED; PG8_LDA(At, 1, 0); PG8_STAGE(PG8_SA(0, 1), a2 + hstep, voffA);
;             PG8_WAIT_L(8); PG8_BAR; PG8_WAIT_L(0); PG8_MMA(0, 0, At, B0); PG8_BAR; PG8_SCHED;
;             PG8_LDB(B1, 1, 1); PG8_STAGE(PG8_SB(1, 0), b3, voffB);
;             PG8_BAR; PG8_WAIT_L(0); PG8_MMA(0, 1, At, B1); PG8_BAR;
;             PG8_LDA(At, 1, 1); PG8_STAGE(PG8_SA(1, 0), a3, voffA);
	s_add_u32 s60, s38, 0x160000
	s_addc_u32 s61, s39, 0
	s_add_i32 s59, s62, s24
	s_mov_b32 m0, s59
	s_nop 0
	global_load_lds_dwordx4 v0, s[60:61]
	s_add_i32 m0, s59, 0x2000
	s_nop 0
	global_load_lds_dwordx4 v134, s[60:61]
	s_waitcnt vmcnt(6)
	s_barrier
	s_setprio 1
	v_mfma_f32_16x16x32_bf16 v[74:77], v[194:197], v[158:161], v[74:77]
	v_mfma_f32_16x16x32_bf16 v[78:81], v[202:205], v[158:161], v[78:81]
	v_mfma_f32_16x16x32_bf16 v[90:93], v[194:197], v[166:169], v[90:93]
	v_mfma_f32_16x16x32_bf16 v[94:97], v[202:205], v[166:169], v[94:97]
	v_mfma_f32_16x16x32_bf16 v[114:117], v[194:197], v[174:177], v[114:117]
	v_mfma_f32_16x16x32_bf16 v[118:121], v[202:205], v[174:177], v[118:121]
	v_mfma_f32_16x16x32_bf16 v[110:113], v[194:197], v[186:189], v[110:113]
	v_mfma_f32_16x16x32_bf16 v[98:101], v[202:205], v[186:189], v[98:101]
	v_mfma_f32_16x16x32_bf16 v[74:77], v[198:201], v[162:165], v[74:77]
	v_mfma_f32_16x16x32_bf16 v[78:81], v[206:209], v[162:165], v[78:81]
	v_mfma_f32_16x16x32_bf16 v[90:93], v[198:201], v[170:173], v[90:93]
	v_mfma_f32_16x16x32_bf16 v[94:97], v[206:209], v[170:173], v[94:97]
	v_mfma_f32_16x16x32_bf16 v[114:117], v[198:201], v[182:185], v[114:117]
	v_mfma_f32_16x16x32_bf16 v[118:121], v[206:209], v[182:185], v[118:121]
	v_mfma_f32_16x16x32_bf16 v[110:113], v[198:201], v[190:193], v[110:113]
	v_mfma_f32_16x16x32_bf16 v[98:101], v[206:209], v[190:193], v[98:101]
	s_setprio 0
	s_add_i32 s59, 0, 0x18000
	v_add_u32_e32 v154, s59, v140
	s_barrier
	ds_read_b128 v[142:145], v154
	ds_read_b128 v[146:149], v154 offset:1024
	ds_read_b128 v[150:153], v154 offset:2048
	ds_read_b128 v[154:157], v154 offset:3072
	s_add_u32 s40, s40, 0x160000
	s_addc_u32 s41, s41, 0
	s_mov_b32 m0, s53
	ds_read_b128 v[158:161], v141 offset:32768
	ds_read_b128 v[162:165], v141 offset:33792
	ds_read_b128 v[166:169], v141 offset:34816
	ds_read_b128 v[170:173], v141 offset:35840
	ds_read_b128 v[174:177], v141 offset:36864
	ds_read_b128 v[182:185], v141 offset:37888
	ds_read_b128 v[186:189], v141 offset:38912
	ds_read_b128 v[190:193], v141 offset:39936
	global_load_lds_dwordx4 v130, s[40:41]
	s_mov_b32 m0, s54
	s_nop 0
	global_load_lds_dwordx4 v132, s[40:41]
	s_waitcnt lgkmcnt(8)
	s_barrier
	s_waitcnt lgkmcnt(0)
	s_setprio 1
	v_mfma_f32_16x16x32_bf16 v[6:9], v[142:145], v[158:161], v[6:9]
	v_mfma_f32_16x16x32_bf16 v[14:17], v[150:153], v[158:161], v[14:17]
	v_mfma_f32_16x16x32_bf16 v[18:21], v[142:145], v[166:169], v[18:21]
	v_mfma_f32_16x16x32_bf16 v[22:25], v[150:153], v[166:169], v[22:25]
	v_mfma_f32_16x16x32_bf16 v[34:37], v[142:145], v[174:177], v[34:37]
	v_mfma_f32_16x16x32_bf16 v[38:41], v[150:153], v[174:177], v[38:41]
	v_mfma_f32_16x16x32_bf16 v[50:53], v[142:145], v[186:189], v[50:53]
	v_mfma_f32_16x16x32_bf16 v[54:57], v[150:153], v[186:189], v[54:57]
	v_mfma_f32_16x16x32_bf16 v[6:9], v[146:149], v[162:165], v[6:9]
	v_mfma_f32_16x16x32_bf16 v[14:17], v[154:157], v[162:165], v[14:17]
	v_mfma_f32_16x16x32_bf16 v[18:21], v[146:149], v[170:173], v[18:21]
	v_mfma_f32_16x16x32_bf16 v[22:25], v[154:157], v[170:173], v[22:25]
	v_mfma_f32_16x16x32_bf16 v[34:37], v[146:149], v[182:185], v[34:37]
	v_mfma_f32_16x16x32_bf16 v[38:41], v[154:157], v[182:185], v[38:41]
	v_mfma_f32_16x16x32_bf16 v[50:53], v[146:149], v[190:193], v[50:53]
	v_mfma_f32_16x16x32_bf16 v[54:57], v[154:157], v[190:193], v[54:57]
	s_setprio 0
	s_barrier
	s_add_i32 s40, 0, 0x1c000
	s_add_i32 s41, s59, s24
	v_add_u32_e32 v206, s40, v140
	v_lshl_add_u64 v[178:179], v[178:179], 0, s[36:37]
	s_mov_b32 m0, s41
	ds_read_b128 v[194:197], v206
	ds_read_b128 v[198:201], v206 offset:1024
	ds_read_b128 v[202:205], v206 offset:2048
	ds_read_b128 v[206:209], v206 offset:3072
	global_load_lds_dwordx4 v[178:179], off
	s_add_i32 m0, s41, 0x2000
	v_lshl_add_u64 v[178:179], v[210:211], 0, s[36:37]
	global_load_lds_dwordx4 v[178:179], off
	s_barrier
; #define PG8_STAGE(bufoff, gbase, voff) do { _Pragma("unroll") for (int _i = 0; _i < 2; ++_i) \
;         __builtin_amdgcn_global_load_lds((const unsigned*)((const char*)(gbase) + (voff)[_i]), (LAS unsigned*)(lds + (bufoff) + ldsw + _i * 8192), 16, 0, 0); } while (0)
; #define PG8_MMA(ai, bj, At, Bt) do { __builtin_amdgcn_s_setprio(1); _Pragma("unroll") for (int m = 0; m < 4; ++m) _Pragma("unroll") for (int n = 0; n < 2; ++n) _Pragma("unroll") for (int k = 0; k < 2; ++k) \
;         acc[ai][bj][m][n] = __builtin_amdgcn_mfma_f32_16x16x32_bf16(Bt[n][k], At[m][k], acc[ai][bj][m][n], 0, 0, 0); __builtin_amdgcn_s_setprio(0); } while (0)
; #define PG8_WAIT_V(n) asm volatile("s_waitcnt vmcnt(" #n ")" ::: "memory")
; #define PG8_WAIT_L(n) asm volatile("s_waitcnt lgkmcnt(" #n ")" ::: "memory")
; #define PG8_BAR __builtin_amdgcn_s_barrier()
; #define PG8_SCHED __builtin_amdgcn_sched_barrier(0)
; template <class Epi, class Sched>
; __device__ __forceinline__ void gemm_phase(LAS unsigned char* lds, const Gemm g, const Sched& S, const Epi& E, const int tid) {
;     ...
;             PG8_BAR; PG8_WAIT_L(0); PG8_MMA(1, 0, At, B0); PG8_BAR; PG8_SCHED;
;             PG8_STAGE(PG8_SB(1, 1), b3 + hstep, voffB);
;             PG8_WAIT_V(6); PG8_BAR; PG8_MMA(1, 1, At, B1); PG8_BAR;
;     ...
;     PG8_WAIT_V(0);
;     if (wr == 0) PG8_BAR;
	s_waitcnt lgkmcnt(0)
	s_setprio 1
	v_mfma_f32_16x16x32_bf16 v[2:5], v[194:197], v[158:161], v[2:5]
	v_mfma_f32_16x16x32_bf16 v[10:13], v[202:205], v[158:161], v[10:13]
	v_mfma_f32_16x16x32_bf16 v[26:29], v[194:197], v[166:169], v[26:29]
	v_mfma_f32_16x16x32_bf16 v[30:33], v[202:205], v[166:169], v[30:33]
	v_mfma_f32_16x16x32_bf16 v[42:45], v[194:197], v[174:177], v[42:45]
	v_mfma_f32_16x16x32_bf16 v[46:49], v[202:205], v[174:177], v[46:49]
	v_mfma_f32_16x16x32_bf16 v[58:61], v[194:197], v[186:189], v[58:61]
	v_mfma_f32_16x16x32_bf16 v[62:65], v[202:205], v[186:189], v[62:65]
	v_mfma_f32_16x16x32_bf16 v[2:5], v[198:201], v[162:165], v[2:5]
	v_mfma_f32_16x16x32_bf16 v[10:13], v[206:209], v[162:165], v[10:13]
	v_mfma_f32_16x16x32_bf16 v[26:29], v[198:201], v[170:173], v[26:29]
	v_mfma_f32_16x16x32_bf16 v[30:33], v[206:209], v[170:173], v[30:33]
	v_mfma_f32_16x16x32_bf16 v[42:45], v[198:201], v[182:185], v[42:45]
	v_mfma_f32_16x16x32_bf16 v[46:49], v[206:209], v[182:185], v[46:49]
	v_mfma_f32_16x16x32_bf16 v[58:61], v[198:201], v[190:193], v[58:61]
	v_mfma_f32_16x16x32_bf16 v[62:65], v[206:209], v[190:193], v[62:65]
	s_setprio 0
	s_mov_b32 m0, s55
	v_lshl_add_u64 v[178:179], v[214:215], 0, s[36:37]
	s_barrier
	ds_read_b128 v[158:161], v141 offset:49152
	ds_read_b128 v[162:165], v141 offset:50176
	ds_read_b128 v[166:169], v141 offset:51200
	ds_read_b128 v[170:173], v141 offset:52224
	ds_read_b128 v[174:177], v141 offset:53248
	ds_read_b128 v[182:185], v141 offset:54272
	ds_read_b128 v[186:189], v141 offset:55296
	ds_read_b128 v[190:193], v141 offset:56320
	global_load_lds_dwordx4 v[178:179], off
	s_mov_b32 m0, s58
	v_lshl_add_u64 v[178:179], v[216:217], 0, s[36:37]
	global_load_lds_dwordx4 v[178:179], off
	s_barrier
	s_waitcnt lgkmcnt(0)
	s_setprio 1
	v_mfma_f32_16x16x32_bf16 v[66:69], v[142:145], v[158:161], v[66:69]
	v_mfma_f32_16x16x32_bf16 v[70:73], v[150:153], v[158:161], v[70:73]
	v_mfma_f32_16x16x32_bf16 v[82:85], v[142:145], v[166:169], v[82:85]
	v_mfma_f32_16x16x32_bf16 v[86:89], v[150:153], v[166:169], v[86:89]
	v_mfma_f32_16x16x32_bf16 v[102:105], v[142:145], v[174:177], v[102:105]
	v_mfma_f32_16x16x32_bf16 v[106:109], v[150:153], v[174:177], v[106:109]
	v_mfma_f32_16x16x32_bf16 v[122:125], v[142:145], v[186:189], v[122:125]
	v_mfma_f32_16x16x32_bf16 v[126:129], v[150:153], v[186:189], v[126:129]
	v_mfma_f32_16x16x32_bf16 v[66:69], v[146:149], v[162:165], v[66:69]
	v_mfma_f32_16x16x32_bf16 v[70:73], v[154:157], v[162:165], v[70:73]
	v_mfma_f32_16x16x32_bf16 v[82:85], v[146:149], v[170:173], v[82:85]
	v_mfma_f32_16x16x32_bf16 v[86:89], v[154:157], v[170:173], v[86:89]
	v_mfma_f32_16x16x32_bf16 v[102:105], v[146:149], v[182:185], v[102:105]
	v_mfma_f32_16x16x32_bf16 v[106:109], v[154:157], v[182:185], v[106:109]
	v_mfma_f32_16x16x32_bf16 v[122:125], v[146:149], v[190:193], v[122:125]
	v_mfma_f32_16x16x32_bf16 v[126:129], v[154:157], v[190:193], v[126:129]
	s_setprio 0
	s_barrier
	s_add_u32 s38, s38, 0x160080
	s_addc_u32 s39, s39, 0
	s_add_i32 s40, s40, s24
	s_mov_b32 m0, s40
	s_nop 0
	global_load_lds_dwordx4 v0, s[38:39]
	s_add_i32 m0, s40, 0x2000
	s_nop 0
	global_load_lds_dwordx4 v134, s[38:39]
	s_waitcnt vmcnt(6)
	s_barrier
	s_setprio 1
	v_mfma_f32_16x16x32_bf16 v[74:77], v[194:197], v[158:161], v[74:77]
	v_mfma_f32_16x16x32_bf16 v[78:81], v[202:205], v[158:161], v[78:81]
	v_mfma_f32_16x16x32_bf16 v[90:93], v[194:197], v[166:169], v[90:93]
	v_mfma_f32_16x16x32_bf16 v[94:97], v[202:205], v[166:169], v[94:97]
	v_mfma_f32_16x16x32_bf16 v[114:117], v[194:197], v[174:177], v[114:117]
	v_mfma_f32_16x16x32_bf16 v[118:121], v[202:205], v[174:177], v[118:121]
	v_mfma_f32_16x16x32_bf16 v[110:113], v[194:197], v[186:189], v[110:113]
	v_mfma_f32_16x16x32_bf16 v[98:101], v[202:205], v[186:189], v[98:101]
	v_mfma_f32_16x16x32_bf16 v[74:77], v[198:201], v[162:165], v[74:77]
	v_mfma_f32_16x16x32_bf16 v[78:81], v[206:209], v[162:165], v[78:81]
	v_mfma_f32_16x16x32_bf16 v[90:93], v[198:201], v[170:173], v[90:93]
	v_mfma_f32_16x16x32_bf16 v[94:97], v[206:209], v[170:173], v[94:97]
	v_mfma_f32_16x16x32_bf16 v[114:117], v[198:201], v[182:185], v[114:117]
	v_mfma_f32_16x16x32_bf16 v[118:121], v[206:209], v[182:185], v[118:121]
	v_mfma_f32_16x16x32_bf16 v[110:113], v[198:201], v[190:193], v[110:113]
	v_mfma_f32_16x16x32_bf16 v[98:101], v[206:209], v[190:193], v[98:101]
	s_setprio 0
	s_add_i32 s51, s51, 2
	s_add_u32 s22, s22, 0x100
	s_addc_u32 s23, s23, 0
	s_cmpk_lt_u32 s51, 0x56
	s_barrier
	s_cbranch_scc1 .LBB0_1627
	s_waitcnt vmcnt(0)
	s_cmpk_gt_u32 s42, 0xff
	s_cbranch_scc1 .LBB0_1630
	s_barrier

; #define PG8_STAGE(bufoff, gbase, voff) do { _Pragma("unroll") for (int _i = 0; _i < 2; ++_i) \
;         __builtin_amdgcn_global_load_lds((const unsigned*)((const char*)(gbase) + (voff)[_i]), (LAS unsigned*)(lds + (bufoff) + ldsw + _i * 8192), 16, 0, 0); } while (0)
; #define PG8_LDA(dst, b, h) do { _Pragma("unroll") for (int m = 0; m < 4; ++m) _Pragma("unroll") for (int k = 0; k < 2; ++k) dst[m][k] = *(const LAS bf16x8*)(lds + PG8_SA(b, h) + aoff + m * 2048 + k * 1024); } while (0)
; #define PG8_LDB(dst, b, h) do { _Pragma("unroll") for (int n = 0; n < 2; ++n) _Pragma("unroll") for (int k = 0; k < 2; ++k) dst[n][k] = *(const LAS bf16x8*)(lds + PG8_SB(b, h) + boff + n * 2048 + k * 1024); } while (0)
; #define PG8_MMA(ai, bj, At, Bt) do { __builtin_amdgcn_s_setprio(1); _Pragma("unroll") for (int m = 0; m < 4; ++m) _Pragma("unroll") for (int n = 0; n < 2; ++n) _Pragma("unroll") for (int k = 0; k < 2; ++k) \
;         acc[ai][bj][m][n] = __builtin_amdgcn_mfma_f32_16x16x32_bf16(Bt[n][k], At[m][k], acc[ai][bj][m][n], 0, 0, 0); __builtin_amdgcn_s_setprio(0); } while (0)
; #define PG8_WAIT_L(n) asm volatile("s_waitcnt lgkmcnt(" #n ")" ::: "memory")
; #define PG8_BAR __builtin_amdgcn_s_barrier()
; #define PG8_SCHED __builtin_amdgcn_sched_barrier(0)
; template <class Epi, class Sched>
; __device__ __forceinline__ void gemm_phase(LAS unsigned char* lds, const Gemm g, const Sched& S, const Epi& E, const int tid) {
;     ...
;             const bool last = (t == nt - 2);
;             const char* a1 = cA + (size_t)(t + 1) * kstep;
;             const char* a2 = last ? nA : cA + (size_t)(t + 2) * kstep; const char* b2 = last ? nB : cB + (size_t)(t + 2) * kstep;
;             const char* a3 = a2 + kstep; const char* b3 = b2 + kstep;
;             if (last && has_next) S.a_ready(nxt);
;             if constexpr (Epi::PRELOAD) { if (last) E.preload(cur, lds, wid, lane); }
;             PG8_LDB(B0, 0, 0); PG8_SCHED; PG8_LDA(At, 0, 0); PG8_STAGE(PG8_SA(1, 1), a1 + hstep, voffA);
;             PG8_WAIT_L(8); PG8_BAR; PG8_WAIT_L(0); PG8_MMA(0, 0, At, B0); PG8_BAR; PG8_SCHED;
;             PG8_LDB(B1, 0, 1); PG8_STAGE(PG8_SB(0, 0), b2, voffB);
;             PG8_BAR; PG8_WAIT_L(0); PG8_MMA(0, 1, At, B1); PG8_BAR;
;             PG8_LDA(At, 0, 1); PG8_STAGE(PG8_SA(0, 0), a2, voffA);
;             PG8_BAR; PG8_WAIT_L(0); PG8_MMA(1, 0, At, B0); PG8_BAR; PG8_SCHED;
.LBB0_1680:
	s_add_u32 s14, s12, 0x100
	s_addc_u32 s15, s13, 0
	s_add_i32 s53, 0, 0x10000
	v_add_u32_e32 v152, s53, v137
	ds_read_b128 v[140:143], v152
	ds_read_b128 v[144:147], v152 offset:1024
	ds_read_b128 v[148:151], v152 offset:2048
	ds_read_b128 v[152:155], v152 offset:3072
	s_cmp_eq_u32 s52, 4
	s_cselect_b32 s19, s7, s15
	s_cselect_b32 s18, s6, s14
	s_cselect_b32 s17, s3, s11
	s_cselect_b32 s16, s2, s5
	v_lshl_add_u64 v[188:189], s[12:13], 0, v[132:133]
	s_add_i32 m0, s28, 0xc000
	ds_read_b128 v[156:159], v139
	ds_read_b128 v[160:163], v139 offset:1024
	ds_read_b128 v[164:167], v139 offset:2048
	ds_read_b128 v[168:171], v139 offset:3072
	ds_read_b128 v[172:175], v139 offset:4096
	ds_read_b128 v[176:179], v139 offset:5120
	ds_read_b128 v[180:183], v139 offset:6144
	ds_read_b128 v[184:187], v139 offset:7168
	global_load_lds_dwordx4 v[188:189], off
	s_add_i32 m0, s28, 0xe000
	v_lshl_add_u64 v[188:189], s[12:13], 0, v[134:135]
	global_load_lds_dwordx4 v[188:189], off
	s_waitcnt lgkmcnt(8)
	s_barrier
	s_waitcnt lgkmcnt(0)
	s_setprio 1
	v_mfma_f32_16x16x32_bf16 v[126:129], v[140:143], v[156:159], v[126:129]
	v_mfma_f32_16x16x32_bf16 v[122:125], v[148:151], v[156:159], v[122:125]
	v_mfma_f32_16x16x32_bf16 v[118:121], v[140:143], v[164:167], v[118:121]
	v_mfma_f32_16x16x32_bf16 v[114:117], v[148:151], v[164:167], v[114:117]
	v_mfma_f32_16x16x32_bf16 v[106:109], v[140:143], v[172:175], v[106:109]
	v_mfma_f32_16x16x32_bf16 v[98:101], v[148:151], v[172:175], v[98:101]
	v_mfma_f32_16x16x32_bf16 v[90:93], v[140:143], v[180:183], v[90:93]
	v_mfma_f32_16x16x32_bf16 v[82:85], v[148:151], v[180:183], v[82:85]
	v_mfma_f32_16x16x32_bf16 v[126:129], v[144:147], v[160:163], v[126:129]
	v_mfma_f32_16x16x32_bf16 v[122:125], v[152:155], v[160:163], v[122:125]
	v_mfma_f32_16x16x32_bf16 v[118:121], v[144:147], v[168:171], v[118:121]
	v_mfma_f32_16x16x32_bf16 v[114:117], v[152:155], v[168:171], v[114:117]
	v_mfma_f32_16x16x32_bf16 v[106:109], v[144:147], v[176:179], v[106:109]
	v_mfma_f32_16x16x32_bf16 v[98:101], v[152:155], v[176:179], v[98:101]
	v_mfma_f32_16x16x32_bf16 v[90:93], v[144:147], v[184:187], v[90:93]
	v_mfma_f32_16x16x32_bf16 v[82:85], v[152:155], v[184:187], v[82:85]
	s_setprio 0
	s_barrier
	s_add_i32 s54, 0, 0x14000
	s_add_i32 s12, s53, s39
	v_add_u32_e32 v200, s54, v137
	v_lshl_add_u64 v[204:205], s[16:17], 0, v[0:1]
	s_mov_b32 m0, s12
	ds_read_b128 v[188:191], v200
	ds_read_b128 v[192:195], v200 offset:1024
	ds_read_b128 v[196:199], v200 offset:2048
	ds_read_b128 v[200:203], v200 offset:3072
	global_load_lds_dwordx4 v[204:205], off
	s_add_i32 m0, s12, 0x2000
	v_lshl_add_u64 v[206:207], s[16:17], 0, v[130:131]
	global_load_lds_dwordx4 v[206:207], off
	s_barrier
	s_waitcnt lgkmcnt(0)
	s_setprio 1
	v_mfma_f32_16x16x32_bf16 v[110:113], v[188:191], v[156:159], v[110:113]
	v_mfma_f32_16x16x32_bf16 v[102:105], v[196:199], v[156:159], v[102:105]
	v_mfma_f32_16x16x32_bf16 v[94:97], v[188:191], v[164:167], v[94:97]
	v_mfma_f32_16x16x32_bf16 v[86:89], v[196:199], v[164:167], v[86:89]
	v_mfma_f32_16x16x32_bf16 v[78:81], v[188:191], v[172:175], v[78:81]
	v_mfma_f32_16x16x32_bf16 v[74:77], v[196:199], v[172:175], v[74:77]
	v_mfma_f32_16x16x32_bf16 v[70:73], v[188:191], v[180:183], v[70:73]
	v_mfma_f32_16x16x32_bf16 v[66:69], v[196:199], v[180:183], v[66:69]
	v_mfma_f32_16x16x32_bf16 v[110:113], v[192:195], v[160:163], v[110:113]
	v_mfma_f32_16x16x32_bf16 v[102:105], v[200:203], v[160:163], v[102:105]
	v_mfma_f32_16x16x32_bf16 v[94:97], v[192:195], v[168:171], v[94:97]
	v_mfma_f32_16x16x32_bf16 v[86:89], v[200:203], v[168:171], v[86:89]
	v_mfma_f32_16x16x32_bf16 v[78:81], v[192:195], v[176:179], v[78:81]
	v_mfma_f32_16x16x32_bf16 v[74:77], v[200:203], v[176:179], v[74:77]
	v_mfma_f32_16x16x32_bf16 v[70:73], v[192:195], v[184:187], v[70:73]
	v_mfma_f32_16x16x32_bf16 v[66:69], v[200:203], v[184:187], v[66:69]
	s_setprio 0
	s_mov_b32 m0, s28
	v_lshl_add_u64 v[208:209], s[18:19], 0, v[0:1]
	s_barrier
	ds_read_b128 v[156:159], v139 offset:16384
	ds_read_b128 v[160:163], v139 offset:17408
	ds_read_b128 v[164:167], v139 offset:18432
	ds_read_b128 v[168:171], v139 offset:19456
	ds_read_b128 v[172:175], v139 offset:20480
	ds_read_b128 v[176:179], v139 offset:21504
	ds_read_b128 v[180:183], v139 offset:22528
	ds_read_b128 v[184:187], v139 offset:23552
	global_load_lds_dwordx4 v[208:209], off
	s_mov_b32 m0, s41
	v_lshl_add_u64 v[210:211], s[18:19], 0, v[130:131]
	global_load_lds_dwordx4 v[210:211], off
	s_barrier
	s_waitcnt lgkmcnt(0)
	s_setprio 1
	v_mfma_f32_16x16x32_bf16 v[62:65], v[140:143], v[156:159], v[62:65]
	v_mfma_f32_16x16x32_bf16 v[58:61], v[148:151], v[156:159], v[58:61]
	v_mfma_f32_16x16x32_bf16 v[54:57], v[140:143], v[164:167], v[54:57]
	v_mfma_f32_16x16x32_bf16 v[50:53], v[148:151], v[164:167], v[50:53]
	v_mfma_f32_16x16x32_bf16 v[38:41], v[140:143], v[172:175], v[38:41]
	v_mfma_f32_16x16x32_bf16 v[34:37], v[148:151], v[172:175], v[34:37]
	v_mfma_f32_16x16x32_bf16 v[22:25], v[140:143], v[180:183], v[22:25]
	v_mfma_f32_16x16x32_bf16 v[18:21], v[148:151], v[180:183], v[18:21]
	v_mfma_f32_16x16x32_bf16 v[62:65], v[144:147], v[160:163], v[62:65]
	v_mfma_f32_16x16x32_bf16 v[58:61], v[152:155], v[160:163], v[58:61]
	v_mfma_f32_16x16x32_bf16 v[54:57], v[144:147], v[168:171], v[54:57]
	v_mfma_f32_16x16x32_bf16 v[50:53], v[152:155], v[168:171], v[50:53]
	v_mfma_f32_16x16x32_bf16 v[38:41], v[144:147], v[176:179], v[38:41]
	v_mfma_f32_16x16x32_bf16 v[34:37], v[152:155], v[176:179], v[34:37]
	v_mfma_f32_16x16x32_bf16 v[22:25], v[144:147], v[184:187], v[22:25]
	v_mfma_f32_16x16x32_bf16 v[18:21], v[152:155], v[184:187], v[18:21]
	s_setprio 0
	s_barrier
; #define PG8_STAGE(bufoff, gbase, voff) do { _Pragma("unroll") for (int _i = 0; _i < 2; ++_i) \
;         __builtin_amdgcn_global_load_lds((const unsigned*)((const char*)(gbase) + (voff)[_i]), (LAS unsigned*)(lds + (bufoff) + ldsw + _i * 8192), 16, 0, 0); } while (0)
; #define PG8_LDA(dst, b, h) do { _Pragma("unroll") for (int m = 0; m < 4; ++m) _Pragma("unroll") for (int k = 0; k < 2; ++k) dst[m][k] = *(const LAS bf16x8*)(lds + PG8_SA(b, h) + aoff + m * 2048 + k * 1024); } while (0)
; #define PG8_LDB(dst, b, h) do { _Pragma("unroll") for (int n = 0; n < 2; ++n) _Pragma("unroll") for (int k = 0; k < 2; ++k) dst[n][k] = *(const LAS bf16x8*)(lds + PG8_SB(b, h) + boff + n * 2048 + k * 1024); } while (0)
; #define PG8_WAIT_V(n) asm volatile("s_waitcnt vmcnt(" #n ")" ::: "memory")
; #define PG8_WAIT_L(n) asm volatile("s_waitcnt lgkmcnt(" #n ")" ::: "memory")
; #define PG8_BAR __builtin_amdgcn_s_barrier()
; #define PG8_SCHED __builtin_amdgcn_sched_barrier(0)
; template <class Epi, class Sched>
; __device__ __forceinline__ void gemm_phase(LAS unsigned char* lds, const Gemm g, const Sched& S, const Epi& E, const int tid) {
;     ...
;             PG8_LDB(B0, 0, 0); PG8_SCHED; PG8_LDA(At, 0, 0); PG8_STAGE(PG8_SA(1, 1), a1 + hstep, voffA);
;             PG8_WAIT_L(8); PG8_BAR; PG8_WAIT_L(0); PG8_MMA(0, 0, At, B0); PG8_BAR; PG8_SCHED;
;             PG8_LDB(B1, 0, 1); PG8_STAGE(PG8_SB(0, 0), b2, voffB);
;             PG8_BAR; PG8_WAIT_L(0); PG8_MMA(0, 1, At, B1); PG8_BAR;
;             PG8_LDA(At, 0, 1); PG8_STAGE(PG8_SA(0, 0), a2, voffA);
;             PG8_BAR; PG8_WAIT_L(0); PG8_MMA(1, 0, At, B0); PG8_BAR; PG8_SCHED;
;             PG8_STAGE(PG8_SB(0, 1), b2 + hstep, voffB);
;             PG8_WAIT_V(6); PG8_BAR; PG8_MMA(1, 1, At, B1); PG8_BAR;
;             PG8_LDB(B0, 1, 0); PG8_SCHED; PG8_LDA(At, 1, 0); PG8_STAGE(PG8_SA(0, 1), a2 + hstep, voffA);
;             PG8_WAIT_L(8); PG8_BAR; PG8_WAIT_L(0); PG8_MMA(0, 0, At, B0); PG8_BAR; PG8_SCHED;
;             PG8_LDB(B1, 1, 1); PG8_STAGE(PG8_SB(1, 0), b3, voffB);
;             PG8_BAR; PG8_WAIT_L(0); PG8_MMA(0, 1, At, B1); PG8_BAR;
;             PG8_LDA(At, 1, 1); PG8_STAGE(PG8_SA(1, 0), a3, voffA);
;             PG8_BAR; PG8_WAIT_L(0); PG8_MMA(1, 0, At, B0); PG8_BAR; PG8_SCHED;
;             PG8_STAGE(PG8_SB(1, 1), b3 + hstep, voffB);
;             PG8_WAIT_V(6); PG8_BAR; PG8_MMA(1, 1, At, B1); PG8_BAR;
	s_add_u32 s12, s16, 0x160000
	s_addc_u32 s13, s17, 0
	s_add_i32 s53, s54, s39
	s_mov_b32 m0, s53
	s_nop 0
	global_load_lds_dwordx4 v0, s[12:13]
	s_add_i32 m0, s53, 0x2000
	s_nop 0
	global_load_lds_dwordx4 v130, s[12:13]
	s_waitcnt vmcnt(6)
	s_barrier
	s_setprio 1
	v_mfma_f32_16x16x32_bf16 v[46:49], v[188:191], v[156:159], v[46:49]
	v_mfma_f32_16x16x32_bf16 v[42:45], v[196:199], v[156:159], v[42:45]
	v_mfma_f32_16x16x32_bf16 v[30:33], v[188:191], v[164:167], v[30:33]
	v_mfma_f32_16x16x32_bf16 v[26:29], v[196:199], v[164:167], v[26:29]
	v_mfma_f32_16x16x32_bf16 v[14:17], v[188:191], v[172:175], v[14:17]
	v_mfma_f32_16x16x32_bf16 v[10:13], v[196:199], v[172:175], v[10:13]
	v_mfma_f32_16x16x32_bf16 v[6:9], v[188:191], v[180:183], v[6:9]
	v_mfma_f32_16x16x32_bf16 v[2:5], v[196:199], v[180:183], v[2:5]
	v_mfma_f32_16x16x32_bf16 v[46:49], v[192:195], v[160:163], v[46:49]
	v_mfma_f32_16x16x32_bf16 v[42:45], v[200:203], v[160:163], v[42:45]
	v_mfma_f32_16x16x32_bf16 v[30:33], v[192:195], v[168:171], v[30:33]
	v_mfma_f32_16x16x32_bf16 v[26:29], v[200:203], v[168:171], v[26:29]
	v_mfma_f32_16x16x32_bf16 v[14:17], v[192:195], v[176:179], v[14:17]
	v_mfma_f32_16x16x32_bf16 v[10:13], v[200:203], v[176:179], v[10:13]
	v_mfma_f32_16x16x32_bf16 v[6:9], v[192:195], v[184:187], v[6:9]
	v_mfma_f32_16x16x32_bf16 v[2:5], v[200:203], v[184:187], v[2:5]
	s_setprio 0
	s_add_i32 s53, 0, 0x18000
	v_add_u32_e32 v152, s53, v137
	s_barrier
	ds_read_b128 v[140:143], v152
	ds_read_b128 v[144:147], v152 offset:1024
	ds_read_b128 v[148:151], v152 offset:2048
	ds_read_b128 v[152:155], v152 offset:3072
	s_add_u32 s12, s18, 0x160000
	s_addc_u32 s13, s19, 0
	s_mov_b32 m0, s42
	ds_read_b128 v[156:159], v139 offset:32768
	ds_read_b128 v[160:163], v139 offset:33792
	ds_read_b128 v[164:167], v139 offset:34816
	ds_read_b128 v[168:171], v139 offset:35840
	ds_read_b128 v[172:175], v139 offset:36864
	ds_read_b128 v[176:179], v139 offset:37888
	ds_read_b128 v[180:183], v139 offset:38912
	ds_read_b128 v[184:187], v139 offset:39936
	global_load_lds_dwordx4 v0, s[12:13]
	s_mov_b32 m0, s43
	s_nop 0
	global_load_lds_dwordx4 v130, s[12:13]
	s_waitcnt lgkmcnt(8)
	s_barrier
	s_waitcnt lgkmcnt(0)
	s_setprio 1
	v_mfma_f32_16x16x32_bf16 v[126:129], v[140:143], v[156:159], v[126:129]
	v_mfma_f32_16x16x32_bf16 v[122:125], v[148:151], v[156:159], v[122:125]
	v_mfma_f32_16x16x32_bf16 v[118:121], v[140:143], v[164:167], v[118:121]
	v_mfma_f32_16x16x32_bf16 v[114:117], v[148:151], v[164:167], v[114:117]
	v_mfma_f32_16x16x32_bf16 v[106:109], v[140:143], v[172:175], v[106:109]
	v_mfma_f32_16x16x32_bf16 v[98:101], v[148:151], v[172:175], v[98:101]
	v_mfma_f32_16x16x32_bf16 v[90:93], v[140:143], v[180:183], v[90:93]
	v_mfma_f32_16x16x32_bf16 v[82:85], v[148:151], v[180:183], v[82:85]
	v_mfma_f32_16x16x32_bf16 v[126:129], v[144:147], v[160:163], v[126:129]
	v_mfma_f32_16x16x32_bf16 v[122:125], v[152:155], v[160:163], v[122:125]
	v_mfma_f32_16x16x32_bf16 v[118:121], v[144:147], v[168:171], v[118:121]
	v_mfma_f32_16x16x32_bf16 v[114:117], v[152:155], v[168:171], v[114:117]
	v_mfma_f32_16x16x32_bf16 v[106:109], v[144:147], v[176:179], v[106:109]
	v_mfma_f32_16x16x32_bf16 v[98:101], v[152:155], v[176:179], v[98:101]
	v_mfma_f32_16x16x32_bf16 v[90:93], v[144:147], v[184:187], v[90:93]
	v_mfma_f32_16x16x32_bf16 v[82:85], v[152:155], v[184:187], v[82:85]
	s_setprio 0
	s_barrier
	s_add_i32 s18, 0, 0x1c000
	s_add_i32 s12, s53, s39
	v_add_u32_e32 v200, s18, v137
	v_lshl_add_u64 v[204:205], v[204:205], 0, s[36:37]
	s_mov_b32 m0, s12
	ds_read_b128 v[188:191], v200
	ds_read_b128 v[192:195], v200 offset:1024
	ds_read_b128 v[196:199], v200 offset:2048
	ds_read_b128 v[200:203], v200 offset:3072
	global_load_lds_dwordx4 v[204:205], off
	s_add_i32 m0, s12, 0x2000
	v_lshl_add_u64 v[204:205], v[206:207], 0, s[36:37]
	global_load_lds_dwordx4 v[204:205], off
	s_barrier
	s_waitcnt lgkmcnt(0)
	s_setprio 1
	v_mfma_f32_16x16x32_bf16 v[110:113], v[188:191], v[156:159], v[110:113]
	v_mfma_f32_16x16x32_bf16 v[102:105], v[196:199], v[156:159], v[102:105]
	v_mfma_f32_16x16x32_bf16 v[94:97], v[188:191], v[164:167], v[94:97]
	v_mfma_f32_16x16x32_bf16 v[86:89], v[196:199], v[164:167], v[86:89]
	v_mfma_f32_16x16x32_bf16 v[78:81], v[188:191], v[172:175], v[78:81]
	v_mfma_f32_16x16x32_bf16 v[74:77], v[196:199], v[172:175], v[74:77]
	v_mfma_f32_16x16x32_bf16 v[70:73], v[188:191], v[180:183], v[70:73]
	v_mfma_f32_16x16x32_bf16 v[66:69], v[196:199], v[180:183], v[66:69]
	v_mfma_f32_16x16x32_bf16 v[110:113], v[192:195], v[160:163], v[110:113]
	v_mfma_f32_16x16x32_bf16 v[102:105], v[200:203], v[160:163], v[102:105]
	v_mfma_f32_16x16x32_bf16 v[94:97], v[192:195], v[168:171], v[94:97]
	v_mfma_f32_16x16x32_bf16 v[86:89], v[200:203], v[168:171], v[86:89]
	v_mfma_f32_16x16x32_bf16 v[78:81], v[192:195], v[176:179], v[78:81]
	v_mfma_f32_16x16x32_bf16 v[74:77], v[200:203], v[176:179], v[74:77]
	v_mfma_f32_16x16x32_bf16 v[70:73], v[192:195], v[184:187], v[70:73]
	v_mfma_f32_16x16x32_bf16 v[66:69], v[200:203], v[184:187], v[66:69]
	s_setprio 0
	s_mov_b32 m0, s45
	v_lshl_add_u64 v[204:205], v[208:209], 0, s[36:37]
	s_barrier
	ds_read_b128 v[156:159], v139 offset:49152
	ds_read_b128 v[160:163], v139 offset:50176
	ds_read_b128 v[164:167], v139 offset:51200
	ds_read_b128 v[168:171], v139 offset:52224
	ds_read_b128 v[172:175], v139 offset:53248
	ds_read_b128 v[176:179], v139 offset:54272
	ds_read_b128 v[180:183], v139 offset:55296
	ds_read_b128 v[184:187], v139 offset:56320
	global_load_lds_dwordx4 v[204:205], off
	s_mov_b32 m0, s46
	v_lshl_add_u64 v[204:205], v[210:211], 0, s[36:37]
	global_load_lds_dwordx4 v[204:205], off
	s_barrier
; #define PG8_STAGE(bufoff, gbase, voff) do { _Pragma("unroll") for (int _i = 0; _i < 2; ++_i) \
;         __builtin_amdgcn_global_load_lds((const unsigned*)((const char*)(gbase) + (voff)[_i]), (LAS unsigned*)(lds + (bufoff) + ldsw + _i * 8192), 16, 0, 0); } while (0)
; #define PG8_LDA(dst, b, h) do { _Pragma("unroll") for (int m = 0; m < 4; ++m) _Pragma("unroll") for (int k = 0; k < 2; ++k) dst[m][k] = *(const LAS bf16x8*)(lds + PG8_SA(b, h) + aoff + m * 2048 + k * 1024); } while (0)
; #define PG8_WAIT_V(n) asm volatile("s_waitcnt vmcnt(" #n ")" ::: "memory")
; #define PG8_WAIT_L(n) asm volatile("s_waitcnt lgkmcnt(" #n ")" ::: "memory")
;     __device__ __forceinline__ void operator()(const f32x4 (&acc)[2][2][4][2], const Unit& u, int wr, int wc, int fr, int fq) const {
;         const int row0 = u.pm * BM + wr * 64 + fr, col0 = u.pn * BM + wc * 32 + 4 * fq;
;         float* base = (u.nt < ntfull) ? part + ((size_t)u.ks * MCTX - MLAT) * ldc : C;
; #pragma unroll
;         for (int ai = 0; ai < 2; ++ai)
; #pragma unroll
;             for (int m = 0; m < 4; ++m) { float* rowp = base + (size_t)(row0 + ai * HALF + m * 16) * ldc + col0;
; #pragma unroll
;                 for (int bj = 0; bj < 2; ++bj)
; #pragma unroll
;                     for (int n = 0; n < 2; ++n) *(f32x4*)(rowp + bj * HALF + n * 16) = acc[ai][bj][m][n]; }
;     }
; template <class Epi, class Sched>
; __device__ __forceinline__ void gemm_phase(LAS unsigned char* lds, const Gemm g, const Sched& S, const Epi& E, const int tid) {
;     ...
;             PG8_WAIT_V(6); PG8_BAR; PG8_MMA(1, 1, At, B1); PG8_BAR;
;             PG8_LDB(B0, 1, 0); PG8_SCHED; PG8_LDA(At, 1, 0); PG8_STAGE(PG8_SA(0, 1), a2 + hstep, voffA);
;             PG8_WAIT_L(8); PG8_BAR; PG8_WAIT_L(0); PG8_MMA(0, 0, At, B0); PG8_BAR; PG8_SCHED;
;             PG8_LDB(B1, 1, 1); PG8_STAGE(PG8_SB(1, 0), b3, voffB);
;             PG8_BAR; PG8_WAIT_L(0); PG8_MMA(0, 1, At, B1); PG8_BAR;
;             PG8_LDA(At, 1, 1); PG8_STAGE(PG8_SA(1, 0), a3, voffA);
;             PG8_BAR; PG8_WAIT_L(0); PG8_MMA(1, 0, At, B0); PG8_BAR; PG8_SCHED;
;             PG8_STAGE(PG8_SB(1, 1), b3 + hstep, voffB);
;             PG8_WAIT_V(6); PG8_BAR; PG8_MMA(1, 1, At, B1); PG8_BAR;
;         }
;         if constexpr (!Epi::AFTER_DRAIN) { if constexpr (Epi::PRELOAD) E(acc, cur, wr, wc, fr, fq, lds); else E(acc, cur, wr, wc, fr, fq); S.done(cur); }
	s_waitcnt lgkmcnt(0)
	s_setprio 1
	v_mfma_f32_16x16x32_bf16 v[62:65], v[140:143], v[156:159], v[62:65]
	v_mfma_f32_16x16x32_bf16 v[58:61], v[148:151], v[156:159], v[58:61]
	v_mfma_f32_16x16x32_bf16 v[54:57], v[140:143], v[164:167], v[54:57]
	v_mfma_f32_16x16x32_bf16 v[50:53], v[148:151], v[164:167], v[50:53]
	v_mfma_f32_16x16x32_bf16 v[38:41], v[140:143], v[172:175], v[38:41]
	v_mfma_f32_16x16x32_bf16 v[34:37], v[148:151], v[172:175], v[34:37]
	v_mfma_f32_16x16x32_bf16 v[22:25], v[140:143], v[180:183], v[22:25]
	v_mfma_f32_16x16x32_bf16 v[18:21], v[148:151], v[180:183], v[18:21]
	v_mfma_f32_16x16x32_bf16 v[62:65], v[144:147], v[160:163], v[62:65]
	v_mfma_f32_16x16x32_bf16 v[58:61], v[152:155], v[160:163], v[58:61]
	v_mfma_f32_16x16x32_bf16 v[54:57], v[144:147], v[168:171], v[54:57]
	v_mfma_f32_16x16x32_bf16 v[50:53], v[152:155], v[168:171], v[50:53]
	v_mfma_f32_16x16x32_bf16 v[38:41], v[144:147], v[176:179], v[38:41]
	v_mfma_f32_16x16x32_bf16 v[34:37], v[152:155], v[176:179], v[34:37]
	v_mfma_f32_16x16x32_bf16 v[22:25], v[144:147], v[184:187], v[22:25]
	v_mfma_f32_16x16x32_bf16 v[18:21], v[152:155], v[184:187], v[18:21]
	s_setprio 0
	s_barrier
	s_add_u32 s12, s16, 0x160080
	s_addc_u32 s13, s17, 0
	s_add_i32 s16, s18, s39
	s_mov_b32 m0, s16
	s_nop 0
	global_load_lds_dwordx4 v0, s[12:13]
	s_add_i32 m0, s16, 0x2000
	s_nop 0
	global_load_lds_dwordx4 v130, s[12:13]
	s_waitcnt vmcnt(6)
	s_barrier
	s_setprio 1
	v_mfma_f32_16x16x32_bf16 v[46:49], v[188:191], v[156:159], v[46:49]
	v_mfma_f32_16x16x32_bf16 v[42:45], v[196:199], v[156:159], v[42:45]
	v_mfma_f32_16x16x32_bf16 v[30:33], v[188:191], v[164:167], v[30:33]
	v_mfma_f32_16x16x32_bf16 v[26:29], v[196:199], v[164:167], v[26:29]
	v_mfma_f32_16x16x32_bf16 v[14:17], v[188:191], v[172:175], v[14:17]
	v_mfma_f32_16x16x32_bf16 v[10:13], v[196:199], v[172:175], v[10:13]
	v_mfma_f32_16x16x32_bf16 v[6:9], v[188:191], v[180:183], v[6:9]
	v_mfma_f32_16x16x32_bf16 v[2:5], v[196:199], v[180:183], v[2:5]
	v_mfma_f32_16x16x32_bf16 v[46:49], v[192:195], v[160:163], v[46:49]
	v_mfma_f32_16x16x32_bf16 v[42:45], v[200:203], v[160:163], v[42:45]
	v_mfma_f32_16x16x32_bf16 v[30:33], v[192:195], v[168:171], v[30:33]
	v_mfma_f32_16x16x32_bf16 v[26:29], v[200:203], v[168:171], v[26:29]
	v_mfma_f32_16x16x32_bf16 v[14:17], v[192:195], v[176:179], v[14:17]
	v_mfma_f32_16x16x32_bf16 v[10:13], v[200:203], v[176:179], v[10:13]
	v_mfma_f32_16x16x32_bf16 v[6:9], v[192:195], v[184:187], v[6:9]
	v_mfma_f32_16x16x32_bf16 v[2:5], v[200:203], v[184:187], v[2:5]
	s_setprio 0
	s_add_i32 s52, s52, 2
	s_add_u32 s5, s5, 0x100
	s_addc_u32 s11, s11, 0
	s_cmp_gt_u32 s52, 5
	s_mov_b64 s[12:13], s[14:15]
	s_barrier
	s_cbranch_scc0 .LBB0_1680
	s_ashr_i32 s5, s4, 31
	s_lshl_b64 s[4:5], s[4:5], 22
	s_add_u32 s4, s47, s4
	v_lshl_or_b32 v140, s40, 8, v138
	v_lshl_add_u32 v142, s29, 8, v136
	s_addc_u32 s5, s48, s5
	v_ashrrev_i32_e32 v141, 31, v140
	v_ashrrev_i32_e32 v143, 31, v142
	v_lshl_add_u64 v[140:141], v[140:141], 2, s[4:5]
	v_lshlrev_b64 v[144:145], 13, v[142:143]
	v_lshl_add_u64 v[144:145], v[140:141], 0, v[144:145]
	global_store_dwordx4 v[144:145], v[126:129], off
	global_store_dwordx4 v[144:145], v[122:125], off offset:64
	global_store_dwordx4 v[144:145], v[110:113], off offset:512
	global_store_dwordx4 v[144:145], v[102:105], off offset:576
	s_mov_b64 s[4:5], 0x100000
	s_mov_b32 s29, s50
	v_or_b32_e32 v102, 16, v142
	v_ashrrev_i32_e32 v103, 31, v102
	v_lshlrev_b64 v[102:103], 13, v[102:103]
	v_lshl_add_u64 v[102:103], v[140:141], 0, v[102:103]
	global_store_dwordx4 v[102:103], v[118:121], off
	global_store_dwordx4 v[102:103], v[114:117], off offset:64
	global_store_dwordx4 v[102:103], v[94:97], off offset:512
	global_store_dwordx4 v[102:103], v[86:89], off offset:576
	s_mov_b32 s40, s51
	s_mov_b64 s[14:15], s[2:3]
	v_or_b32_e32 v86, 32, v142
	v_ashrrev_i32_e32 v87, 31, v86
	v_lshlrev_b64 v[86:87], 13, v[86:87]
	v_lshl_add_u64 v[86:87], v[140:141], 0, v[86:87]
	global_store_dwordx4 v[86:87], v[106:109], off
	global_store_dwordx4 v[86:87], v[98:101], off offset:64
	global_store_dwordx4 v[86:87], v[78:81], off offset:512
	global_store_dwordx4 v[86:87], v[74:77], off offset:576
	s_mov_b64 s[12:13], s[6:7]
	s_mov_b64 s[52:53], 0xc000
	v_or_b32_e32 v74, 48, v142
	v_ashrrev_i32_e32 v75, 31, v74
	v_lshlrev_b64 v[74:75], 13, v[74:75]
	v_lshl_add_u64 v[74:75], v[140:141], 0, v[74:75]
	global_store_dwordx4 v[74:75], v[90:93], off
	global_store_dwordx4 v[74:75], v[82:85], off offset:64
	global_store_dwordx4 v[74:75], v[70:73], off offset:512
	global_store_dwordx4 v[74:75], v[66:69], off offset:576
	s_mov_b64 s[54:55], 0x8000
	s_nop 0
	v_lshl_add_u64 v[66:67], v[144:145], 0, s[4:5]
	s_mov_b32 s4, 0x100000
	v_add_co_u32_e32 v68, vcc, s4, v144
	s_mov_b64 s[4:5], 0x120000
	s_nop 0
	v_addc_co_u32_e32 v69, vcc, 0, v145, vcc
	global_store_dwordx4 v[68:69], v[62:65], off
	global_store_dwordx4 v[66:67], v[58:61], off offset:64
	global_store_dwordx4 v[66:67], v[46:49], off offset:512
	global_store_dwordx4 v[66:67], v[42:45], off offset:576
	s_nop 1
	v_lshl_add_u64 v[42:43], v[144:145], 0, s[4:5]
	s_mov_b32 s4, 0x120000
	v_add_co_u32_e32 v44, vcc, s4, v144
	s_mov_b64 s[4:5], 0x140000
	s_nop 0
	v_addc_co_u32_e32 v45, vcc, 0, v145, vcc
	global_store_dwordx4 v[44:45], v[54:57], off
	global_store_dwordx4 v[42:43], v[50:53], off offset:64
	global_store_dwordx4 v[42:43], v[30:33], off offset:512
	global_store_dwordx4 v[42:43], v[26:29], off offset:576
	s_nop 1
	v_lshl_add_u64 v[26:27], v[144:145], 0, s[4:5]
	s_mov_b32 s4, 0x140000
	v_add_co_u32_e32 v28, vcc, s4, v144
	s_mov_b64 s[4:5], 0x160000
	s_nop 0
	v_addc_co_u32_e32 v29, vcc, 0, v145, vcc
	global_store_dwordx4 v[28:29], v[38:41], off
	global_store_dwordx4 v[26:27], v[34:37], off offset:64
	global_store_dwordx4 v[26:27], v[14:17], off offset:512
	global_store_dwordx4 v[26:27], v[10:13], off offset:576
	s_nop 1
	v_add_co_u32_e32 v12, vcc, 0x160000, v144
	v_lshl_add_u64 v[10:11], v[144:145], 0, s[4:5]
	s_nop 0
	v_addc_co_u32_e32 v13, vcc, 0, v145, vcc
	s_and_b64 vcc, exec, s[0:1]
	s_mov_b32 s4, s10
	global_store_dwordx4 v[12:13], v[22:25], off
	global_store_dwordx4 v[10:11], v[18:21], off offset:64
	global_store_dwordx4 v[10:11], v[6:9], off offset:512
	global_store_dwordx4 v[10:11], v[2:5], off offset:576
	s_cbranch_vccz .LBB0_1675
	s_waitcnt vmcnt(0)
	s_cmpk_gt_u32 s21, 0xff
	s_cbranch_scc1 .LBB0_1684
	s_barrier
